# v108 plus RES epilogue rounds 1-2 loads issued with round 0 and DIFF first QK chain prefetch
# baseline (speedup 1.0000x reference)
.LBB0_707:
	s_add_i32 s58, s64, 0xffffe000
	s_lshr_b32 s58, s58, 12
	s_mulk_i32 s58, 0x1800
	s_addk_i32 s58, 0x1800
	s_cmp_gt_i32 s6, 63
	s_cselect_b32 s6, s58, 0
	s_lshl_b64 s[58:59], s[6:7], 2
	v_mov_b32_e32 v70, s68
	s_add_u32 s6, s14, s58
	ds_read_b64 v[70:71], v70
	s_addc_u32 s63, s15, s59
	s_lshl_b32 s58, s69, 14
	s_add_i32 s58, s58, 0x20000
	s_ashr_i32 s59, s58, 31
	s_lshl_b64 s[58:59], s[58:59], 2
	s_add_u32 s58, s10, s58
	s_waitcnt lgkmcnt(0)
	v_readfirstlane_b32 s70, v70
	s_addc_u32 s59, s11, s59
	v_add_u32_e32 v70, s64, v141
	s_add_u32 s60, s6, 0x5ba2000
	v_lshlrev_b32_e32 v190, 10, v70
	s_addc_u32 s61, s63, 0
	v_or_b32_e32 v102, s66, v140
	v_or_b32_e32 v188, 0x400, v190
	v_or_b32_e32 v187, 0x4400, v190
	v_or_b32_e32 v191, 0x4c00, v190
	v_or_b32_e32 v195, 0x6c00, v190
	v_readfirstlane_b32 s71, v71
	s_add_u32 s62, s6, 0x5ba4000
	v_ashrrev_i32_e32 v103, 31, v102
	v_add_u32_e32 v134, v190, v102
	v_add_u32_e32 v136, v188, v102
	v_or_b32_e32 v186, 0x800, v190
	v_or_b32_e32 v185, 0xc00, v190
	v_or_b32_e32 v183, 0x2000, v190
	v_or_b32_e32 v181, 0x2400, v190
	v_or_b32_e32 v71, 0x2800, v190
	v_or_b32_e32 v182, 0x2c00, v190
	v_or_b32_e32 v184, 0x4000, v190
	v_add_u32_e32 v114, v187, v102
	v_or_b32_e32 v189, 0x4800, v190
	v_add_u32_e32 v120, v191, v102
	v_or_b32_e32 v192, 0x6000, v190
	v_or_b32_e32 v193, 0x6400, v190
	v_or_b32_e32 v194, 0x6800, v190
	v_add_u32_e32 v130, v195, v102
	s_addc_u32 s63, s63, 0
	v_lshlrev_b64 v[72:73], 2, v[102:103]
	v_ashrrev_i32_e32 v137, 31, v136
	v_add_u32_e32 v138, v186, v102
	v_add_u32_e32 v132, v185, v102
	v_add_u32_e32 v124, v183, v102
	v_add_u32_e32 v116, v181, v102
	v_add_u32_e32 v108, v71, v102
	v_add_u32_e32 v110, v182, v102
	v_add_u32_e32 v112, v184, v102
	v_ashrrev_i32_e32 v115, 31, v114
	v_add_u32_e32 v118, v189, v102
	v_ashrrev_i32_e32 v121, 31, v120
	v_add_u32_e32 v122, v192, v102
	v_add_u32_e32 v126, v193, v102
	v_add_u32_e32 v128, v194, v102
	v_ashrrev_i32_e32 v131, 31, v130
	v_ashrrev_i32_e32 v135, 31, v134
	v_lshl_add_u64 v[74:75], s[60:61], 0, v[72:73]
	v_lshl_add_u64 v[104:105], s[70:71], 0, v[72:73]
	v_lshl_add_u64 v[72:73], s[62:63], 0, v[72:73]
	v_lshl_add_u64 v[88:89], v[136:137], 2, s[12:13]
	v_ashrrev_i32_e32 v139, 31, v138
	v_ashrrev_i32_e32 v133, 31, v132
	v_ashrrev_i32_e32 v125, 31, v124
	v_ashrrev_i32_e32 v117, 31, v116
	v_ashrrev_i32_e32 v109, 31, v108
	v_ashrrev_i32_e32 v111, 31, v110
	v_ashrrev_i32_e32 v113, 31, v112
	v_lshl_add_u64 v[86:87], v[114:115], 2, s[12:13]
	v_ashrrev_i32_e32 v119, 31, v118
	v_lshl_add_u64 v[92:93], v[120:121], 2, s[12:13]
	v_ashrrev_i32_e32 v123, 31, v122
	v_ashrrev_i32_e32 v127, 31, v126
	v_ashrrev_i32_e32 v129, 31, v128
	v_lshl_add_u64 v[100:101], v[130:131], 2, s[12:13]
	v_lshl_add_u64 v[106:107], v[134:135], 2, s[12:13]
	global_load_dword v196, v[74:75], off
	global_load_dword v206, v[74:75], off offset:128
	global_load_dword v225, v[74:75], off offset:256
	global_load_dword v198, v[72:73], off
	global_load_dword v207, v[72:73], off offset:128
	global_load_dword v226, v[72:73], off offset:256
	global_load_dword v197, v[104:105], off
	v_lshl_add_u64 v[84:85], v[138:139], 2, s[12:13]
	v_lshl_add_u64 v[82:83], v[132:133], 2, s[12:13]
	v_lshl_add_u64 v[78:79], v[124:125], 2, s[12:13]
	v_lshl_add_u64 v[72:73], v[116:117], 2, s[12:13]
	v_lshl_add_u64 v[74:75], v[108:109], 2, s[12:13]
	v_lshl_add_u64 v[76:77], v[110:111], 2, s[12:13]
	v_lshl_add_u64 v[80:81], v[112:113], 2, s[12:13]
	global_load_dword v180, v[88:89], off
	global_load_dword v179, v[84:85], off
	global_load_dword v178, v[82:83], off
	global_load_dword v177, v[78:79], off
	global_load_dword v176, v[72:73], off
	global_load_dword v175, v[74:75], off
	global_load_dword v174, v[76:77], off
	global_load_dword v173, v[80:81], off
	v_lshl_add_u64 v[90:91], v[118:119], 2, s[12:13]
	global_load_dword v172, v[86:87], off
	global_load_dword v170, v[90:91], off
	v_lshl_add_u64 v[94:95], v[122:123], 2, s[12:13]
	v_lshl_add_u64 v[96:97], v[126:127], 2, s[12:13]
	v_lshl_add_u64 v[98:99], v[128:129], 2, s[12:13]
	global_load_dword v171, v[92:93], off
	global_load_dword v169, v[94:95], off
	global_load_dword v168, v[96:97], off
	global_load_dword v167, v[98:99], off
	global_load_dword v103, v[100:101], off
	global_load_dword v202, v[106:107], off
	v_lshl_add_u64 v[108:109], v[108:109], 1, s[8:9]
	global_load_dword v205, v[106:107], off offset:128
	global_load_dword v208, v[104:105], off offset:128
	global_load_dword v209, v[84:85], off offset:128
	global_load_dword v210, v[78:79], off offset:128
	global_load_dword v211, v[72:73], off offset:128
	global_load_dword v212, v[74:75], off offset:128
	global_load_dword v213, v[80:81], off offset:128
	global_load_dword v214, v[76:77], off offset:128
	global_load_dword v215, v[86:87], off offset:128
	global_load_dword v216, v[82:83], off offset:128
	global_load_dword v217, v[90:91], off offset:128
	global_load_dword v218, v[92:93], off offset:128
	global_load_dword v219, v[94:95], off offset:128
	global_load_dword v220, v[96:97], off offset:128
	global_load_dword v221, v[98:99], off offset:128
	global_load_dword v222, v[100:101], off offset:128
	global_load_dword v223, v[88:89], off offset:128
	global_load_dword v224, v[88:89], off offset:256
	global_load_dword v227, v[104:105], off offset:256
	global_load_dword v229, v[106:107], off offset:256
	global_load_dword v230, v[84:85], off offset:256
	global_load_dword v231, v[78:79], off offset:256
	global_load_dword v232, v[86:87], off offset:256
	global_load_dword v233, v[82:83], off offset:256
	global_load_dword v234, v[72:73], off offset:256
	global_load_dword v235, v[74:75], off offset:256
	global_load_dword v236, v[80:81], off offset:256
	global_load_dword v237, v[76:77], off offset:256
	global_load_dword v238, v[90:91], off offset:256
	global_load_dword v239, v[92:93], off offset:256
	global_load_dword v240, v[94:95], off offset:256
	global_load_dword v241, v[96:97], off offset:256
	global_load_dword v242, v[98:99], off offset:256
	global_load_dword v243, v[100:101], off offset:256
	s_waitcnt vmcnt(0)
	v_add_f32_e32 v198, 1.0, v198
	v_mul_f32_e32 v197, v197, v198
	v_fmac_f32_e32 v180, v49, v196
	v_fmac_f32_e32 v179, v50, v196
	v_fmac_f32_e32 v178, v51, v196
	v_fmac_f32_e32 v177, v52, v196
	v_fmac_f32_e32 v176, v53, v196
	v_fmac_f32_e32 v175, v54, v196
	v_fmac_f32_e32 v174, v55, v196
	v_fmac_f32_e32 v173, v56, v196
	v_fmac_f32_e32 v172, v57, v196
	v_fmac_f32_e32 v170, v58, v196
	v_fmac_f32_e32 v171, v59, v196
	v_fmac_f32_e32 v169, v60, v196
	v_fmac_f32_e32 v168, v61, v196
	v_fmac_f32_e32 v167, v62, v196
	v_fmac_f32_e32 v103, v63, v196
	v_fmac_f32_e32 v202, v48, v196
	v_or_b32_e32 v48, 32, v102
	v_ashrrev_i32_e32 v49, 31, v48
	v_lshlrev_b64 v[50:51], 2, v[48:49]
	global_store_dword v[88:89], v180, off sc1
	global_store_dword v[84:85], v179, off sc1
	global_store_dword v[82:83], v178, off sc1
	global_store_dword v[78:79], v177, off sc1
	global_store_dword v[72:73], v176, off sc1
	global_store_dword v[74:75], v175, off sc1
	global_store_dword v[76:77], v174, off sc1
	global_store_dword v[80:81], v173, off sc1
	global_store_dword v[86:87], v172, off sc1
	global_store_dword v[90:91], v170, off sc1
	global_store_dword v[92:93], v171, off sc1
	global_store_dword v[94:95], v169, off sc1
	global_store_dword v[96:97], v168, off sc1
	global_store_dword v[98:99], v167, off sc1
	global_store_dword v[100:101], v103, off sc1
	global_store_dword v[106:107], v202, off sc1
	v_mul_f32_e32 v54, v197, v202
	v_lshl_add_u64 v[52:53], s[60:61], 0, v[50:51]
	v_lshl_add_u64 v[50:51], s[62:63], 0, v[50:51]
	v_mov_b32_e32 v198, v205
	v_mov_b32_e32 v196, v206
	v_mov_b32_e32 v203, v207
	v_mov_b32_e32 v204, v208
	v_cvt_pk_bf16_f32 v49, v54, s0
	v_lshl_add_u64 v[50:51], v[134:135], 1, s[8:9]
	global_store_short v[50:51], v49, off sc1
	v_mul_f32_e32 v49, v197, v180
	v_cvt_pk_bf16_f32 v49, v49, s0
	v_lshl_add_u64 v[50:51], v[136:137], 1, s[8:9]
	global_store_short v[50:51], v49, off sc1
	v_mul_f32_e32 v49, v197, v179
	v_cvt_pk_bf16_f32 v49, v49, s0
	v_lshl_add_u64 v[50:51], v[138:139], 1, s[8:9]
	global_store_short v[50:51], v49, off sc1
	v_mul_f32_e32 v49, v197, v178
	v_cvt_pk_bf16_f32 v49, v49, s0
	v_lshl_add_u64 v[50:51], v[132:133], 1, s[8:9]
	global_store_short v[50:51], v49, off sc1
	v_mul_f32_e32 v49, v197, v177
	v_cvt_pk_bf16_f32 v49, v49, s0
	v_lshl_add_u64 v[50:51], v[124:125], 1, s[8:9]
	global_store_short v[50:51], v49, off sc1
	v_mul_f32_e32 v49, v197, v176
	v_cvt_pk_bf16_f32 v49, v49, s0
	v_lshl_add_u64 v[50:51], v[116:117], 1, s[8:9]
	global_store_short v[50:51], v49, off sc1
	v_mul_f32_e32 v49, v197, v175
	v_mov_b32_e32 v62, v209
	v_mov_b32_e32 v60, v210
	v_mov_b32_e32 v59, v211
	v_mov_b32_e32 v58, v212
	v_mov_b32_e32 v56, v213
	v_mov_b32_e32 v57, v214
	v_mov_b32_e32 v55, v215
	v_mov_b32_e32 v61, v216
	v_mov_b32_e32 v54, v217
	v_mov_b32_e32 v53, v218
	v_mov_b32_e32 v52, v219
	v_mov_b32_e32 v51, v220
	v_mov_b32_e32 v50, v221
	v_cvt_pk_bf16_f32 v63, v49, s0
	v_mov_b32_e32 v49, v222
	v_fmac_f32_e32 v198, v32, v196
	global_store_short v[108:109], v63, off sc1
	v_mov_b32_e32 v63, v223
	v_mul_f32_e32 v108, v197, v174
	v_cvt_pk_bf16_f32 v116, v108, s0
	v_lshl_add_u64 v[108:109], v[110:111], 1, s[8:9]
	global_store_short v[108:109], v116, off sc1
	v_mul_f32_e32 v108, v197, v173
	v_cvt_pk_bf16_f32 v110, v108, s0
	v_lshl_add_u64 v[108:109], v[112:113], 1, s[8:9]
	global_store_short v[108:109], v110, off sc1
	v_mul_f32_e32 v108, v197, v172
	v_cvt_pk_bf16_f32 v110, v108, s0
	v_lshl_add_u64 v[108:109], v[114:115], 1, s[8:9]
	global_store_short v[108:109], v110, off sc1
	v_mul_f32_e32 v108, v197, v170
	v_cvt_pk_bf16_f32 v110, v108, s0
	v_lshl_add_u64 v[108:109], v[118:119], 1, s[8:9]
	global_store_short v[108:109], v110, off sc1
	v_mul_f32_e32 v108, v197, v171
	v_cvt_pk_bf16_f32 v110, v108, s0
	v_lshl_add_u64 v[108:109], v[120:121], 1, s[8:9]
	global_store_short v[108:109], v110, off sc1
	v_mul_f32_e32 v108, v197, v169
	v_cvt_pk_bf16_f32 v110, v108, s0
	v_lshl_add_u64 v[108:109], v[122:123], 1, s[8:9]
	global_store_short v[108:109], v110, off sc1
	v_mul_f32_e32 v108, v197, v168
	v_cvt_pk_bf16_f32 v110, v108, s0
	v_lshl_add_u64 v[108:109], v[126:127], 1, s[8:9]
	global_store_short v[108:109], v110, off sc1
	v_mul_f32_e32 v108, v197, v167
	v_cvt_pk_bf16_f32 v110, v108, s0
	v_lshl_add_u64 v[108:109], v[128:129], 1, s[8:9]
	global_store_short v[108:109], v110, off sc1
	v_mul_f32_e32 v108, v197, v103
	v_cvt_pk_bf16_f32 v110, v108, s0
	v_lshl_add_u64 v[108:109], v[130:131], 1, s[8:9]
	global_store_short v[108:109], v110, off sc1
	v_add_f32_e32 v108, 1.0, v203
	v_mul_f32_e32 v112, v204, v108
	v_add_u32_e32 v108, v190, v48
	v_fmac_f32_e32 v62, v34, v196
	v_fmac_f32_e32 v61, v35, v196
	v_fmac_f32_e32 v60, v36, v196
	v_fmac_f32_e32 v59, v37, v196
	v_fmac_f32_e32 v58, v38, v196
	v_fmac_f32_e32 v57, v39, v196
	v_fmac_f32_e32 v56, v40, v196
	v_fmac_f32_e32 v55, v41, v196
	v_fmac_f32_e32 v54, v42, v196
	v_fmac_f32_e32 v53, v43, v196
	v_fmac_f32_e32 v52, v44, v196
	v_fmac_f32_e32 v51, v45, v196
	v_fmac_f32_e32 v50, v46, v196
	v_fmac_f32_e32 v49, v47, v196
	v_ashrrev_i32_e32 v109, 31, v108
	global_store_dword v[106:107], v198, off offset:128 sc1
	v_mul_f32_e32 v32, v112, v198
	global_store_dword v[84:85], v62, off offset:128 sc1
	global_store_dword v[82:83], v61, off offset:128 sc1
	global_store_dword v[78:79], v60, off offset:128 sc1
	global_store_dword v[72:73], v59, off offset:128 sc1
	global_store_dword v[74:75], v58, off offset:128 sc1
	global_store_dword v[76:77], v57, off offset:128 sc1
	global_store_dword v[80:81], v56, off offset:128 sc1
	global_store_dword v[86:87], v55, off offset:128 sc1
	global_store_dword v[90:91], v54, off offset:128 sc1
	global_store_dword v[92:93], v53, off offset:128 sc1
	global_store_dword v[94:95], v52, off offset:128 sc1
	global_store_dword v[96:97], v51, off offset:128 sc1
	global_store_dword v[98:99], v50, off offset:128 sc1
	global_store_dword v[100:101], v49, off offset:128 sc1
	v_cvt_pk_bf16_f32 v32, v32, s0
	v_lshl_add_u64 v[108:109], v[108:109], 1, s[8:9]
	v_add_u32_e32 v110, v188, v48
	v_mov_b32_e32 v45, v224
	v_ashrrev_i32_e32 v111, 31, v110
	global_store_short v[108:109], v32, off sc1
	v_mul_f32_e32 v40, v112, v59
	v_mul_f32_e32 v115, v112, v56
	v_cvt_pk_bf16_f32 v115, v115, s0
	v_fmac_f32_e32 v63, v33, v196
	v_mul_f32_e32 v32, v112, v63
	v_cvt_pk_bf16_f32 v34, v32, s0
	v_lshl_add_u64 v[32:33], v[110:111], 1, s[8:9]
	global_store_short v[32:33], v34, off sc1
	v_add_u32_e32 v32, v186, v48
	v_ashrrev_i32_e32 v33, 31, v32
	v_mul_f32_e32 v34, v112, v62
	v_cvt_pk_bf16_f32 v34, v34, s0
	v_lshl_add_u64 v[32:33], v[32:33], 1, s[8:9]
	global_store_short v[32:33], v34, off sc1
	v_add_u32_e32 v32, v185, v48
	v_ashrrev_i32_e32 v33, 31, v32
	v_mul_f32_e32 v34, v112, v61
	v_cvt_pk_bf16_f32 v34, v34, s0
	v_lshl_add_u64 v[32:33], v[32:33], 1, s[8:9]
	global_store_short v[32:33], v34, off sc1
	v_add_u32_e32 v32, v183, v48
	v_ashrrev_i32_e32 v33, 31, v32
	v_mul_f32_e32 v34, v112, v60
	v_cvt_pk_bf16_f32 v34, v34, s0
	v_lshl_add_u64 v[32:33], v[32:33], 1, s[8:9]
	global_store_short v[32:33], v34, off sc1
	v_or_b32_e32 v32, 64, v102
	v_add_u32_e32 v34, v181, v48
	v_ashrrev_i32_e32 v33, 31, v32
	v_ashrrev_i32_e32 v35, 31, v34
	v_lshlrev_b64 v[36:37], 2, v[32:33]
	global_store_dword v[88:89], v63, off offset:128 sc1
	v_lshl_add_u64 v[38:39], s[60:61], 0, v[36:37]
	v_cvt_pk_bf16_f32 v33, v40, s0
	v_lshl_add_u64 v[34:35], v[34:35], 1, s[8:9]
	v_lshl_add_u64 v[36:37], s[62:63], 0, v[36:37]
	v_mov_b32_e32 v109, v225
	v_mov_b32_e32 v113, v226
	v_mov_b32_e32 v114, v227
	v_mov_b32_e32 v116, v229
	v_mov_b32_e32 v47, v230
	v_mov_b32_e32 v44, v231
	v_mov_b32_e32 v39, v232
	v_mov_b32_e32 v46, v233
	v_mov_b32_e32 v43, v234
	v_mov_b32_e32 v42, v235
	v_mov_b32_e32 v40, v236
	v_mov_b32_e32 v41, v237
	v_mov_b32_e32 v38, v238
	v_mov_b32_e32 v37, v239
	v_mov_b32_e32 v36, v240
	v_add_u32_e32 v110, v184, v48
	global_store_short v[34:35], v33, off sc1
	v_add_u32_e32 v34, v71, v48
	v_ashrrev_i32_e32 v35, 31, v34
	v_mul_f32_e32 v33, v112, v58
	v_cvt_pk_bf16_f32 v33, v33, s0
	v_lshl_add_u64 v[34:35], v[34:35], 1, s[8:9]
	global_store_short v[34:35], v33, off sc1
	v_add_u32_e32 v34, v182, v48
	v_ashrrev_i32_e32 v35, 31, v34
	v_mul_f32_e32 v33, v112, v57
	v_cvt_pk_bf16_f32 v33, v33, s0
	v_lshl_add_u64 v[34:35], v[34:35], 1, s[8:9]
	global_store_short v[34:35], v33, off sc1
	v_mov_b32_e32 v35, v241
	v_ashrrev_i32_e32 v111, 31, v110
	v_mov_b32_e32 v34, v242
	v_mov_b32_e32 v33, v243
	v_lshl_add_u64 v[110:111], v[110:111], 1, s[8:9]
	global_store_short v[110:111], v115, off sc1
	v_add_u32_e32 v110, v187, v48
	v_ashrrev_i32_e32 v111, 31, v110
	v_mul_f32_e32 v115, v112, v55
	v_cvt_pk_bf16_f32 v115, v115, s0
	v_lshl_add_u64 v[110:111], v[110:111], 1, s[8:9]
	global_store_short v[110:111], v115, off sc1
	v_add_u32_e32 v110, v189, v48
	v_ashrrev_i32_e32 v111, 31, v110
	v_mul_f32_e32 v115, v112, v54
	v_cvt_pk_bf16_f32 v115, v115, s0
	v_lshl_add_u64 v[110:111], v[110:111], 1, s[8:9]
	global_store_short v[110:111], v115, off sc1
	v_add_u32_e32 v110, v191, v48
	v_ashrrev_i32_e32 v111, 31, v110
	v_mul_f32_e32 v115, v112, v53
	v_cvt_pk_bf16_f32 v115, v115, s0
	v_lshl_add_u64 v[110:111], v[110:111], 1, s[8:9]
	global_store_short v[110:111], v115, off sc1
	v_add_u32_e32 v110, v192, v48
	v_ashrrev_i32_e32 v111, 31, v110
	v_mul_f32_e32 v115, v112, v52
	v_cvt_pk_bf16_f32 v115, v115, s0
	v_lshl_add_u64 v[110:111], v[110:111], 1, s[8:9]
	global_store_short v[110:111], v115, off sc1
	v_add_u32_e32 v110, v193, v48
	v_ashrrev_i32_e32 v111, 31, v110
	v_mul_f32_e32 v115, v112, v51
	v_cvt_pk_bf16_f32 v115, v115, s0
	v_lshl_add_u64 v[110:111], v[110:111], 1, s[8:9]
	global_store_short v[110:111], v115, off sc1
	v_add_u32_e32 v110, v194, v48
	v_ashrrev_i32_e32 v111, 31, v110
	v_mul_f32_e32 v115, v112, v50
	v_cvt_pk_bf16_f32 v115, v115, s0
	v_lshl_add_u64 v[110:111], v[110:111], 1, s[8:9]
	global_store_short v[110:111], v115, off sc1
	v_add_u32_e32 v110, v195, v48
	v_ashrrev_i32_e32 v111, 31, v110
	v_mul_f32_e32 v48, v112, v49
	v_cvt_pk_bf16_f32 v48, v48, s0
	v_lshl_add_u64 v[110:111], v[110:111], 1, s[8:9]
	global_store_short v[110:111], v48, off sc1
	v_add_u32_e32 v110, v190, v32
	v_ashrrev_i32_e32 v111, 31, v110
	v_mul_f32_e32 v108, v198, v198
	v_fmac_f32_e32 v45, v17, v109
	v_add_f32_e32 v48, 1.0, v113
	v_mul_f32_e32 v48, v114, v48
	v_fmac_f32_e32 v116, v16, v109
	v_mul_f32_e32 v16, v48, v116
	v_fmac_f32_e32 v47, v18, v109
	v_cvt_pk_bf16_f32 v18, v16, s0
	v_lshl_add_u64 v[16:17], v[110:111], 1, s[8:9]
	global_store_short v[16:17], v18, off sc1
	v_add_u32_e32 v16, v188, v32
	v_ashrrev_i32_e32 v17, 31, v16
	v_mul_f32_e32 v18, v48, v45
	v_cvt_pk_bf16_f32 v18, v18, s0
	v_lshl_add_u64 v[16:17], v[16:17], 1, s[8:9]
	global_store_short v[16:17], v18, off sc1
	v_add_u32_e32 v16, v186, v32
	v_ashrrev_i32_e32 v17, 31, v16
	v_mul_f32_e32 v18, v48, v47
	v_cvt_pk_bf16_f32 v18, v18, s0
	v_lshl_add_u64 v[16:17], v[16:17], 1, s[8:9]
	v_fmac_f32_e32 v46, v19, v109
	global_store_short v[16:17], v18, off sc1
	v_add_u32_e32 v16, v185, v32
	v_ashrrev_i32_e32 v17, 31, v16
	v_mul_f32_e32 v18, v48, v46
	v_cvt_pk_bf16_f32 v18, v18, s0
	v_lshl_add_u64 v[16:17], v[16:17], 1, s[8:9]
	global_store_short v[16:17], v18, off sc1
	v_or_b32_e32 v16, 0x60, v102
	v_ashrrev_i32_e32 v17, 31, v16
	v_fmac_f32_e32 v44, v20, v109
	v_fmac_f32_e32 v43, v21, v109
	v_fmac_f32_e32 v42, v22, v109
	v_fmac_f32_e32 v41, v23, v109
	v_fmac_f32_e32 v40, v24, v109
	v_fmac_f32_e32 v39, v25, v109
	v_fmac_f32_e32 v38, v26, v109
	v_fmac_f32_e32 v37, v27, v109
	v_fmac_f32_e32 v36, v28, v109
	v_fmac_f32_e32 v35, v29, v109
	v_fmac_f32_e32 v34, v30, v109
	v_fmac_f32_e32 v33, v31, v109
	v_lshlrev_b64 v[20:21], 2, v[16:17]
	global_store_dword v[88:89], v45, off offset:256 sc1
	global_store_dword v[84:85], v47, off offset:256 sc1
	global_store_dword v[82:83], v46, off offset:256 sc1
	global_store_dword v[78:79], v44, off offset:256 sc1
	global_store_dword v[72:73], v43, off offset:256 sc1
	global_store_dword v[74:75], v42, off offset:256 sc1
	global_store_dword v[76:77], v41, off offset:256 sc1
	global_store_dword v[80:81], v40, off offset:256 sc1
	global_store_dword v[86:87], v39, off offset:256 sc1
	global_store_dword v[90:91], v38, off offset:256 sc1
	global_store_dword v[92:93], v37, off offset:256 sc1
	global_store_dword v[94:95], v36, off offset:256 sc1
	global_store_dword v[96:97], v35, off offset:256 sc1
	global_store_dword v[98:99], v34, off offset:256 sc1
	global_store_dword v[100:101], v33, off offset:256 sc1
	global_store_dword v[106:107], v116, off offset:256 sc1
	v_lshl_add_u64 v[22:23], s[60:61], 0, v[20:21]
	v_lshl_add_u64 v[20:21], s[62:63], 0, v[20:21]
	global_load_dword v29, v[106:107], off offset:384
	global_load_dword v102, v[22:23], off
	global_load_dword v17, v[20:21], off
	s_nop 0
	global_load_dword v20, v[104:105], off offset:384
	v_add_u32_e32 v18, v183, v32
	v_ashrrev_i32_e32 v19, 31, v18
	v_mul_f32_e32 v21, v48, v44
	v_cvt_pk_bf16_f32 v21, v21, s0
	v_lshl_add_u64 v[18:19], v[18:19], 1, s[8:9]
	global_store_short v[18:19], v21, off sc1
	v_add_u32_e32 v18, v181, v32
	v_ashrrev_i32_e32 v19, 31, v18
	v_mul_f32_e32 v21, v48, v43
	v_cvt_pk_bf16_f32 v21, v21, s0
	v_lshl_add_u64 v[18:19], v[18:19], 1, s[8:9]
	global_store_short v[18:19], v21, off sc1
	v_add_u32_e32 v18, v71, v32
	v_ashrrev_i32_e32 v19, 31, v18
	v_mul_f32_e32 v21, v48, v42
	v_cvt_pk_bf16_f32 v21, v21, s0
	v_lshl_add_u64 v[18:19], v[18:19], 1, s[8:9]
	global_store_short v[18:19], v21, off sc1
	v_add_u32_e32 v18, v182, v32
	v_ashrrev_i32_e32 v19, 31, v18
	v_mul_f32_e32 v21, v48, v41
	v_cvt_pk_bf16_f32 v21, v21, s0
	v_lshl_add_u64 v[18:19], v[18:19], 1, s[8:9]
	global_store_short v[18:19], v21, off sc1
	v_add_u32_e32 v18, v184, v32
	v_ashrrev_i32_e32 v19, 31, v18
	v_mul_f32_e32 v21, v48, v40
	v_cvt_pk_bf16_f32 v21, v21, s0
	v_lshl_add_u64 v[18:19], v[18:19], 1, s[8:9]
	global_store_short v[18:19], v21, off sc1
	v_add_u32_e32 v18, v187, v32
	v_ashrrev_i32_e32 v19, 31, v18
	v_mul_f32_e32 v21, v48, v39
	v_cvt_pk_bf16_f32 v21, v21, s0
	v_lshl_add_u64 v[18:19], v[18:19], 1, s[8:9]
	global_store_short v[18:19], v21, off sc1
	v_add_u32_e32 v18, v189, v32
	v_ashrrev_i32_e32 v19, 31, v18
	v_mul_f32_e32 v21, v48, v38
	v_cvt_pk_bf16_f32 v21, v21, s0
	v_lshl_add_u64 v[18:19], v[18:19], 1, s[8:9]
	global_store_short v[18:19], v21, off sc1
	v_add_u32_e32 v18, v191, v32
	v_ashrrev_i32_e32 v19, 31, v18
	v_mul_f32_e32 v21, v48, v37
	v_cvt_pk_bf16_f32 v21, v21, s0
	v_lshl_add_u64 v[18:19], v[18:19], 1, s[8:9]
	global_store_short v[18:19], v21, off sc1
	v_add_u32_e32 v18, v192, v32
	v_ashrrev_i32_e32 v19, 31, v18
	v_mul_f32_e32 v21, v48, v36
	v_cvt_pk_bf16_f32 v21, v21, s0
	v_lshl_add_u64 v[18:19], v[18:19], 1, s[8:9]
	global_load_dword v28, v[88:89], off offset:384
	global_load_dword v27, v[84:85], off offset:384
	global_load_dword v25, v[78:79], off offset:384
	global_load_dword v24, v[72:73], off offset:384
	global_load_dword v23, v[74:75], off offset:384
	v_mul_f32_e32 v30, v48, v33
	global_store_short v[18:19], v21, off sc1
	v_add_u32_e32 v18, v193, v32
	v_ashrrev_i32_e32 v19, 31, v18
	v_mul_f32_e32 v21, v48, v35
	v_cvt_pk_bf16_f32 v21, v21, s0
	v_lshl_add_u64 v[18:19], v[18:19], 1, s[8:9]
	global_store_short v[18:19], v21, off sc1
	v_add_u32_e32 v18, v194, v32
	v_ashrrev_i32_e32 v19, 31, v18
	v_mul_f32_e32 v21, v48, v34
	v_cvt_pk_bf16_f32 v21, v21, s0
	v_lshl_add_u64 v[18:19], v[18:19], 1, s[8:9]
	global_store_short v[18:19], v21, off sc1
	v_add_u32_e32 v18, v195, v32
	global_load_dword v21, v[80:81], off offset:384
	global_load_dword v22, v[76:77], off offset:384
	v_ashrrev_i32_e32 v19, 31, v18
	v_cvt_pk_bf16_f32 v30, v30, s0
	v_lshl_add_u64 v[18:19], v[18:19], 1, s[8:9]
	s_waitcnt vmcnt(19)
	v_add_f32_e32 v17, 1.0, v17
	s_waitcnt vmcnt(18)
	v_mul_f32_e32 v32, v20, v17
	global_load_dword v20, v[86:87], off offset:384
	global_load_dword v26, v[82:83], off offset:384
	v_fmac_f32_e32 v29, v0, v102
	global_store_short v[18:19], v30, off sc1
	v_add_u32_e32 v18, v190, v16
	v_ashrrev_i32_e32 v19, 31, v18
	v_mul_f32_e32 v0, v32, v29
	v_cvt_pk_bf16_f32 v0, v0, s0
	v_lshl_add_u64 v[18:19], v[18:19], 1, s[8:9]
	global_store_short v[18:19], v0, off sc1
	global_load_dword v19, v[90:91], off offset:384
	v_add_u32_e32 v30, v188, v16
	global_load_dword v18, v[92:93], off offset:384
	v_ashrrev_i32_e32 v31, 31, v30
	v_fmac_f32_e32 v108, v202, v202
	v_fmac_f32_e32 v108, v116, v116
	v_fmac_f32_e32 v108, v29, v29
	global_store_dword v[106:107], v29, off offset:384 sc1
	s_waitcnt vmcnt(16)
	v_fmac_f32_e32 v28, v1, v102
	v_mul_f32_e32 v0, v32, v28
	v_cvt_pk_bf16_f32 v17, v0, s0
	v_lshl_add_u64 v[0:1], v[30:31], 1, s[8:9]
	global_store_short v[0:1], v17, off sc1
	v_add_u32_e32 v0, v186, v16
	s_waitcnt vmcnt(16)
	v_fmac_f32_e32 v27, v2, v102
	global_load_dword v17, v[94:95], off offset:384
	v_ashrrev_i32_e32 v1, 31, v0
	v_mul_f32_e32 v2, v32, v27
	v_cvt_pk_bf16_f32 v2, v2, s0
	v_lshl_add_u64 v[0:1], v[0:1], 1, s[8:9]
	global_store_short v[0:1], v2, off sc1
	v_add_u32_e32 v0, v185, v16
	global_load_dword v2, v[96:97], off offset:384
	v_ashrrev_i32_e32 v1, 31, v0
	v_lshl_add_u64 v[0:1], v[0:1], 1, s[8:9]
	v_add_u32_e32 v30, v183, v16
	s_waitcnt vmcnt(18)
	v_fmac_f32_e32 v25, v4, v102
	v_ashrrev_i32_e32 v31, 31, v30
	v_lshl_add_u64 v[30:31], v[30:31], 1, s[8:9]
	s_waitcnt vmcnt(17)
	v_fmac_f32_e32 v24, v5, v102
	s_waitcnt vmcnt(16)
	v_fmac_f32_e32 v23, v6, v102
	s_waitcnt vmcnt(11)
	v_fmac_f32_e32 v22, v7, v102
	v_fmac_f32_e32 v21, v8, v102
	global_store_dword v[88:89], v28, off offset:384 sc1
	global_store_dword v[84:85], v27, off offset:384 sc1
	s_waitcnt vmcnt(12)
	v_fmac_f32_e32 v20, v9, v102
	s_waitcnt vmcnt(11)
	v_fmac_f32_e32 v26, v3, v102
	v_mul_f32_e32 v3, v32, v26
	v_cvt_pk_bf16_f32 v3, v3, s0
	global_store_short v[0:1], v3, off sc1
	global_load_dword v1, v[98:99], off offset:384
	v_mul_f32_e32 v0, v32, v25
	v_cvt_pk_bf16_f32 v0, v0, s0
	global_store_short v[30:31], v0, off sc1
	global_load_dword v0, v[100:101], off offset:384
	v_add_u32_e32 v30, v181, v16
	v_ashrrev_i32_e32 v31, 31, v30
	v_mul_f32_e32 v3, v32, v24
	v_cvt_pk_bf16_f32 v3, v3, s0
	v_lshl_add_u64 v[4:5], v[30:31], 1, s[8:9]
	global_store_short v[4:5], v3, off sc1
	v_add_u32_e32 v4, v71, v16
	v_ashrrev_i32_e32 v5, 31, v4
	v_mul_f32_e32 v3, v32, v23
	v_cvt_pk_bf16_f32 v3, v3, s0
	v_lshl_add_u64 v[4:5], v[4:5], 1, s[8:9]
	global_store_short v[4:5], v3, off sc1
	v_add_u32_e32 v4, v182, v16
	v_ashrrev_i32_e32 v5, 31, v4
	v_mul_f32_e32 v3, v32, v22
	v_cvt_pk_bf16_f32 v3, v3, s0
	v_lshl_add_u64 v[4:5], v[4:5], 1, s[8:9]
	global_store_short v[4:5], v3, off sc1
	v_add_u32_e32 v4, v184, v16
	v_ashrrev_i32_e32 v5, 31, v4
	v_mul_f32_e32 v3, v32, v21
	v_cvt_pk_bf16_f32 v3, v3, s0
	v_lshl_add_u64 v[4:5], v[4:5], 1, s[8:9]
	global_store_short v[4:5], v3, off sc1
	v_add_u32_e32 v4, v187, v16
	v_ashrrev_i32_e32 v5, 31, v4
	v_mul_f32_e32 v3, v32, v20
	v_cvt_pk_bf16_f32 v3, v3, s0
	v_lshl_add_u64 v[4:5], v[4:5], 1, s[8:9]
	global_store_short v[4:5], v3, off sc1
	v_add_u32_e32 v4, v189, v16
	s_waitcnt vmcnt(17)
	v_fmac_f32_e32 v19, v10, v102
	v_ashrrev_i32_e32 v5, 31, v4
	v_mul_f32_e32 v3, v32, v19
	v_cvt_pk_bf16_f32 v3, v3, s0
	v_lshl_add_u64 v[4:5], v[4:5], 1, s[8:9]
	global_store_short v[4:5], v3, off sc1
	v_add_u32_e32 v4, v191, v16
	s_waitcnt vmcnt(17)
	v_fmac_f32_e32 v18, v11, v102
	v_ashrrev_i32_e32 v5, 31, v4
	v_mul_f32_e32 v3, v32, v18
	v_cvt_pk_bf16_f32 v3, v3, s0
	v_lshl_add_u64 v[4:5], v[4:5], 1, s[8:9]
	global_store_short v[4:5], v3, off sc1
	v_add_u32_e32 v4, v192, v16
	v_ashrrev_i32_e32 v5, 31, v4
	v_lshl_add_u64 v[4:5], v[4:5], 1, s[8:9]
	v_add_u32_e32 v10, v195, v16
	v_ashrrev_i32_e32 v11, 31, v10
	v_lshl_add_u64 v[10:11], v[10:11], 1, s[8:9]
	s_waitcnt vmcnt(15)
	v_fmac_f32_e32 v17, v12, v102
	v_mul_f32_e32 v3, v32, v17
	v_cvt_pk_bf16_f32 v3, v3, s0
	global_store_short v[4:5], v3, off sc1
	v_add_u32_e32 v4, v193, v16
	v_ashrrev_i32_e32 v5, 31, v4
	v_lshl_add_u64 v[4:5], v[4:5], 1, s[8:9]
	s_waitcnt vmcnt(14)
	v_fmac_f32_e32 v2, v13, v102
	v_mul_f32_e32 v3, v32, v2
	v_cvt_pk_bf16_f32 v3, v3, s0
	global_store_short v[4:5], v3, off sc1
	v_add_u32_e32 v4, v194, v16
	v_ashrrev_i32_e32 v5, 31, v4
	v_lshl_add_u64 v[4:5], v[4:5], 1, s[8:9]
	v_xor_b32_e32 v13, 16, v166
	v_ashrrev_i32_e32 v71, 31, v70
	global_store_dword v[82:83], v26, off offset:384 sc1
	global_store_dword v[78:79], v25, off offset:384 sc1
	global_store_dword v[72:73], v24, off offset:384 sc1
	global_store_dword v[74:75], v23, off offset:384 sc1
	global_store_dword v[76:77], v22, off offset:384 sc1
	global_store_dword v[80:81], v21, off offset:384 sc1
	global_store_dword v[86:87], v20, off offset:384 sc1
	global_store_dword v[90:91], v19, off offset:384 sc1
	global_store_dword v[92:93], v18, off offset:384 sc1
	s_waitcnt vmcnt(20)
	v_fmac_f32_e32 v1, v14, v102
	v_mul_f32_e32 v3, v32, v1
	v_cvt_pk_bf16_f32 v3, v3, s0
	global_store_short v[4:5], v3, off sc1
	v_and_b32_e32 v4, 64, v166
	v_xor_b32_e32 v3, 1, v166
	v_add_u32_e32 v7, 64, v4
	v_cmp_lt_i32_e32 vcc, v3, v7
	v_xor_b32_e32 v4, 2, v166
	s_waitcnt vmcnt(19)
	v_fmac_f32_e32 v0, v15, v102
	v_cndmask_b32_e32 v3, v166, v3, vcc
	v_lshlrev_b32_e32 v3, 2, v3
	v_cmp_lt_i32_e32 vcc, v4, v7
	v_mul_f32_e32 v12, v32, v0
	v_cvt_pk_bf16_f32 v12, v12, s0
	v_cndmask_b32_e32 v4, v166, v4, vcc
	v_lshlrev_b32_e32 v4, 2, v4
	v_add_f32_dpp v6, v108, v108 quad_perm:[1,0,3,2] row_mask:0xf bank_mask:0xf
	v_xor_b32_e32 v5, 4, v166
	v_cmp_lt_i32_e32 vcc, v5, v7
	global_store_dword v[94:95], v17, off offset:384 sc1
	global_store_dword v[96:97], v2, off offset:384 sc1
	v_cndmask_b32_e32 v5, v166, v5, vcc
	v_lshlrev_b32_e32 v5, 2, v5
	v_add_f32_dpp v8, v6, v6 quad_perm:[2,3,0,1] row_mask:0xf bank_mask:0xf
	v_xor_b32_e32 v6, 8, v166
	v_cmp_lt_i32_e32 vcc, v6, v7
	global_store_dword v[98:99], v1, off offset:384 sc1
	global_store_dword v[100:101], v0, off offset:384 sc1
	v_cndmask_b32_e32 v6, v166, v6, vcc
	v_lshlrev_b32_e32 v6, 2, v6
	v_add_f32_dpp v8, v8, v8 row_half_mirror row_mask:0xf bank_mask:0xf
	v_cmp_lt_i32_e32 vcc, v13, v7
	global_store_short v[10:11], v12, off sc1
	v_add_f32_dpp v8, v8, v8 row_mirror row_mask:0xf bank_mask:0xf
	v_cndmask_b32_e32 v7, v166, v13, vcc
	v_lshlrev_b32_e32 v7, 2, v7
	ds_bpermute_b32 v9, v7, v8
	s_and_saveexec_b64 s[60:61], s[0:1]
	s_cbranch_execz .LBB0_709
	s_waitcnt lgkmcnt(0)
	v_add_f32_e32 v10, v8, v9
	v_lshl_add_u64 v[8:9], v[70:71], 2, s[58:59]
	global_store_dword v[8:9], v10, off sc1

.LBB0_779:
	s_add_i32 s58, s67, 0xffffe000
	s_lshr_b32 s58, s58, 12
	s_mulk_i32 s58, 0x1800
	s_addk_i32 s58, 0x1800
	s_cmp_gt_i32 s6, 63
	s_cselect_b32 s6, s58, 0
	s_lshl_b64 s[58:59], s[6:7], 2
	s_add_u32 s58, s14, s58
	s_addc_u32 s59, s15, s59
	s_add_u32 s60, s58, 0x5ba5000
	s_addc_u32 s61, s59, 0
	s_addk_i32 s6, 0x4800
	s_lshl_b64 s[58:59], s[6:7], 2
	v_mov_b32_e32 v70, s66
	s_add_u32 s6, s14, s58
	ds_read_b64 v[70:71], v70
	s_addc_u32 s65, s15, s59
	s_lshl_b32 s58, s64, 14
	s_add_i32 s58, s58, 0x40000
	s_ashr_i32 s59, s58, 31
	s_lshl_b64 s[58:59], s[58:59], 2
	s_add_u32 s58, s10, s58
	s_waitcnt lgkmcnt(0)
	v_readfirstlane_b32 s62, v70
	s_addc_u32 s59, s11, s59
	v_or_b32_e32 v102, s68, v138
	v_add_u32_e32 v70, s67, v139
	v_readfirstlane_b32 s63, v71
	s_add_u32 s62, s62, 0x1000
	v_ashrrev_i32_e32 v103, 31, v102
	v_lshlrev_b32_e32 v191, 10, v70
	s_addc_u32 s63, s63, 0
	v_lshlrev_b64 v[72:73], 2, v[102:103]
	v_or_b32_e32 v187, 0x400, v191
	v_or_b32_e32 v186, 0x4400, v191
	v_or_b32_e32 v189, 0x4c00, v191
	v_or_b32_e32 v194, 0x6c00, v191
	s_add_u32 s64, s6, 0x5ba1000
	v_lshl_add_u64 v[74:75], s[60:61], 0, v[72:73]
	v_add_u32_e32 v130, v191, v102
	v_add_u32_e32 v132, v187, v102
	v_or_b32_e32 v185, 0x800, v191
	v_or_b32_e32 v184, 0xc00, v191
	v_or_b32_e32 v182, 0x2000, v191
	v_or_b32_e32 v180, 0x2400, v191
	v_or_b32_e32 v71, 0x2800, v191
	v_or_b32_e32 v181, 0x2c00, v191
	v_or_b32_e32 v183, 0x4000, v191
	v_add_u32_e32 v112, v186, v102
	v_or_b32_e32 v188, 0x4800, v191
	v_add_u32_e32 v116, v189, v102
	v_or_b32_e32 v190, 0x6000, v191
	v_or_b32_e32 v192, 0x6400, v191
	v_or_b32_e32 v193, 0x6800, v191
	v_add_u32_e32 v128, v194, v102
	s_addc_u32 s65, s65, 0
	global_load_dword v195, v[74:75], off
	global_load_dword v205, v[74:75], off offset:128
	global_load_dword v224, v[74:75], off offset:256
	v_lshl_add_u64 v[74:75], s[62:63], 0, v[72:73]
	v_ashrrev_i32_e32 v133, 31, v132
	v_add_u32_e32 v134, v185, v102
	v_add_u32_e32 v136, v184, v102
	v_add_u32_e32 v126, v182, v102
	v_add_u32_e32 v118, v180, v102
	v_add_u32_e32 v110, v71, v102
	v_add_u32_e32 v106, v181, v102
	v_add_u32_e32 v108, v183, v102
	v_ashrrev_i32_e32 v113, 31, v112
	v_add_u32_e32 v114, v188, v102
	v_ashrrev_i32_e32 v117, 31, v116
	v_add_u32_e32 v120, v190, v102
	v_add_u32_e32 v122, v192, v102
	v_add_u32_e32 v124, v193, v102
	v_ashrrev_i32_e32 v129, 31, v128
	v_ashrrev_i32_e32 v131, 31, v130
	v_lshl_add_u64 v[72:73], s[64:65], 0, v[72:73]
	global_load_dword v196, v[74:75], off
	global_load_dword v204, v[74:75], off offset:128
	global_load_dword v223, v[74:75], off offset:256
	global_load_dword v197, v[72:73], off
	global_load_dword v203, v[72:73], off offset:128
	global_load_dword v222, v[72:73], off offset:256
	v_lshl_add_u64 v[88:89], v[132:133], 2, s[12:13]
	v_ashrrev_i32_e32 v135, 31, v134
	v_ashrrev_i32_e32 v137, 31, v136
	v_ashrrev_i32_e32 v127, 31, v126
	v_ashrrev_i32_e32 v119, 31, v118
	v_ashrrev_i32_e32 v111, 31, v110
	v_ashrrev_i32_e32 v107, 31, v106
	v_ashrrev_i32_e32 v109, 31, v108
	v_lshl_add_u64 v[86:87], v[112:113], 2, s[12:13]
	v_ashrrev_i32_e32 v115, 31, v114
	v_lshl_add_u64 v[92:93], v[116:117], 2, s[12:13]
	v_ashrrev_i32_e32 v121, 31, v120
	v_ashrrev_i32_e32 v123, 31, v122
	v_ashrrev_i32_e32 v125, 31, v124
	v_lshl_add_u64 v[100:101], v[128:129], 2, s[12:13]
	v_lshl_add_u64 v[104:105], v[130:131], 2, s[12:13]
	v_lshl_add_u64 v[84:85], v[134:135], 2, s[12:13]
	v_lshl_add_u64 v[82:83], v[136:137], 2, s[12:13]
	v_lshl_add_u64 v[78:79], v[126:127], 2, s[12:13]
	v_lshl_add_u64 v[72:73], v[118:119], 2, s[12:13]
	v_lshl_add_u64 v[74:75], v[110:111], 2, s[12:13]
	v_lshl_add_u64 v[76:77], v[106:107], 2, s[12:13]
	v_lshl_add_u64 v[80:81], v[108:109], 2, s[12:13]
	global_load_dword v179, v[88:89], off
	global_load_dword v178, v[84:85], off
	global_load_dword v177, v[82:83], off
	global_load_dword v176, v[78:79], off
	global_load_dword v175, v[72:73], off
	global_load_dword v174, v[74:75], off
	global_load_dword v173, v[76:77], off
	global_load_dword v172, v[80:81], off
	v_lshl_add_u64 v[90:91], v[114:115], 2, s[12:13]
	global_load_dword v171, v[86:87], off
	global_load_dword v169, v[90:91], off
	v_lshl_add_u64 v[94:95], v[120:121], 2, s[12:13]
	v_lshl_add_u64 v[96:97], v[122:123], 2, s[12:13]
	v_lshl_add_u64 v[98:99], v[124:125], 2, s[12:13]
	global_load_dword v170, v[92:93], off
	global_load_dword v168, v[94:95], off
	global_load_dword v167, v[96:97], off
	global_load_dword v166, v[98:99], off
	global_load_dword v103, v[100:101], off
	global_load_dword v198, v[104:105], off
	v_lshl_add_u64 v[110:111], v[110:111], 1, s[8:9]
	v_lshl_add_u64 v[106:107], v[106:107], 1, s[8:9]
	global_load_dword v202, v[104:105], off offset:128
	global_load_dword v206, v[84:85], off offset:128
	global_load_dword v207, v[78:79], off offset:128
	global_load_dword v208, v[72:73], off offset:128
	global_load_dword v209, v[74:75], off offset:128
	global_load_dword v210, v[80:81], off offset:128
	global_load_dword v211, v[76:77], off offset:128
	global_load_dword v212, v[86:87], off offset:128
	global_load_dword v213, v[82:83], off offset:128
	global_load_dword v214, v[90:91], off offset:128
	global_load_dword v215, v[92:93], off offset:128
	global_load_dword v216, v[94:95], off offset:128
	global_load_dword v217, v[96:97], off offset:128
	global_load_dword v218, v[98:99], off offset:128
	global_load_dword v219, v[100:101], off offset:128
	global_load_dword v220, v[88:89], off offset:128
	global_load_dword v221, v[88:89], off offset:256
	global_load_dword v225, v[90:91], off offset:256
	global_load_dword v226, v[92:93], off offset:256
	global_load_dword v227, v[94:95], off offset:256
	global_load_dword v229, v[104:105], off offset:256
	global_load_dword v230, v[84:85], off offset:256
	global_load_dword v231, v[86:87], off offset:256
	global_load_dword v232, v[82:83], off offset:256
	global_load_dword v233, v[78:79], off offset:256
	global_load_dword v234, v[72:73], off offset:256
	global_load_dword v235, v[74:75], off offset:256
	global_load_dword v236, v[80:81], off offset:256
	global_load_dword v237, v[76:77], off offset:256
	global_load_dword v238, v[96:97], off offset:256
	global_load_dword v239, v[98:99], off offset:256
	global_load_dword v240, v[100:101], off offset:256
	s_waitcnt vmcnt(0)
	v_add_f32_e32 v197, 1.0, v197
	v_mul_f32_e32 v196, v196, v197
	v_fmac_f32_e32 v179, v49, v195
	v_fmac_f32_e32 v178, v50, v195
	v_fmac_f32_e32 v177, v51, v195
	v_fmac_f32_e32 v176, v52, v195
	v_fmac_f32_e32 v175, v53, v195
	v_fmac_f32_e32 v174, v54, v195
	v_fmac_f32_e32 v173, v55, v195
	v_fmac_f32_e32 v172, v56, v195
	v_fmac_f32_e32 v171, v57, v195
	v_fmac_f32_e32 v169, v58, v195
	v_fmac_f32_e32 v170, v59, v195
	v_fmac_f32_e32 v168, v60, v195
	v_fmac_f32_e32 v167, v61, v195
	v_fmac_f32_e32 v166, v62, v195
	v_fmac_f32_e32 v103, v63, v195
	v_fmac_f32_e32 v198, v48, v195
	v_mul_f32_e32 v48, v196, v198
	v_cvt_pk_bf16_f32 v58, v48, s0
	v_or_b32_e32 v48, 32, v102
	v_ashrrev_i32_e32 v49, 31, v48
	v_lshlrev_b64 v[52:53], 2, v[48:49]
	global_store_dword v[88:89], v179, off sc1
	global_store_dword v[84:85], v178, off sc1
	global_store_dword v[82:83], v177, off sc1
	global_store_dword v[78:79], v176, off sc1
	global_store_dword v[72:73], v175, off sc1
	global_store_dword v[74:75], v174, off sc1
	global_store_dword v[76:77], v173, off sc1
	global_store_dword v[80:81], v172, off sc1
	global_store_dword v[86:87], v171, off sc1
	global_store_dword v[90:91], v169, off sc1
	global_store_dword v[92:93], v170, off sc1
	global_store_dword v[94:95], v168, off sc1
	global_store_dword v[96:97], v167, off sc1
	global_store_dword v[98:99], v166, off sc1
	global_store_dword v[100:101], v103, off sc1
	global_store_dword v[104:105], v198, off sc1
	v_lshl_add_u64 v[50:51], v[130:131], 1, s[8:9]
	v_lshl_add_u64 v[56:57], s[64:65], 0, v[52:53]
	v_mov_b32_e32 v197, v202
	v_lshl_add_u64 v[54:55], s[62:63], 0, v[52:53]
	v_mov_b32_e32 v130, v203
	v_mov_b32_e32 v131, v204
	v_mul_f32_e32 v49, v196, v179
	global_store_short v[50:51], v58, off sc1
	v_lshl_add_u64 v[50:51], s[60:61], 0, v[52:53]
	v_mov_b32_e32 v195, v205
	v_lshl_add_u64 v[50:51], v[132:133], 1, s[8:9]
	v_cvt_pk_bf16_f32 v49, v49, s0
	global_store_short v[50:51], v49, off sc1
	v_mul_f32_e32 v49, v196, v178
	v_lshl_add_u64 v[50:51], v[134:135], 1, s[8:9]
	v_cvt_pk_bf16_f32 v49, v49, s0
	global_store_short v[50:51], v49, off sc1
	v_mul_f32_e32 v49, v196, v177
	v_lshl_add_u64 v[50:51], v[136:137], 1, s[8:9]
	v_cvt_pk_bf16_f32 v49, v49, s0
	global_store_short v[50:51], v49, off sc1
	v_mul_f32_e32 v49, v196, v176
	v_lshl_add_u64 v[50:51], v[126:127], 1, s[8:9]
	v_cvt_pk_bf16_f32 v49, v49, s0
	global_store_short v[50:51], v49, off sc1
	v_mul_f32_e32 v49, v196, v175
	v_lshl_add_u64 v[50:51], v[118:119], 1, s[8:9]
	v_cvt_pk_bf16_f32 v49, v49, s0
	v_mov_b32_e32 v62, v206
	v_mov_b32_e32 v60, v207
	v_mov_b32_e32 v59, v208
	v_mov_b32_e32 v58, v209
	v_mov_b32_e32 v56, v210
	v_mov_b32_e32 v57, v211
	v_mov_b32_e32 v55, v212
	v_mov_b32_e32 v61, v213
	v_mov_b32_e32 v54, v214
	v_mov_b32_e32 v53, v215
	v_mov_b32_e32 v52, v216
	v_mul_f32_e32 v63, v196, v174
	global_store_short v[50:51], v49, off sc1
	v_mov_b32_e32 v51, v217
	v_cvt_pk_bf16_f32 v63, v63, s0
	v_mov_b32_e32 v50, v218
	v_mov_b32_e32 v49, v219
	v_fmac_f32_e32 v197, v32, v195
	global_store_short v[110:111], v63, off sc1
	v_mov_b32_e32 v63, v220
	v_mul_f32_e32 v110, v196, v173
	v_cvt_pk_bf16_f32 v110, v110, s0
	global_store_short v[106:107], v110, off sc1
	v_lshl_add_u64 v[106:107], v[108:109], 1, s[8:9]
	v_mul_f32_e32 v108, v196, v172
	v_cvt_pk_bf16_f32 v108, v108, s0
	global_store_short v[106:107], v108, off sc1
	v_mul_f32_e32 v108, v196, v171
	v_lshl_add_u64 v[106:107], v[112:113], 1, s[8:9]
	v_cvt_pk_bf16_f32 v108, v108, s0
	global_store_short v[106:107], v108, off sc1
	v_mul_f32_e32 v108, v196, v169
	v_lshl_add_u64 v[106:107], v[114:115], 1, s[8:9]
	v_cvt_pk_bf16_f32 v108, v108, s0
	global_store_short v[106:107], v108, off sc1
	v_mul_f32_e32 v108, v196, v170
	v_lshl_add_u64 v[106:107], v[116:117], 1, s[8:9]
	v_cvt_pk_bf16_f32 v108, v108, s0
	global_store_short v[106:107], v108, off sc1
	v_mul_f32_e32 v108, v196, v168
	v_lshl_add_u64 v[106:107], v[120:121], 1, s[8:9]
	v_cvt_pk_bf16_f32 v108, v108, s0
	global_store_short v[106:107], v108, off sc1
	v_mul_f32_e32 v108, v196, v167
	v_lshl_add_u64 v[106:107], v[122:123], 1, s[8:9]
	v_cvt_pk_bf16_f32 v108, v108, s0
	global_store_short v[106:107], v108, off sc1
	v_mul_f32_e32 v108, v196, v166
	v_lshl_add_u64 v[106:107], v[124:125], 1, s[8:9]
	v_cvt_pk_bf16_f32 v108, v108, s0
	global_store_short v[106:107], v108, off sc1
	v_mul_f32_e32 v108, v196, v103
	v_lshl_add_u64 v[106:107], v[128:129], 1, s[8:9]
	v_cvt_pk_bf16_f32 v108, v108, s0
	global_store_short v[106:107], v108, off sc1
	v_add_f32_e32 v106, 1.0, v130
	v_mul_f32_e32 v107, v131, v106
	v_add_u32_e32 v108, v191, v48
	v_ashrrev_i32_e32 v109, 31, v108
	v_mul_f32_e32 v32, v107, v197
	v_fmac_f32_e32 v62, v34, v195
	v_fmac_f32_e32 v61, v35, v195
	v_fmac_f32_e32 v60, v36, v195
	v_fmac_f32_e32 v59, v37, v195
	v_fmac_f32_e32 v58, v38, v195
	v_fmac_f32_e32 v57, v39, v195
	v_fmac_f32_e32 v56, v40, v195
	v_fmac_f32_e32 v55, v41, v195
	v_fmac_f32_e32 v54, v42, v195
	v_fmac_f32_e32 v53, v43, v195
	v_fmac_f32_e32 v52, v44, v195
	v_fmac_f32_e32 v51, v45, v195
	v_fmac_f32_e32 v50, v46, v195
	v_fmac_f32_e32 v49, v47, v195
	global_store_dword v[104:105], v197, off offset:128 sc1
	v_lshl_add_u64 v[108:109], v[108:109], 1, s[8:9]
	v_cvt_pk_bf16_f32 v32, v32, s0
	global_store_dword v[84:85], v62, off offset:128 sc1
	global_store_dword v[82:83], v61, off offset:128 sc1
	global_store_dword v[78:79], v60, off offset:128 sc1
	global_store_dword v[72:73], v59, off offset:128 sc1
	global_store_dword v[74:75], v58, off offset:128 sc1
	global_store_dword v[76:77], v57, off offset:128 sc1
	global_store_dword v[80:81], v56, off offset:128 sc1
	global_store_dword v[86:87], v55, off offset:128 sc1
	global_store_dword v[90:91], v54, off offset:128 sc1
	global_store_dword v[92:93], v53, off offset:128 sc1
	global_store_dword v[94:95], v52, off offset:128 sc1
	global_store_dword v[96:97], v51, off offset:128 sc1
	global_store_dword v[98:99], v50, off offset:128 sc1
	global_store_dword v[100:101], v49, off offset:128 sc1
	global_store_short v[108:109], v32, off sc1
	v_add_u32_e32 v108, v187, v48
	v_mov_b32_e32 v45, v221
	v_ashrrev_i32_e32 v109, 31, v108
	v_mul_f32_e32 v113, v107, v56
	v_cvt_pk_bf16_f32 v113, v113, s0
	v_mul_f32_e32 v106, v197, v197
	v_fmac_f32_e32 v106, v198, v198
	v_fmac_f32_e32 v63, v33, v195
	v_mul_f32_e32 v34, v107, v63
	v_lshl_add_u64 v[32:33], v[108:109], 1, s[8:9]
	v_cvt_pk_bf16_f32 v34, v34, s0
	global_store_short v[32:33], v34, off sc1
	v_add_u32_e32 v32, v185, v48
	v_ashrrev_i32_e32 v33, 31, v32
	v_mul_f32_e32 v34, v107, v62
	v_lshl_add_u64 v[32:33], v[32:33], 1, s[8:9]
	v_cvt_pk_bf16_f32 v34, v34, s0
	global_store_short v[32:33], v34, off sc1
	v_add_u32_e32 v32, v184, v48
	v_ashrrev_i32_e32 v33, 31, v32
	v_mul_f32_e32 v34, v107, v61
	v_lshl_add_u64 v[32:33], v[32:33], 1, s[8:9]
	v_cvt_pk_bf16_f32 v34, v34, s0
	global_store_short v[32:33], v34, off sc1
	v_add_u32_e32 v32, v182, v48
	v_ashrrev_i32_e32 v33, 31, v32
	v_mul_f32_e32 v34, v107, v60
	v_lshl_add_u64 v[32:33], v[32:33], 1, s[8:9]
	v_cvt_pk_bf16_f32 v34, v34, s0
	global_store_short v[32:33], v34, off sc1
	v_add_u32_e32 v32, v180, v48
	v_ashrrev_i32_e32 v33, 31, v32
	v_lshl_add_u64 v[34:35], v[32:33], 1, s[8:9]
	v_mul_f32_e32 v32, v107, v59
	v_cvt_pk_bf16_f32 v42, v32, s0
	v_or_b32_e32 v32, 64, v102
	v_ashrrev_i32_e32 v33, 31, v32
	v_lshlrev_b64 v[36:37], 2, v[32:33]
	global_store_dword v[88:89], v63, off offset:128 sc1
	v_lshl_add_u64 v[40:41], s[64:65], 0, v[36:37]
	v_lshl_add_u64 v[38:39], s[62:63], 0, v[36:37]
	v_mov_b32_e32 v110, v222
	v_mov_b32_e32 v111, v223
	v_mul_f32_e32 v33, v107, v58
	global_store_short v[34:35], v42, off sc1
	v_lshl_add_u64 v[34:35], s[60:61], 0, v[36:37]
	v_mov_b32_e32 v112, v224
	v_add_u32_e32 v34, v71, v48
	v_ashrrev_i32_e32 v35, 31, v34
	v_lshl_add_u64 v[34:35], v[34:35], 1, s[8:9]
	v_cvt_pk_bf16_f32 v33, v33, s0
	global_store_short v[34:35], v33, off sc1
	v_add_u32_e32 v34, v181, v48
	v_ashrrev_i32_e32 v35, 31, v34
	v_mul_f32_e32 v33, v107, v57
	v_lshl_add_u64 v[34:35], v[34:35], 1, s[8:9]
	v_cvt_pk_bf16_f32 v33, v33, s0
	v_mov_b32_e32 v38, v225
	v_mov_b32_e32 v37, v226
	v_mov_b32_e32 v36, v227
	v_mov_b32_e32 v114, v229
	v_mov_b32_e32 v47, v230
	v_mov_b32_e32 v39, v231
	v_mov_b32_e32 v46, v232
	v_mov_b32_e32 v44, v233
	v_mov_b32_e32 v43, v234
	v_mov_b32_e32 v42, v235
	v_mov_b32_e32 v40, v236
	v_mov_b32_e32 v41, v237
	v_add_u32_e32 v108, v183, v48
	global_store_short v[34:35], v33, off sc1
	v_mov_b32_e32 v35, v238
	v_ashrrev_i32_e32 v109, 31, v108
	v_mov_b32_e32 v34, v239
	v_mov_b32_e32 v33, v240
	v_lshl_add_u64 v[108:109], v[108:109], 1, s[8:9]
	global_store_short v[108:109], v113, off sc1
	v_add_u32_e32 v108, v186, v48
	v_ashrrev_i32_e32 v109, 31, v108
	v_mul_f32_e32 v113, v107, v55
	v_lshl_add_u64 v[108:109], v[108:109], 1, s[8:9]
	v_cvt_pk_bf16_f32 v113, v113, s0
	global_store_short v[108:109], v113, off sc1
	v_add_u32_e32 v108, v188, v48
	v_ashrrev_i32_e32 v109, 31, v108
	v_mul_f32_e32 v113, v107, v54
	v_lshl_add_u64 v[108:109], v[108:109], 1, s[8:9]
	v_cvt_pk_bf16_f32 v113, v113, s0
	global_store_short v[108:109], v113, off sc1
	v_add_u32_e32 v108, v189, v48
	v_ashrrev_i32_e32 v109, 31, v108
	v_mul_f32_e32 v113, v107, v53
	v_lshl_add_u64 v[108:109], v[108:109], 1, s[8:9]
	v_cvt_pk_bf16_f32 v113, v113, s0
	global_store_short v[108:109], v113, off sc1
	v_add_u32_e32 v108, v190, v48
	v_ashrrev_i32_e32 v109, 31, v108
	v_mul_f32_e32 v113, v107, v52
	v_lshl_add_u64 v[108:109], v[108:109], 1, s[8:9]
	v_cvt_pk_bf16_f32 v113, v113, s0
	global_store_short v[108:109], v113, off sc1
	v_add_u32_e32 v108, v192, v48
	v_ashrrev_i32_e32 v109, 31, v108
	v_mul_f32_e32 v113, v107, v51
	v_lshl_add_u64 v[108:109], v[108:109], 1, s[8:9]
	v_cvt_pk_bf16_f32 v113, v113, s0
	global_store_short v[108:109], v113, off sc1
	v_add_u32_e32 v108, v193, v48
	v_ashrrev_i32_e32 v109, 31, v108
	v_mul_f32_e32 v113, v107, v50
	v_lshl_add_u64 v[108:109], v[108:109], 1, s[8:9]
	v_cvt_pk_bf16_f32 v113, v113, s0
	global_store_short v[108:109], v113, off sc1
	v_add_u32_e32 v108, v194, v48
	v_ashrrev_i32_e32 v109, 31, v108
	v_mul_f32_e32 v48, v107, v49
	v_lshl_add_u64 v[108:109], v[108:109], 1, s[8:9]
	v_cvt_pk_bf16_f32 v48, v48, s0
	global_store_short v[108:109], v48, off sc1
	v_add_u32_e32 v108, v191, v32
	v_ashrrev_i32_e32 v109, 31, v108
	v_add_f32_e32 v48, 1.0, v110
	v_mul_f32_e32 v48, v111, v48
	v_fmac_f32_e32 v45, v17, v112
	global_store_dword v[88:89], v45, off offset:256 sc1
	v_fmac_f32_e32 v38, v26, v112
	v_fmac_f32_e32 v37, v27, v112
	v_fmac_f32_e32 v36, v28, v112
	v_fmac_f32_e32 v114, v16, v112
	v_fmac_f32_e32 v47, v18, v112
	v_mul_f32_e32 v18, v48, v114
	v_lshl_add_u64 v[16:17], v[108:109], 1, s[8:9]
	v_cvt_pk_bf16_f32 v18, v18, s0
	global_store_short v[16:17], v18, off sc1
	v_add_u32_e32 v16, v187, v32
	v_ashrrev_i32_e32 v17, 31, v16
	v_mul_f32_e32 v18, v48, v45
	v_lshl_add_u64 v[16:17], v[16:17], 1, s[8:9]
	v_cvt_pk_bf16_f32 v18, v18, s0
	global_store_short v[16:17], v18, off sc1
	v_add_u32_e32 v16, v185, v32
	v_ashrrev_i32_e32 v17, 31, v16
	v_mul_f32_e32 v18, v48, v47
	v_lshl_add_u64 v[16:17], v[16:17], 1, s[8:9]
	v_cvt_pk_bf16_f32 v18, v18, s0
	v_fmac_f32_e32 v46, v19, v112
	global_store_short v[16:17], v18, off sc1
	v_add_u32_e32 v16, v184, v32
	v_ashrrev_i32_e32 v17, 31, v16
	v_mul_f32_e32 v18, v48, v46
	v_lshl_add_u64 v[16:17], v[16:17], 1, s[8:9]
	v_cvt_pk_bf16_f32 v18, v18, s0
	global_store_short v[16:17], v18, off sc1
	v_add_u32_e32 v16, v182, v32
	v_ashrrev_i32_e32 v17, 31, v16
	v_lshl_add_u64 v[18:19], v[16:17], 1, s[8:9]
	v_or_b32_e32 v16, 0x60, v102
	v_ashrrev_i32_e32 v17, 31, v16
	v_fmac_f32_e32 v44, v20, v112
	v_fmac_f32_e32 v43, v21, v112
	v_fmac_f32_e32 v42, v22, v112
	v_fmac_f32_e32 v41, v23, v112
	v_fmac_f32_e32 v40, v24, v112
	v_fmac_f32_e32 v39, v25, v112
	v_fmac_f32_e32 v35, v29, v112
	v_fmac_f32_e32 v34, v30, v112
	v_fmac_f32_e32 v33, v31, v112
	v_lshlrev_b64 v[20:21], 2, v[16:17]
	global_store_dword v[84:85], v47, off offset:256 sc1
	global_store_dword v[82:83], v46, off offset:256 sc1
	global_store_dword v[78:79], v44, off offset:256 sc1
	global_store_dword v[72:73], v43, off offset:256 sc1
	global_store_dword v[74:75], v42, off offset:256 sc1
	global_store_dword v[76:77], v41, off offset:256 sc1
	global_store_dword v[80:81], v40, off offset:256 sc1
	global_store_dword v[86:87], v39, off offset:256 sc1
	global_store_dword v[90:91], v38, off offset:256 sc1
	global_store_dword v[92:93], v37, off offset:256 sc1
	global_store_dword v[94:95], v36, off offset:256 sc1
	global_store_dword v[96:97], v35, off offset:256 sc1
	global_store_dword v[98:99], v34, off offset:256 sc1
	global_store_dword v[100:101], v33, off offset:256 sc1
	global_store_dword v[104:105], v114, off offset:256 sc1
	v_mul_f32_e32 v26, v48, v44
	v_lshl_add_u64 v[22:23], s[62:63], 0, v[20:21]
	v_lshl_add_u64 v[24:25], s[64:65], 0, v[20:21]
	global_load_dword v29, v[104:105], off offset:384
	global_load_dword v17, v[24:25], off
	global_load_dword v30, v[22:23], off
	v_cvt_pk_bf16_f32 v22, v26, s0
	global_store_short v[18:19], v22, off sc1
	v_lshl_add_u64 v[18:19], s[60:61], 0, v[20:21]
	global_load_dword v102, v[18:19], off
	v_add_u32_e32 v18, v180, v32
	v_ashrrev_i32_e32 v19, 31, v18
	v_mul_f32_e32 v20, v48, v43
	v_lshl_add_u64 v[18:19], v[18:19], 1, s[8:9]
	v_cvt_pk_bf16_f32 v20, v20, s0
	global_store_short v[18:19], v20, off sc1
	v_add_u32_e32 v18, v71, v32
	v_ashrrev_i32_e32 v19, 31, v18
	v_mul_f32_e32 v20, v48, v42
	v_lshl_add_u64 v[18:19], v[18:19], 1, s[8:9]
	v_cvt_pk_bf16_f32 v20, v20, s0
	global_store_short v[18:19], v20, off sc1
	v_add_u32_e32 v18, v181, v32
	v_ashrrev_i32_e32 v19, 31, v18
	v_mul_f32_e32 v20, v48, v41
	v_lshl_add_u64 v[18:19], v[18:19], 1, s[8:9]
	v_cvt_pk_bf16_f32 v20, v20, s0
	global_store_short v[18:19], v20, off sc1
	v_add_u32_e32 v18, v183, v32
	v_ashrrev_i32_e32 v19, 31, v18
	v_mul_f32_e32 v20, v48, v40
	v_lshl_add_u64 v[18:19], v[18:19], 1, s[8:9]
	v_cvt_pk_bf16_f32 v20, v20, s0
	global_store_short v[18:19], v20, off sc1
	v_add_u32_e32 v18, v186, v32
	v_ashrrev_i32_e32 v19, 31, v18
	v_mul_f32_e32 v20, v48, v39
	v_lshl_add_u64 v[18:19], v[18:19], 1, s[8:9]
	v_cvt_pk_bf16_f32 v20, v20, s0
	global_store_short v[18:19], v20, off sc1
	v_add_u32_e32 v18, v188, v32
	v_ashrrev_i32_e32 v19, 31, v18
	v_mul_f32_e32 v20, v48, v38
	v_lshl_add_u64 v[18:19], v[18:19], 1, s[8:9]
	v_cvt_pk_bf16_f32 v20, v20, s0
	global_store_short v[18:19], v20, off sc1
	v_add_u32_e32 v18, v189, v32
	v_ashrrev_i32_e32 v19, 31, v18
	v_mul_f32_e32 v20, v48, v37
	v_lshl_add_u64 v[18:19], v[18:19], 1, s[8:9]
	v_cvt_pk_bf16_f32 v20, v20, s0
	global_store_short v[18:19], v20, off sc1
	v_add_u32_e32 v18, v190, v32
	v_ashrrev_i32_e32 v19, 31, v18
	v_mul_f32_e32 v20, v48, v36
	v_lshl_add_u64 v[18:19], v[18:19], 1, s[8:9]
	v_cvt_pk_bf16_f32 v20, v20, s0
	global_store_short v[18:19], v20, off sc1
	v_add_u32_e32 v18, v192, v32
	v_ashrrev_i32_e32 v19, 31, v18
	v_mul_f32_e32 v20, v48, v35
	v_lshl_add_u64 v[18:19], v[18:19], 1, s[8:9]
	v_cvt_pk_bf16_f32 v20, v20, s0
	global_load_dword v28, v[88:89], off offset:384
	global_load_dword v27, v[84:85], off offset:384
	global_load_dword v25, v[78:79], off offset:384
	global_load_dword v24, v[72:73], off offset:384
	global_load_dword v23, v[74:75], off offset:384
	global_load_dword v21, v[80:81], off offset:384
	global_load_dword v22, v[76:77], off offset:384
	v_fmac_f32_e32 v106, v114, v114
	global_store_short v[18:19], v20, off sc1
	v_add_u32_e32 v18, v193, v32
	v_ashrrev_i32_e32 v19, 31, v18
	v_mul_f32_e32 v20, v48, v34
	v_lshl_add_u64 v[18:19], v[18:19], 1, s[8:9]
	v_cvt_pk_bf16_f32 v20, v20, s0
	global_store_short v[18:19], v20, off sc1
	v_add_u32_e32 v18, v194, v32
	v_ashrrev_i32_e32 v19, 31, v18
	v_mul_f32_e32 v20, v48, v33
	v_lshl_add_u64 v[18:19], v[18:19], 1, s[8:9]
	v_cvt_pk_bf16_f32 v20, v20, s0
	global_store_short v[18:19], v20, off sc1
	global_load_dword v20, v[86:87], off offset:384
	s_waitcnt vmcnt(22)
	v_add_f32_e32 v17, 1.0, v17
	global_load_dword v26, v[82:83], off offset:384
	s_waitcnt vmcnt(22)
	v_mul_f32_e32 v32, v30, v17
	v_add_u32_e32 v18, v191, v16
	s_waitcnt vmcnt(20)
	v_fmac_f32_e32 v29, v0, v102
	v_ashrrev_i32_e32 v19, 31, v18
	v_mul_f32_e32 v0, v32, v29
	v_lshl_add_u64 v[18:19], v[18:19], 1, s[8:9]
	v_cvt_pk_bf16_f32 v0, v0, s0
	global_store_short v[18:19], v0, off sc1
	global_load_dword v19, v[90:91], off offset:384
	v_add_u32_e32 v30, v187, v16
	global_load_dword v18, v[92:93], off offset:384
	v_ashrrev_i32_e32 v31, 31, v30
	v_fmac_f32_e32 v106, v29, v29
	global_store_dword v[104:105], v29, off offset:384 sc1
	s_waitcnt vmcnt(15)
	v_fmac_f32_e32 v28, v1, v102
	v_mul_f32_e32 v17, v32, v28
	v_lshl_add_u64 v[0:1], v[30:31], 1, s[8:9]
	v_cvt_pk_bf16_f32 v17, v17, s0
	global_store_short v[0:1], v17, off sc1
	v_add_u32_e32 v0, v185, v16
	s_waitcnt vmcnt(15)
	v_fmac_f32_e32 v27, v2, v102
	global_load_dword v17, v[94:95], off offset:384
	v_ashrrev_i32_e32 v1, 31, v0
	v_mul_f32_e32 v2, v32, v27
	v_lshl_add_u64 v[0:1], v[0:1], 1, s[8:9]
	v_cvt_pk_bf16_f32 v2, v2, s0
	global_store_short v[0:1], v2, off sc1
	v_add_u32_e32 v0, v184, v16
	global_load_dword v2, v[96:97], off offset:384
	v_ashrrev_i32_e32 v1, 31, v0
	v_lshl_add_u64 v[0:1], v[0:1], 1, s[8:9]
	v_add_u32_e32 v30, v182, v16
	s_waitcnt vmcnt(17)
	v_fmac_f32_e32 v25, v4, v102
	v_ashrrev_i32_e32 v31, 31, v30
	v_lshl_add_u64 v[30:31], v[30:31], 1, s[8:9]
	s_waitcnt vmcnt(16)
	v_fmac_f32_e32 v24, v5, v102
	s_waitcnt vmcnt(15)
	v_fmac_f32_e32 v23, v6, v102
	s_waitcnt vmcnt(8)
	v_fmac_f32_e32 v26, v3, v102
	v_mul_f32_e32 v3, v32, v26
	v_cvt_pk_bf16_f32 v3, v3, s0
	global_store_short v[0:1], v3, off sc1
	global_load_dword v1, v[98:99], off offset:384
	v_mul_f32_e32 v0, v32, v25
	v_cvt_pk_bf16_f32 v0, v0, s0
	global_store_short v[30:31], v0, off sc1
	global_load_dword v0, v[100:101], off offset:384
	v_add_u32_e32 v30, v180, v16
	v_ashrrev_i32_e32 v31, 31, v30
	v_mul_f32_e32 v3, v32, v24
	v_lshl_add_u64 v[4:5], v[30:31], 1, s[8:9]
	v_cvt_pk_bf16_f32 v3, v3, s0
	global_store_short v[4:5], v3, off sc1
	v_add_u32_e32 v4, v71, v16
	v_ashrrev_i32_e32 v5, 31, v4
	v_mul_f32_e32 v3, v32, v23
	v_lshl_add_u64 v[4:5], v[4:5], 1, s[8:9]
	v_cvt_pk_bf16_f32 v3, v3, s0
	global_store_short v[4:5], v3, off sc1
	v_add_u32_e32 v4, v181, v16
	v_fmac_f32_e32 v22, v7, v102
	v_ashrrev_i32_e32 v5, 31, v4
	v_mul_f32_e32 v3, v32, v22
	v_lshl_add_u64 v[4:5], v[4:5], 1, s[8:9]
	v_cvt_pk_bf16_f32 v3, v3, s0
	global_store_short v[4:5], v3, off sc1
	v_add_u32_e32 v4, v183, v16
	v_fmac_f32_e32 v21, v8, v102
	v_ashrrev_i32_e32 v5, 31, v4
	v_mul_f32_e32 v3, v32, v21
	v_lshl_add_u64 v[4:5], v[4:5], 1, s[8:9]
	v_cvt_pk_bf16_f32 v3, v3, s0
	global_store_short v[4:5], v3, off sc1
	v_add_u32_e32 v4, v186, v16
	v_fmac_f32_e32 v20, v9, v102
	v_ashrrev_i32_e32 v5, 31, v4
	v_mul_f32_e32 v3, v32, v20
	v_lshl_add_u64 v[4:5], v[4:5], 1, s[8:9]
	v_cvt_pk_bf16_f32 v3, v3, s0
	global_store_short v[4:5], v3, off sc1
	v_add_u32_e32 v4, v188, v16
	s_waitcnt vmcnt(15)
	v_fmac_f32_e32 v19, v10, v102
	v_ashrrev_i32_e32 v5, 31, v4
	v_mul_f32_e32 v3, v32, v19
	v_lshl_add_u64 v[4:5], v[4:5], 1, s[8:9]
	v_cvt_pk_bf16_f32 v3, v3, s0
	global_store_short v[4:5], v3, off sc1
	v_add_u32_e32 v4, v189, v16
	s_waitcnt vmcnt(15)
	v_fmac_f32_e32 v18, v11, v102
	v_ashrrev_i32_e32 v5, 31, v4
	v_mul_f32_e32 v3, v32, v18
	v_lshl_add_u64 v[4:5], v[4:5], 1, s[8:9]
	v_cvt_pk_bf16_f32 v3, v3, s0
	global_store_short v[4:5], v3, off sc1
	v_add_u32_e32 v4, v190, v16
	v_ashrrev_i32_e32 v5, 31, v4
	v_lshl_add_u64 v[4:5], v[4:5], 1, s[8:9]
	v_ashrrev_i32_e32 v71, 31, v70
	global_store_dword v[88:89], v28, off offset:384 sc1
	global_store_dword v[84:85], v27, off offset:384 sc1
	global_store_dword v[82:83], v26, off offset:384 sc1
	global_store_dword v[78:79], v25, off offset:384 sc1
	s_waitcnt vmcnt(17)
	v_fmac_f32_e32 v17, v12, v102
	v_mul_f32_e32 v3, v32, v17
	v_cvt_pk_bf16_f32 v3, v3, s0
	global_store_short v[4:5], v3, off sc1
	v_add_u32_e32 v4, v192, v16
	v_ashrrev_i32_e32 v5, 31, v4
	v_lshl_add_u64 v[4:5], v[4:5], 1, s[8:9]
	s_waitcnt vmcnt(16)
	v_fmac_f32_e32 v2, v13, v102
	v_mul_f32_e32 v3, v32, v2
	v_cvt_pk_bf16_f32 v3, v3, s0
	global_store_short v[4:5], v3, off sc1
	v_add_u32_e32 v4, v193, v16
	v_ashrrev_i32_e32 v5, 31, v4
	v_lshl_add_u64 v[4:5], v[4:5], 1, s[8:9]
	v_xor_b32_e32 v12, 16, v165
	global_store_dword v[72:73], v24, off offset:384 sc1
	global_store_dword v[74:75], v23, off offset:384 sc1
	global_store_dword v[76:77], v22, off offset:384 sc1
	global_store_dword v[80:81], v21, off offset:384 sc1
	global_store_dword v[86:87], v20, off offset:384 sc1
	s_waitcnt vmcnt(20)
	v_fmac_f32_e32 v1, v14, v102
	v_mul_f32_e32 v3, v32, v1
	v_cvt_pk_bf16_f32 v3, v3, s0
	global_store_short v[4:5], v3, off sc1
	v_add_u32_e32 v4, v194, v16
	v_ashrrev_i32_e32 v5, 31, v4
	v_lshl_add_u64 v[10:11], v[4:5], 1, s[8:9]
	v_and_b32_e32 v4, 64, v165
	v_xor_b32_e32 v3, 1, v165
	v_add_u32_e32 v7, 64, v4
	v_cmp_lt_i32_e32 vcc, v3, v7
	v_xor_b32_e32 v4, 2, v165
	s_waitcnt vmcnt(19)
	v_fmac_f32_e32 v0, v15, v102
	v_cndmask_b32_e32 v3, v165, v3, vcc
	v_lshlrev_b32_e32 v3, 2, v3
	v_cmp_lt_i32_e32 vcc, v4, v7
	global_store_dword v[90:91], v19, off offset:384 sc1
	global_store_dword v[92:93], v18, off offset:384 sc1
	v_cndmask_b32_e32 v4, v165, v4, vcc
	v_lshlrev_b32_e32 v4, 2, v4
	v_add_f32_dpp v6, v106, v106 quad_perm:[1,0,3,2] row_mask:0xf bank_mask:0xf
	v_xor_b32_e32 v5, 4, v165
	v_cmp_lt_i32_e32 vcc, v5, v7
	global_store_dword v[94:95], v17, off offset:384 sc1
	global_store_dword v[96:97], v2, off offset:384 sc1
	v_cndmask_b32_e32 v5, v165, v5, vcc
	v_lshlrev_b32_e32 v5, 2, v5
	v_add_f32_dpp v8, v6, v6 quad_perm:[2,3,0,1] row_mask:0xf bank_mask:0xf
	v_xor_b32_e32 v6, 8, v165
	v_cmp_lt_i32_e32 vcc, v6, v7
	global_store_dword v[98:99], v1, off offset:384 sc1
	global_store_dword v[100:101], v0, off offset:384 sc1
	v_cndmask_b32_e32 v6, v165, v6, vcc
	v_lshlrev_b32_e32 v6, 2, v6
	v_add_f32_dpp v8, v8, v8 row_half_mirror row_mask:0xf bank_mask:0xf
	v_cmp_lt_i32_e32 vcc, v12, v7
	v_add_f32_dpp v8, v8, v8 row_mirror row_mask:0xf bank_mask:0xf
	v_cndmask_b32_e32 v7, v165, v12, vcc
	v_lshlrev_b32_e32 v7, 2, v7
	ds_bpermute_b32 v9, v7, v8
	v_mul_f32_e32 v12, v32, v0
	v_cvt_pk_bf16_f32 v12, v12, s0
	global_store_short v[10:11], v12, off sc1
	s_and_saveexec_b64 s[60:61], s[0:1]
	s_cbranch_execz .LBB0_781
	s_waitcnt lgkmcnt(0)
	v_add_f32_e32 v10, v8, v9
	v_lshl_add_u64 v[8:9], v[70:71], 2, s[58:59]
	global_store_dword v[8:9], v10, off sc1

.LBB0_1022:
	ds_read_b128 v[2:5], v193
	ds_read_b128 v[6:9], v193 offset:32
	ds_read_b128 v[228:231], v193 offset:64
	ds_read_b128 v[232:235], v193 offset:96
	s_waitcnt lgkmcnt(3)
	v_mfma_f32_32x32x16_bf16 v[80:95], v[2:5], v[96:99], 0
	s_waitcnt lgkmcnt(2)
	v_mfma_f32_32x32x16_bf16 v[80:95], v[6:9], v[100:103], v[80:95]
	s_waitcnt lgkmcnt(1)
	v_mfma_f32_32x32x16_bf16 v[80:95], v[228:231], v[104:107], v[80:95]
	s_waitcnt lgkmcnt(0)
	v_mfma_f32_32x32x16_bf16 v[80:95], v[232:235], v[108:111], v[80:95]
	s_nop 11
	v_max_f32_e32 v1, v80, v81
	v_max3_f32 v1, v1, v82, v83
	v_max3_f32 v1, v1, v84, v85
	v_max3_f32 v1, v1, v86, v87
	v_max3_f32 v1, v1, v88, v89
	v_max3_f32 v1, v1, v90, v91
	v_max3_f32 v1, v1, v92, v93
	v_max3_f32 v1, v1, v94, v95
	v_mov_b32_e32 v2, v1
	s_nop 1
	v_permlane32_swap_b32_e32 v2, v1
	s_waitcnt lgkmcnt(0)
	v_max_f32_e32 v1, v1, v2
	v_mul_f32_e32 v1, 0x3e38aa3b, v1
	v_add_f32_e32 v250, 0xc1000000, v1
	v_cmp_gt_f32_e32 vcc, v250, v180
	s_cbranch_vccz .LBB0_1024
	v_max_f32_e32 v1, v1, v1
	v_max_f32_e32 v2, v180, v180
	v_max_f32_e32 v1, v2, v1
	v_sub_f32_e32 v2, v180, v1
	v_exp_f32_e32 v2, v2
	v_mov_b32_e32 v180, v1
	v_pk_mul_f32 v[78:79], v[78:79], v[2:3] op_sel_hi:[1,0]
	v_pk_mul_f32 v[76:77], v[76:77], v[2:3] op_sel_hi:[1,0]
	v_pk_mul_f32 v[74:75], v[74:75], v[2:3] op_sel_hi:[1,0]
	v_pk_mul_f32 v[72:73], v[72:73], v[2:3] op_sel_hi:[1,0]
	v_pk_mul_f32 v[70:71], v[70:71], v[2:3] op_sel_hi:[1,0]
	v_pk_mul_f32 v[68:69], v[68:69], v[2:3] op_sel_hi:[1,0]
	v_pk_mul_f32 v[66:67], v[66:67], v[2:3] op_sel_hi:[1,0]
	v_pk_mul_f32 v[64:65], v[64:65], v[2:3] op_sel_hi:[1,0]
	v_pk_mul_f32 v[62:63], v[62:63], v[2:3] op_sel_hi:[1,0]
	v_pk_mul_f32 v[60:61], v[60:61], v[2:3] op_sel_hi:[1,0]
	v_pk_mul_f32 v[58:59], v[58:59], v[2:3] op_sel_hi:[1,0]
	v_pk_mul_f32 v[56:57], v[56:57], v[2:3] op_sel_hi:[1,0]
	v_pk_mul_f32 v[54:55], v[54:55], v[2:3] op_sel_hi:[1,0]
	v_pk_mul_f32 v[52:53], v[52:53], v[2:3] op_sel_hi:[1,0]
	v_pk_mul_f32 v[50:51], v[50:51], v[2:3] op_sel_hi:[1,0]
	v_pk_mul_f32 v[48:49], v[48:49], v[2:3] op_sel_hi:[1,0]
	v_pk_mul_f32 v[46:47], v[46:47], v[2:3] op_sel_hi:[1,0]
	v_pk_mul_f32 v[44:45], v[44:45], v[2:3] op_sel_hi:[1,0]
	v_pk_mul_f32 v[42:43], v[42:43], v[2:3] op_sel_hi:[1,0]
	v_pk_mul_f32 v[40:41], v[40:41], v[2:3] op_sel_hi:[1,0]
	v_pk_mul_f32 v[38:39], v[38:39], v[2:3] op_sel_hi:[1,0]
	v_pk_mul_f32 v[36:37], v[36:37], v[2:3] op_sel_hi:[1,0]
	v_pk_mul_f32 v[34:35], v[34:35], v[2:3] op_sel_hi:[1,0]
	v_pk_mul_f32 v[32:33], v[32:33], v[2:3] op_sel_hi:[1,0]
	v_pk_mul_f32 v[30:31], v[30:31], v[2:3] op_sel_hi:[1,0]
	v_pk_mul_f32 v[28:29], v[28:29], v[2:3] op_sel_hi:[1,0]
	v_pk_mul_f32 v[26:27], v[26:27], v[2:3] op_sel_hi:[1,0]
	v_pk_mul_f32 v[24:25], v[24:25], v[2:3] op_sel_hi:[1,0]
	v_pk_mul_f32 v[22:23], v[22:23], v[2:3] op_sel_hi:[1,0]
	v_pk_mul_f32 v[20:21], v[20:21], v[2:3] op_sel_hi:[1,0]
	v_pk_mul_f32 v[18:19], v[18:19], v[2:3] op_sel_hi:[1,0]
	v_pk_mul_f32 v[16:17], v[16:17], v[2:3] op_sel_hi:[1,0]
	v_mul_f32_e32 v196, v196, v2

.LBB0_1050:
	s_add_i32 s58, s66, 0xffffe000
	s_lshr_b32 s58, s58, 12
	s_mulk_i32 s58, 0x1800
	v_mov_b32_e32 v70, s70
	s_addk_i32 s58, 0x6000
	ds_read_b64 v[70:71], v70
	s_cmp_gt_i32 s6, 63
	s_cselect_b32 s6, s58, 0x4800
	s_lshl_b64 s[58:59], s[6:7], 2
	s_add_u32 s6, s14, s58
	s_addc_u32 s65, s15, s59
	s_waitcnt lgkmcnt(0)
	v_readfirstlane_b32 s58, v70
	v_readfirstlane_b32 s59, v71
	s_add_u32 s60, s58, 0x1000
	s_addc_u32 s61, s59, 0
	s_lshl_b32 s58, s64, 14
	s_add_i32 s58, s58, 0x60000
	s_ashr_i32 s59, s58, 31
	s_lshl_b64 s[58:59], s[58:59], 2
	s_add_u32 s58, s10, s58
	s_addc_u32 s59, s11, s59
	s_add_u32 s62, s6, 0x5ba2000
	v_or_b32_e32 v102, s68, v138
	v_add_u32_e32 v70, s66, v139
	s_addc_u32 s63, s65, 0
	v_lshlrev_b32_e32 v188, 10, v70
	v_ashrrev_i32_e32 v103, 31, v102
	s_add_u32 s64, s6, 0x5ba4000
	v_lshlrev_b64 v[72:73], 2, v[102:103]
	v_or_b32_e32 v186, 0x400, v188
	v_or_b32_e32 v185, 0x4400, v188
	v_or_b32_e32 v189, 0x4c00, v188
	v_or_b32_e32 v193, 0x6c00, v188
	s_addc_u32 s65, s65, 0
	v_lshl_add_u64 v[74:75], s[62:63], 0, v[72:73]
	v_add_u32_e32 v132, v188, v102
	v_add_u32_e32 v134, v186, v102
	v_or_b32_e32 v184, 0x800, v188
	v_or_b32_e32 v183, 0xc00, v188
	v_or_b32_e32 v181, 0x2000, v188
	v_or_b32_e32 v179, 0x2400, v188
	v_or_b32_e32 v71, 0x2800, v188
	v_or_b32_e32 v180, 0x2c00, v188
	v_or_b32_e32 v182, 0x4000, v188
	v_add_u32_e32 v112, v185, v102
	v_or_b32_e32 v187, 0x4800, v188
	v_add_u32_e32 v118, v189, v102
	v_or_b32_e32 v190, 0x6000, v188
	v_or_b32_e32 v191, 0x6400, v188
	v_or_b32_e32 v192, 0x6800, v188
	v_add_u32_e32 v128, v193, v102
	global_load_dword v194, v[74:75], off
	global_load_dword v204, v[74:75], off offset:128
	global_load_dword v223, v[74:75], off offset:256
	v_lshl_add_u64 v[74:75], s[60:61], 0, v[72:73]
	v_lshl_add_u64 v[72:73], s[64:65], 0, v[72:73]
	v_ashrrev_i32_e32 v135, 31, v134
	v_add_u32_e32 v136, v184, v102
	v_add_u32_e32 v130, v183, v102
	v_add_u32_e32 v122, v181, v102
	v_add_u32_e32 v114, v179, v102
	v_add_u32_e32 v106, v71, v102
	v_add_u32_e32 v108, v180, v102
	v_add_u32_e32 v110, v182, v102
	v_ashrrev_i32_e32 v113, 31, v112
	v_add_u32_e32 v116, v187, v102
	v_ashrrev_i32_e32 v119, 31, v118
	v_add_u32_e32 v120, v190, v102
	v_add_u32_e32 v124, v191, v102
	v_add_u32_e32 v126, v192, v102
	v_ashrrev_i32_e32 v129, 31, v128
	v_ashrrev_i32_e32 v133, 31, v132
	global_load_dword v196, v[72:73], off
	global_load_dword v202, v[72:73], off offset:128
	global_load_dword v221, v[72:73], off offset:256
	v_lshl_add_u64 v[88:89], v[134:135], 2, s[12:13]
	v_ashrrev_i32_e32 v137, 31, v136
	v_ashrrev_i32_e32 v131, 31, v130
	v_ashrrev_i32_e32 v123, 31, v122
	v_ashrrev_i32_e32 v115, 31, v114
	v_ashrrev_i32_e32 v107, 31, v106
	v_ashrrev_i32_e32 v109, 31, v108
	v_ashrrev_i32_e32 v111, 31, v110
	v_lshl_add_u64 v[86:87], v[112:113], 2, s[12:13]
	v_ashrrev_i32_e32 v117, 31, v116
	v_lshl_add_u64 v[92:93], v[118:119], 2, s[12:13]
	v_ashrrev_i32_e32 v121, 31, v120
	v_ashrrev_i32_e32 v125, 31, v124
	v_ashrrev_i32_e32 v127, 31, v126
	v_lshl_add_u64 v[100:101], v[128:129], 2, s[12:13]
	v_lshl_add_u64 v[104:105], v[132:133], 2, s[12:13]
	global_load_dword v195, v[74:75], off
	global_load_dword v203, v[74:75], off offset:128
	global_load_dword v222, v[74:75], off offset:256
	v_lshl_add_u64 v[84:85], v[136:137], 2, s[12:13]
	v_lshl_add_u64 v[82:83], v[130:131], 2, s[12:13]
	v_lshl_add_u64 v[78:79], v[122:123], 2, s[12:13]
	v_lshl_add_u64 v[72:73], v[114:115], 2, s[12:13]
	v_lshl_add_u64 v[74:75], v[106:107], 2, s[12:13]
	v_lshl_add_u64 v[76:77], v[108:109], 2, s[12:13]
	v_lshl_add_u64 v[80:81], v[110:111], 2, s[12:13]
	global_load_dword v178, v[88:89], off
	global_load_dword v177, v[84:85], off
	global_load_dword v176, v[82:83], off
	global_load_dword v175, v[78:79], off
	global_load_dword v174, v[72:73], off
	global_load_dword v173, v[74:75], off
	global_load_dword v172, v[76:77], off
	global_load_dword v171, v[80:81], off
	v_lshl_add_u64 v[90:91], v[116:117], 2, s[12:13]
	global_load_dword v170, v[86:87], off
	global_load_dword v168, v[90:91], off
	v_lshl_add_u64 v[94:95], v[120:121], 2, s[12:13]
	v_lshl_add_u64 v[96:97], v[124:125], 2, s[12:13]
	v_lshl_add_u64 v[98:99], v[126:127], 2, s[12:13]
	global_load_dword v169, v[92:93], off
	global_load_dword v167, v[94:95], off
	global_load_dword v166, v[96:97], off
	global_load_dword v165, v[98:99], off
	global_load_dword v103, v[100:101], off
	global_load_dword v197, v[104:105], off
	v_lshl_add_u64 v[106:107], v[106:107], 1, s[8:9]
	global_load_dword v198, v[104:105], off offset:128
	global_load_dword v205, v[84:85], off offset:128
	global_load_dword v206, v[78:79], off offset:128
	global_load_dword v207, v[72:73], off offset:128
	global_load_dword v208, v[74:75], off offset:128
	global_load_dword v209, v[80:81], off offset:128
	global_load_dword v210, v[76:77], off offset:128
	global_load_dword v211, v[86:87], off offset:128
	global_load_dword v212, v[82:83], off offset:128
	global_load_dword v213, v[90:91], off offset:128
	global_load_dword v214, v[92:93], off offset:128
	global_load_dword v215, v[94:95], off offset:128
	global_load_dword v216, v[96:97], off offset:128
	global_load_dword v217, v[98:99], off offset:128
	global_load_dword v218, v[100:101], off offset:128
	global_load_dword v219, v[88:89], off offset:128
	global_load_dword v220, v[88:89], off offset:256
	global_load_dword v224, v[90:91], off offset:256
	global_load_dword v225, v[92:93], off offset:256
	global_load_dword v226, v[94:95], off offset:256
	global_load_dword v227, v[104:105], off offset:256
	global_load_dword v229, v[84:85], off offset:256
	global_load_dword v230, v[86:87], off offset:256
	global_load_dword v231, v[82:83], off offset:256
	global_load_dword v232, v[78:79], off offset:256
	global_load_dword v233, v[72:73], off offset:256
	global_load_dword v234, v[74:75], off offset:256
	global_load_dword v235, v[80:81], off offset:256
	global_load_dword v236, v[76:77], off offset:256
	global_load_dword v237, v[96:97], off offset:256
	global_load_dword v238, v[98:99], off offset:256
	global_load_dword v239, v[100:101], off offset:256
	s_waitcnt vmcnt(0)
	v_add_f32_e32 v196, 1.0, v196
	v_mul_f32_e32 v195, v195, v196
	v_fmac_f32_e32 v178, v49, v194
	v_fmac_f32_e32 v177, v50, v194
	v_fmac_f32_e32 v176, v51, v194
	v_fmac_f32_e32 v175, v52, v194
	v_fmac_f32_e32 v174, v53, v194
	v_fmac_f32_e32 v173, v54, v194
	v_fmac_f32_e32 v172, v55, v194
	v_fmac_f32_e32 v171, v56, v194
	v_fmac_f32_e32 v170, v57, v194
	v_fmac_f32_e32 v168, v58, v194
	v_fmac_f32_e32 v169, v59, v194
	v_fmac_f32_e32 v167, v60, v194
	v_fmac_f32_e32 v166, v61, v194
	v_fmac_f32_e32 v165, v62, v194
	v_fmac_f32_e32 v103, v63, v194
	v_fmac_f32_e32 v197, v48, v194
	v_mul_f32_e32 v48, v195, v197
	v_cvt_pk_bf16_f32 v58, v48, s0
	v_or_b32_e32 v48, 32, v102
	v_ashrrev_i32_e32 v49, 31, v48
	v_lshlrev_b64 v[52:53], 2, v[48:49]
	global_store_dword v[88:89], v178, off sc1
	global_store_dword v[84:85], v177, off sc1
	global_store_dword v[82:83], v176, off sc1
	global_store_dword v[78:79], v175, off sc1
	global_store_dword v[72:73], v174, off sc1
	global_store_dword v[74:75], v173, off sc1
	global_store_dword v[76:77], v172, off sc1
	global_store_dword v[80:81], v171, off sc1
	global_store_dword v[86:87], v170, off sc1
	global_store_dword v[90:91], v168, off sc1
	global_store_dword v[92:93], v169, off sc1
	global_store_dword v[94:95], v167, off sc1
	global_store_dword v[96:97], v166, off sc1
	global_store_dword v[98:99], v165, off sc1
	global_store_dword v[100:101], v103, off sc1
	global_store_dword v[104:105], v197, off sc1
	v_lshl_add_u64 v[50:51], v[132:133], 1, s[8:9]
	v_lshl_add_u64 v[56:57], s[64:65], 0, v[52:53]
	v_mov_b32_e32 v196, v198
	v_lshl_add_u64 v[54:55], s[60:61], 0, v[52:53]
	v_mov_b32_e32 v132, v202
	v_mov_b32_e32 v133, v203
	v_mul_f32_e32 v49, v195, v178
	global_store_short v[50:51], v58, off sc1
	v_lshl_add_u64 v[50:51], s[62:63], 0, v[52:53]
	v_mov_b32_e32 v194, v204
	v_cvt_pk_bf16_f32 v49, v49, s0
	v_lshl_add_u64 v[50:51], v[134:135], 1, s[8:9]
	global_store_short v[50:51], v49, off sc1
	v_mul_f32_e32 v49, v195, v177
	v_cvt_pk_bf16_f32 v49, v49, s0
	v_lshl_add_u64 v[50:51], v[136:137], 1, s[8:9]
	global_store_short v[50:51], v49, off sc1
	v_mul_f32_e32 v49, v195, v176
	v_cvt_pk_bf16_f32 v49, v49, s0
	v_lshl_add_u64 v[50:51], v[130:131], 1, s[8:9]
	global_store_short v[50:51], v49, off sc1
	v_mul_f32_e32 v49, v195, v175
	v_cvt_pk_bf16_f32 v49, v49, s0
	v_lshl_add_u64 v[50:51], v[122:123], 1, s[8:9]
	global_store_short v[50:51], v49, off sc1
	v_mul_f32_e32 v49, v195, v174
	v_cvt_pk_bf16_f32 v49, v49, s0
	v_lshl_add_u64 v[50:51], v[114:115], 1, s[8:9]
	global_store_short v[50:51], v49, off sc1
	v_mul_f32_e32 v49, v195, v173
	v_mov_b32_e32 v62, v205
	v_mov_b32_e32 v60, v206
	v_mov_b32_e32 v59, v207
	v_mov_b32_e32 v58, v208
	v_mov_b32_e32 v56, v209
	v_mov_b32_e32 v57, v210
	v_mov_b32_e32 v55, v211
	v_mov_b32_e32 v61, v212
	v_mov_b32_e32 v54, v213
	v_mov_b32_e32 v53, v214
	v_mov_b32_e32 v52, v215
	v_mov_b32_e32 v51, v216
	v_mov_b32_e32 v50, v217
	v_cvt_pk_bf16_f32 v63, v49, s0
	v_mov_b32_e32 v49, v218
	v_fmac_f32_e32 v196, v32, v194
	global_store_short v[106:107], v63, off sc1
	v_mov_b32_e32 v63, v219
	v_mul_f32_e32 v106, v195, v172
	v_cvt_pk_bf16_f32 v114, v106, s0
	v_lshl_add_u64 v[106:107], v[108:109], 1, s[8:9]
	global_store_short v[106:107], v114, off sc1
	v_mul_f32_e32 v106, v195, v171
	v_cvt_pk_bf16_f32 v108, v106, s0
	v_lshl_add_u64 v[106:107], v[110:111], 1, s[8:9]
	global_store_short v[106:107], v108, off sc1
	v_mul_f32_e32 v106, v195, v170
	v_cvt_pk_bf16_f32 v108, v106, s0
	v_lshl_add_u64 v[106:107], v[112:113], 1, s[8:9]
	global_store_short v[106:107], v108, off sc1
	v_mul_f32_e32 v106, v195, v168
	v_cvt_pk_bf16_f32 v108, v106, s0
	v_lshl_add_u64 v[106:107], v[116:117], 1, s[8:9]
	global_store_short v[106:107], v108, off sc1
	v_mul_f32_e32 v106, v195, v169
	v_cvt_pk_bf16_f32 v108, v106, s0
	v_lshl_add_u64 v[106:107], v[118:119], 1, s[8:9]
	global_store_short v[106:107], v108, off sc1
	v_mul_f32_e32 v106, v195, v167
	v_cvt_pk_bf16_f32 v108, v106, s0
	v_lshl_add_u64 v[106:107], v[120:121], 1, s[8:9]
	global_store_short v[106:107], v108, off sc1
	v_mul_f32_e32 v106, v195, v166
	v_cvt_pk_bf16_f32 v108, v106, s0
	v_lshl_add_u64 v[106:107], v[124:125], 1, s[8:9]
	global_store_short v[106:107], v108, off sc1
	v_mul_f32_e32 v106, v195, v165
	v_cvt_pk_bf16_f32 v108, v106, s0
	v_lshl_add_u64 v[106:107], v[126:127], 1, s[8:9]
	global_store_short v[106:107], v108, off sc1
	v_mul_f32_e32 v106, v195, v103
	v_cvt_pk_bf16_f32 v108, v106, s0
	v_lshl_add_u64 v[106:107], v[128:129], 1, s[8:9]
	global_store_short v[106:107], v108, off sc1
	v_add_f32_e32 v106, 1.0, v132
	v_mul_f32_e32 v110, v133, v106
	v_add_u32_e32 v106, v188, v48
	v_fmac_f32_e32 v62, v34, v194
	v_fmac_f32_e32 v61, v35, v194
	v_fmac_f32_e32 v60, v36, v194
	v_fmac_f32_e32 v59, v37, v194
	v_fmac_f32_e32 v58, v38, v194
	v_fmac_f32_e32 v57, v39, v194
	v_fmac_f32_e32 v56, v40, v194
	v_fmac_f32_e32 v55, v41, v194
	v_fmac_f32_e32 v54, v42, v194
	v_fmac_f32_e32 v53, v43, v194
	v_fmac_f32_e32 v52, v44, v194
	v_fmac_f32_e32 v51, v45, v194
	v_fmac_f32_e32 v50, v46, v194
	v_fmac_f32_e32 v49, v47, v194
	v_ashrrev_i32_e32 v107, 31, v106
	global_store_dword v[104:105], v196, off offset:128 sc1
	v_mul_f32_e32 v32, v110, v196
	global_store_dword v[84:85], v62, off offset:128 sc1
	global_store_dword v[82:83], v61, off offset:128 sc1
	global_store_dword v[78:79], v60, off offset:128 sc1
	global_store_dword v[72:73], v59, off offset:128 sc1
	global_store_dword v[74:75], v58, off offset:128 sc1
	global_store_dword v[76:77], v57, off offset:128 sc1
	global_store_dword v[80:81], v56, off offset:128 sc1
	global_store_dword v[86:87], v55, off offset:128 sc1
	global_store_dword v[90:91], v54, off offset:128 sc1
	global_store_dword v[92:93], v53, off offset:128 sc1
	global_store_dword v[94:95], v52, off offset:128 sc1
	global_store_dword v[96:97], v51, off offset:128 sc1
	global_store_dword v[98:99], v50, off offset:128 sc1
	global_store_dword v[100:101], v49, off offset:128 sc1
	v_cvt_pk_bf16_f32 v32, v32, s0
	v_lshl_add_u64 v[106:107], v[106:107], 1, s[8:9]
	v_add_u32_e32 v108, v186, v48
	v_mov_b32_e32 v45, v220
	v_ashrrev_i32_e32 v109, 31, v108
	global_store_short v[106:107], v32, off sc1
	v_mul_f32_e32 v113, v110, v56
	v_cvt_pk_bf16_f32 v113, v113, s0
	v_mul_f32_e32 v106, v196, v196
	v_fmac_f32_e32 v63, v33, v194
	v_mul_f32_e32 v32, v110, v63
	v_cvt_pk_bf16_f32 v34, v32, s0
	v_lshl_add_u64 v[32:33], v[108:109], 1, s[8:9]
	global_store_short v[32:33], v34, off sc1
	v_add_u32_e32 v32, v184, v48
	v_ashrrev_i32_e32 v33, 31, v32
	v_mul_f32_e32 v34, v110, v62
	v_cvt_pk_bf16_f32 v34, v34, s0
	v_lshl_add_u64 v[32:33], v[32:33], 1, s[8:9]
	global_store_short v[32:33], v34, off sc1
	v_add_u32_e32 v32, v183, v48
	v_ashrrev_i32_e32 v33, 31, v32
	v_mul_f32_e32 v34, v110, v61
	v_cvt_pk_bf16_f32 v34, v34, s0
	v_lshl_add_u64 v[32:33], v[32:33], 1, s[8:9]
	global_store_short v[32:33], v34, off sc1
	v_add_u32_e32 v32, v181, v48
	v_ashrrev_i32_e32 v33, 31, v32
	v_mul_f32_e32 v34, v110, v60
	v_cvt_pk_bf16_f32 v34, v34, s0
	v_lshl_add_u64 v[32:33], v[32:33], 1, s[8:9]
	global_store_short v[32:33], v34, off sc1
	v_add_u32_e32 v32, v179, v48
	v_ashrrev_i32_e32 v33, 31, v32
	v_mul_f32_e32 v34, v110, v59
	v_cvt_pk_bf16_f32 v42, v34, s0
	v_lshl_add_u64 v[34:35], v[32:33], 1, s[8:9]
	v_or_b32_e32 v32, 64, v102
	v_ashrrev_i32_e32 v33, 31, v32
	v_lshlrev_b64 v[36:37], 2, v[32:33]
	global_store_dword v[88:89], v63, off offset:128 sc1
	v_lshl_add_u64 v[40:41], s[64:65], 0, v[36:37]
	v_lshl_add_u64 v[38:39], s[60:61], 0, v[36:37]
	v_mov_b32_e32 v107, v221
	v_mov_b32_e32 v111, v222
	v_mul_f32_e32 v33, v110, v58
	global_store_short v[34:35], v42, off sc1
	v_lshl_add_u64 v[34:35], s[62:63], 0, v[36:37]
	v_mov_b32_e32 v112, v223
	v_add_u32_e32 v34, v71, v48
	v_ashrrev_i32_e32 v35, 31, v34
	v_cvt_pk_bf16_f32 v33, v33, s0
	v_lshl_add_u64 v[34:35], v[34:35], 1, s[8:9]
	global_store_short v[34:35], v33, off sc1
	v_add_u32_e32 v34, v180, v48
	v_ashrrev_i32_e32 v35, 31, v34
	v_mul_f32_e32 v33, v110, v57
	v_cvt_pk_bf16_f32 v33, v33, s0
	v_lshl_add_u64 v[34:35], v[34:35], 1, s[8:9]
	v_mov_b32_e32 v38, v224
	v_mov_b32_e32 v37, v225
	v_mov_b32_e32 v36, v226
	v_mov_b32_e32 v114, v227
	v_mov_b32_e32 v47, v229
	v_mov_b32_e32 v39, v230
	v_mov_b32_e32 v46, v231
	v_mov_b32_e32 v44, v232
	v_mov_b32_e32 v43, v233
	v_mov_b32_e32 v42, v234
	v_mov_b32_e32 v40, v235
	v_mov_b32_e32 v41, v236
	v_add_u32_e32 v108, v182, v48
	global_store_short v[34:35], v33, off sc1
	v_mov_b32_e32 v35, v237
	v_ashrrev_i32_e32 v109, 31, v108
	v_mov_b32_e32 v34, v238
	v_mov_b32_e32 v33, v239
	v_lshl_add_u64 v[108:109], v[108:109], 1, s[8:9]
	global_store_short v[108:109], v113, off sc1
	v_add_u32_e32 v108, v185, v48
	v_ashrrev_i32_e32 v109, 31, v108
	v_mul_f32_e32 v113, v110, v55
	v_cvt_pk_bf16_f32 v113, v113, s0
	v_lshl_add_u64 v[108:109], v[108:109], 1, s[8:9]
	global_store_short v[108:109], v113, off sc1
	v_add_u32_e32 v108, v187, v48
	v_ashrrev_i32_e32 v109, 31, v108
	v_mul_f32_e32 v113, v110, v54
	v_cvt_pk_bf16_f32 v113, v113, s0
	v_lshl_add_u64 v[108:109], v[108:109], 1, s[8:9]
	global_store_short v[108:109], v113, off sc1
	v_add_u32_e32 v108, v189, v48
	v_ashrrev_i32_e32 v109, 31, v108
	v_mul_f32_e32 v113, v110, v53
	v_cvt_pk_bf16_f32 v113, v113, s0
	v_lshl_add_u64 v[108:109], v[108:109], 1, s[8:9]
	global_store_short v[108:109], v113, off sc1
	v_add_u32_e32 v108, v190, v48
	v_ashrrev_i32_e32 v109, 31, v108
	v_mul_f32_e32 v113, v110, v52
	v_cvt_pk_bf16_f32 v113, v113, s0
	v_lshl_add_u64 v[108:109], v[108:109], 1, s[8:9]
	global_store_short v[108:109], v113, off sc1
	v_add_u32_e32 v108, v191, v48
	v_ashrrev_i32_e32 v109, 31, v108
	v_mul_f32_e32 v113, v110, v51
	v_cvt_pk_bf16_f32 v113, v113, s0
	v_lshl_add_u64 v[108:109], v[108:109], 1, s[8:9]
	global_store_short v[108:109], v113, off sc1
	v_add_u32_e32 v108, v192, v48
	v_ashrrev_i32_e32 v109, 31, v108
	v_mul_f32_e32 v113, v110, v50
	v_cvt_pk_bf16_f32 v113, v113, s0
	v_lshl_add_u64 v[108:109], v[108:109], 1, s[8:9]
	global_store_short v[108:109], v113, off sc1
	v_add_u32_e32 v108, v193, v48
	v_ashrrev_i32_e32 v109, 31, v108
	v_mul_f32_e32 v48, v110, v49
	v_cvt_pk_bf16_f32 v48, v48, s0
	v_lshl_add_u64 v[108:109], v[108:109], 1, s[8:9]
	global_store_short v[108:109], v48, off sc1
	v_add_u32_e32 v108, v188, v32
	v_ashrrev_i32_e32 v109, 31, v108
	v_add_f32_e32 v48, 1.0, v107
	v_mul_f32_e32 v48, v111, v48
	v_fmac_f32_e32 v106, v197, v197
	v_fmac_f32_e32 v45, v17, v112
	global_store_dword v[88:89], v45, off offset:256 sc1
	v_fmac_f32_e32 v38, v26, v112
	v_fmac_f32_e32 v37, v27, v112
	v_fmac_f32_e32 v36, v28, v112
	v_fmac_f32_e32 v114, v16, v112
	v_mul_f32_e32 v16, v48, v114
	v_fmac_f32_e32 v47, v18, v112
	v_cvt_pk_bf16_f32 v18, v16, s0
	v_lshl_add_u64 v[16:17], v[108:109], 1, s[8:9]
	global_store_short v[16:17], v18, off sc1
	v_add_u32_e32 v16, v186, v32
	v_ashrrev_i32_e32 v17, 31, v16
	v_mul_f32_e32 v18, v48, v45
	v_cvt_pk_bf16_f32 v18, v18, s0
	v_lshl_add_u64 v[16:17], v[16:17], 1, s[8:9]
	global_store_short v[16:17], v18, off sc1
	v_add_u32_e32 v16, v184, v32
	v_ashrrev_i32_e32 v17, 31, v16
	v_mul_f32_e32 v18, v48, v47
	v_cvt_pk_bf16_f32 v18, v18, s0
	v_lshl_add_u64 v[16:17], v[16:17], 1, s[8:9]
	v_fmac_f32_e32 v46, v19, v112
	global_store_short v[16:17], v18, off sc1
	v_add_u32_e32 v16, v183, v32
	v_ashrrev_i32_e32 v17, 31, v16
	v_mul_f32_e32 v18, v48, v46
	v_fmac_f32_e32 v44, v20, v112
	v_cvt_pk_bf16_f32 v18, v18, s0
	v_lshl_add_u64 v[16:17], v[16:17], 1, s[8:9]
	global_store_short v[16:17], v18, off sc1
	v_mul_f32_e32 v16, v48, v44
	v_cvt_pk_bf16_f32 v26, v16, s0
	v_or_b32_e32 v16, 0x60, v102
	v_add_u32_e32 v18, v181, v32
	v_ashrrev_i32_e32 v17, 31, v16
	v_fmac_f32_e32 v43, v21, v112
	v_fmac_f32_e32 v42, v22, v112
	v_fmac_f32_e32 v41, v23, v112
	v_fmac_f32_e32 v40, v24, v112
	v_fmac_f32_e32 v39, v25, v112
	v_fmac_f32_e32 v35, v29, v112
	v_fmac_f32_e32 v34, v30, v112
	v_fmac_f32_e32 v33, v31, v112
	v_ashrrev_i32_e32 v19, 31, v18
	v_lshlrev_b64 v[20:21], 2, v[16:17]
	global_store_dword v[84:85], v47, off offset:256 sc1
	global_store_dword v[82:83], v46, off offset:256 sc1
	global_store_dword v[78:79], v44, off offset:256 sc1
	global_store_dword v[72:73], v43, off offset:256 sc1
	global_store_dword v[74:75], v42, off offset:256 sc1
	global_store_dword v[76:77], v41, off offset:256 sc1
	global_store_dword v[80:81], v40, off offset:256 sc1
	global_store_dword v[86:87], v39, off offset:256 sc1
	global_store_dword v[90:91], v38, off offset:256 sc1
	global_store_dword v[92:93], v37, off offset:256 sc1
	global_store_dword v[94:95], v36, off offset:256 sc1
	global_store_dword v[96:97], v35, off offset:256 sc1
	global_store_dword v[98:99], v34, off offset:256 sc1
	global_store_dword v[100:101], v33, off offset:256 sc1
	global_store_dword v[104:105], v114, off offset:256 sc1
	v_lshl_add_u64 v[24:25], s[64:65], 0, v[20:21]
	v_lshl_add_u64 v[18:19], v[18:19], 1, s[8:9]
	global_load_dword v29, v[104:105], off offset:384
	v_lshl_add_u64 v[22:23], s[60:61], 0, v[20:21]
	global_load_dword v17, v[24:25], off
	global_load_dword v30, v[22:23], off
	global_load_dword v28, v[88:89], off offset:384
	global_load_dword v27, v[84:85], off offset:384
	v_fmac_f32_e32 v106, v114, v114
	global_store_short v[18:19], v26, off sc1
	v_lshl_add_u64 v[18:19], s[62:63], 0, v[20:21]
	global_load_dword v102, v[18:19], off
	v_add_u32_e32 v18, v179, v32
	v_ashrrev_i32_e32 v19, 31, v18
	v_mul_f32_e32 v20, v48, v43
	v_cvt_pk_bf16_f32 v20, v20, s0
	v_lshl_add_u64 v[18:19], v[18:19], 1, s[8:9]
	global_store_short v[18:19], v20, off sc1
	v_add_u32_e32 v18, v71, v32
	v_ashrrev_i32_e32 v19, 31, v18
	v_mul_f32_e32 v20, v48, v42
	v_cvt_pk_bf16_f32 v20, v20, s0
	v_lshl_add_u64 v[18:19], v[18:19], 1, s[8:9]
	global_store_short v[18:19], v20, off sc1
	v_add_u32_e32 v18, v180, v32
	v_ashrrev_i32_e32 v19, 31, v18
	v_mul_f32_e32 v20, v48, v41
	v_cvt_pk_bf16_f32 v20, v20, s0
	v_lshl_add_u64 v[18:19], v[18:19], 1, s[8:9]
	global_store_short v[18:19], v20, off sc1
	v_add_u32_e32 v18, v182, v32
	v_ashrrev_i32_e32 v19, 31, v18
	v_mul_f32_e32 v20, v48, v40
	v_cvt_pk_bf16_f32 v20, v20, s0
	v_lshl_add_u64 v[18:19], v[18:19], 1, s[8:9]
	global_store_short v[18:19], v20, off sc1
	v_add_u32_e32 v18, v185, v32
	v_ashrrev_i32_e32 v19, 31, v18
	v_mul_f32_e32 v20, v48, v39
	v_cvt_pk_bf16_f32 v20, v20, s0
	v_lshl_add_u64 v[18:19], v[18:19], 1, s[8:9]
	global_store_short v[18:19], v20, off sc1
	v_add_u32_e32 v18, v187, v32
	v_ashrrev_i32_e32 v19, 31, v18
	v_mul_f32_e32 v20, v48, v38
	v_cvt_pk_bf16_f32 v20, v20, s0
	v_lshl_add_u64 v[18:19], v[18:19], 1, s[8:9]
	global_store_short v[18:19], v20, off sc1
	v_add_u32_e32 v18, v189, v32
	v_ashrrev_i32_e32 v19, 31, v18
	v_mul_f32_e32 v20, v48, v37
	v_cvt_pk_bf16_f32 v20, v20, s0
	v_lshl_add_u64 v[18:19], v[18:19], 1, s[8:9]
	global_store_short v[18:19], v20, off sc1
	v_add_u32_e32 v18, v190, v32
	v_ashrrev_i32_e32 v19, 31, v18
	v_mul_f32_e32 v20, v48, v36
	v_cvt_pk_bf16_f32 v20, v20, s0
	v_lshl_add_u64 v[18:19], v[18:19], 1, s[8:9]
	global_store_short v[18:19], v20, off sc1
	v_add_u32_e32 v18, v191, v32
	v_ashrrev_i32_e32 v19, 31, v18
	v_mul_f32_e32 v20, v48, v35
	v_cvt_pk_bf16_f32 v20, v20, s0
	v_lshl_add_u64 v[18:19], v[18:19], 1, s[8:9]
	global_store_short v[18:19], v20, off sc1
	v_add_u32_e32 v18, v192, v32
	v_ashrrev_i32_e32 v19, 31, v18
	v_mul_f32_e32 v20, v48, v34
	v_cvt_pk_bf16_f32 v20, v20, s0
	v_lshl_add_u64 v[18:19], v[18:19], 1, s[8:9]
	global_store_short v[18:19], v20, off sc1
	v_add_u32_e32 v18, v193, v32
	v_ashrrev_i32_e32 v19, 31, v18
	v_mul_f32_e32 v20, v48, v33
	v_cvt_pk_bf16_f32 v20, v20, s0
	v_lshl_add_u64 v[18:19], v[18:19], 1, s[8:9]
	global_store_short v[18:19], v20, off sc1
	global_load_dword v20, v[86:87], off offset:384
	v_add_u32_e32 v18, v188, v16
	global_load_dword v26, v[82:83], off offset:384
	global_load_dword v25, v[78:79], off offset:384
	global_load_dword v24, v[72:73], off offset:384
	global_load_dword v23, v[74:75], off offset:384
	global_load_dword v21, v[80:81], off offset:384
	global_load_dword v22, v[76:77], off offset:384
	s_waitcnt vmcnt(23)
	v_add_f32_e32 v17, 1.0, v17
	s_waitcnt vmcnt(22)
	v_mul_f32_e32 v32, v30, v17
	v_ashrrev_i32_e32 v19, 31, v18
	v_lshl_add_u64 v[18:19], v[18:19], 1, s[8:9]
	v_add_u32_e32 v30, v186, v16
	s_waitcnt vmcnt(18)
	v_fmac_f32_e32 v29, v0, v102
	v_mul_f32_e32 v0, v32, v29
	v_cvt_pk_bf16_f32 v0, v0, s0
	global_store_short v[18:19], v0, off sc1
	global_load_dword v19, v[90:91], off offset:384
	v_ashrrev_i32_e32 v31, 31, v30
	global_load_dword v18, v[92:93], off offset:384
	v_fmac_f32_e32 v28, v1, v102
	v_mul_f32_e32 v0, v32, v28
	v_cvt_pk_bf16_f32 v17, v0, s0
	v_lshl_add_u64 v[0:1], v[30:31], 1, s[8:9]
	global_store_short v[0:1], v17, off sc1
	v_add_u32_e32 v0, v184, v16
	v_fmac_f32_e32 v27, v2, v102
	global_load_dword v17, v[94:95], off offset:384
	v_ashrrev_i32_e32 v1, 31, v0
	v_mul_f32_e32 v2, v32, v27
	v_cvt_pk_bf16_f32 v2, v2, s0
	v_lshl_add_u64 v[0:1], v[0:1], 1, s[8:9]
	global_store_short v[0:1], v2, off sc1
	v_add_u32_e32 v0, v183, v16
	global_load_dword v2, v[96:97], off offset:384
	v_ashrrev_i32_e32 v1, 31, v0
	v_lshl_add_u64 v[0:1], v[0:1], 1, s[8:9]
	v_add_u32_e32 v30, v181, v16
	v_ashrrev_i32_e32 v31, 31, v30
	v_lshl_add_u64 v[30:31], v[30:31], 1, s[8:9]
	v_fmac_f32_e32 v106, v29, v29
	global_store_dword v[104:105], v29, off offset:384 sc1
	global_store_dword v[88:89], v28, off offset:384 sc1
	global_store_dword v[84:85], v27, off offset:384 sc1
	s_waitcnt vmcnt(16)
	v_fmac_f32_e32 v20, v9, v102
	global_store_dword v[86:87], v20, off offset:384 sc1
	s_waitcnt vmcnt(16)
	v_fmac_f32_e32 v26, v3, v102
	v_mul_f32_e32 v3, v32, v26
	v_cvt_pk_bf16_f32 v3, v3, s0
	global_store_short v[0:1], v3, off sc1
	global_load_dword v1, v[98:99], off offset:384
	s_waitcnt vmcnt(17)
	v_fmac_f32_e32 v25, v4, v102
	v_mul_f32_e32 v0, v32, v25
	v_cvt_pk_bf16_f32 v0, v0, s0
	global_store_short v[30:31], v0, off sc1
	global_load_dword v0, v[100:101], off offset:384
	v_add_u32_e32 v30, v179, v16
	s_waitcnt vmcnt(18)
	v_fmac_f32_e32 v24, v5, v102
	v_ashrrev_i32_e32 v31, 31, v30
	v_mul_f32_e32 v3, v32, v24
	v_cvt_pk_bf16_f32 v3, v3, s0
	v_lshl_add_u64 v[4:5], v[30:31], 1, s[8:9]
	global_store_short v[4:5], v3, off sc1
	v_add_u32_e32 v4, v71, v16
	s_waitcnt vmcnt(18)
	v_fmac_f32_e32 v23, v6, v102
	v_ashrrev_i32_e32 v5, 31, v4
	v_mul_f32_e32 v3, v32, v23
	v_cvt_pk_bf16_f32 v3, v3, s0
	v_lshl_add_u64 v[4:5], v[4:5], 1, s[8:9]
	global_store_short v[4:5], v3, off sc1
	v_add_u32_e32 v4, v180, v16
	s_waitcnt vmcnt(17)
	v_fmac_f32_e32 v22, v7, v102
	v_ashrrev_i32_e32 v5, 31, v4
	v_mul_f32_e32 v3, v32, v22
	v_cvt_pk_bf16_f32 v3, v3, s0
	v_lshl_add_u64 v[4:5], v[4:5], 1, s[8:9]
	global_store_short v[4:5], v3, off sc1
	v_add_u32_e32 v4, v182, v16
	v_fmac_f32_e32 v21, v8, v102
	v_ashrrev_i32_e32 v5, 31, v4
	v_mul_f32_e32 v3, v32, v21
	v_cvt_pk_bf16_f32 v3, v3, s0
	v_lshl_add_u64 v[4:5], v[4:5], 1, s[8:9]
	global_store_short v[4:5], v3, off sc1
	v_add_u32_e32 v4, v185, v16
	v_ashrrev_i32_e32 v5, 31, v4
	v_mul_f32_e32 v3, v32, v20
	v_cvt_pk_bf16_f32 v3, v3, s0
	v_lshl_add_u64 v[4:5], v[4:5], 1, s[8:9]
	global_store_short v[4:5], v3, off sc1
	v_add_u32_e32 v4, v187, v16
	s_waitcnt vmcnt(18)
	v_fmac_f32_e32 v19, v10, v102
	v_ashrrev_i32_e32 v5, 31, v4
	v_mul_f32_e32 v3, v32, v19
	v_cvt_pk_bf16_f32 v3, v3, s0
	v_lshl_add_u64 v[4:5], v[4:5], 1, s[8:9]
	global_store_short v[4:5], v3, off sc1
	v_add_u32_e32 v4, v189, v16
	s_waitcnt vmcnt(18)
	v_fmac_f32_e32 v18, v11, v102
	v_ashrrev_i32_e32 v5, 31, v4
	v_mul_f32_e32 v3, v32, v18
	v_cvt_pk_bf16_f32 v3, v3, s0
	v_lshl_add_u64 v[4:5], v[4:5], 1, s[8:9]
	global_store_short v[4:5], v3, off sc1
	v_add_u32_e32 v4, v190, v16
	s_waitcnt vmcnt(17)
	v_fmac_f32_e32 v17, v12, v102
	v_ashrrev_i32_e32 v5, 31, v4
	v_mul_f32_e32 v3, v32, v17
	v_cvt_pk_bf16_f32 v3, v3, s0
	v_lshl_add_u64 v[4:5], v[4:5], 1, s[8:9]
	global_store_short v[4:5], v3, off sc1
	v_add_u32_e32 v4, v191, v16
	s_waitcnt vmcnt(16)
	v_fmac_f32_e32 v2, v13, v102
	v_ashrrev_i32_e32 v5, 31, v4
	v_mul_f32_e32 v3, v32, v2
	v_cvt_pk_bf16_f32 v3, v3, s0
	v_lshl_add_u64 v[4:5], v[4:5], 1, s[8:9]
	global_store_short v[4:5], v3, off sc1
	v_add_u32_e32 v4, v192, v16
	v_ashrrev_i32_e32 v5, 31, v4
	v_lshl_add_u64 v[4:5], v[4:5], 1, s[8:9]
	v_xor_b32_e32 v13, 16, v164
	v_add_u32_e32 v10, v193, v16
	v_ashrrev_i32_e32 v11, 31, v10
	v_lshl_add_u64 v[10:11], v[10:11], 1, s[8:9]
	v_ashrrev_i32_e32 v71, 31, v70
	global_store_dword v[82:83], v26, off offset:384 sc1
	global_store_dword v[78:79], v25, off offset:384 sc1
	global_store_dword v[72:73], v24, off offset:384 sc1
	global_store_dword v[74:75], v23, off offset:384 sc1
	s_waitcnt vmcnt(15)
	v_fmac_f32_e32 v1, v14, v102
	v_mul_f32_e32 v3, v32, v1
	v_cvt_pk_bf16_f32 v3, v3, s0
	global_store_short v[4:5], v3, off sc1
	v_and_b32_e32 v4, 64, v164
	v_xor_b32_e32 v3, 1, v164
	v_add_u32_e32 v7, 64, v4
	v_cmp_lt_i32_e32 vcc, v3, v7
	v_xor_b32_e32 v4, 2, v164
	s_waitcnt vmcnt(14)
	v_fmac_f32_e32 v0, v15, v102
	v_cndmask_b32_e32 v3, v164, v3, vcc
	v_lshlrev_b32_e32 v3, 2, v3
	v_cmp_lt_i32_e32 vcc, v4, v7
	v_mul_f32_e32 v12, v32, v0
	v_cvt_pk_bf16_f32 v12, v12, s0
	v_cndmask_b32_e32 v4, v164, v4, vcc
	v_lshlrev_b32_e32 v4, 2, v4
	v_add_f32_dpp v6, v106, v106 quad_perm:[1,0,3,2] row_mask:0xf bank_mask:0xf
	v_xor_b32_e32 v5, 4, v164
	v_cmp_lt_i32_e32 vcc, v5, v7
	global_store_dword v[76:77], v22, off offset:384 sc1
	global_store_dword v[80:81], v21, off offset:384 sc1
	v_cndmask_b32_e32 v5, v164, v5, vcc
	v_lshlrev_b32_e32 v5, 2, v5
	v_add_f32_dpp v8, v6, v6 quad_perm:[2,3,0,1] row_mask:0xf bank_mask:0xf
	v_xor_b32_e32 v6, 8, v164
	v_cmp_lt_i32_e32 vcc, v6, v7
	global_store_dword v[90:91], v19, off offset:384 sc1
	global_store_dword v[92:93], v18, off offset:384 sc1
	v_cndmask_b32_e32 v6, v164, v6, vcc
	v_lshlrev_b32_e32 v6, 2, v6
	v_add_f32_dpp v8, v8, v8 row_half_mirror row_mask:0xf bank_mask:0xf
	v_cmp_lt_i32_e32 vcc, v13, v7
	global_store_dword v[94:95], v17, off offset:384 sc1
	global_store_dword v[96:97], v2, off offset:384 sc1
	v_cndmask_b32_e32 v7, v164, v13, vcc
	v_lshlrev_b32_e32 v7, 2, v7
	v_add_f32_dpp v8, v8, v8 row_mirror row_mask:0xf bank_mask:0xf
	ds_bpermute_b32 v9, v7, v8
	global_store_dword v[98:99], v1, off offset:384 sc1
	global_store_dword v[100:101], v0, off offset:384 sc1
	global_store_short v[10:11], v12, off sc1
	s_and_saveexec_b64 s[60:61], s[0:1]
	s_cbranch_execz .LBB0_1052
	s_waitcnt lgkmcnt(0)
	v_add_f32_e32 v10, v8, v9
	v_lshl_add_u64 v[8:9], v[70:71], 2, s[58:59]
	global_store_dword v[8:9], v10, off sc1

.LBB0_1122:
	s_add_i32 s58, s67, 0xffffe000
	s_lshr_b32 s58, s58, 12
	s_mulk_i32 s58, 0x1800
	s_addk_i32 s58, 0x1800
	s_cmp_gt_i32 s6, 63
	s_cselect_b32 s62, s58, 0
	s_add_i32 s6, s62, 0x4800
	s_lshl_b64 s[58:59], s[6:7], 2
	s_add_u32 s6, s14, s58
	s_addc_u32 s58, s15, s59
	s_add_u32 s60, s6, 0x5ba5000
	s_addc_u32 s61, s58, 0
	s_add_i32 s6, s62, 0x9000
	s_lshl_b64 s[58:59], s[6:7], 2
	v_mov_b32_e32 v70, s66
	s_add_u32 s6, s14, s58
	ds_read_b64 v[70:71], v70
	s_addc_u32 s69, s15, s59
	s_lshl_b32 s58, s64, 14
	s_add_i32 s58, s58, 0x80000
	s_ashr_i32 s59, s58, 31
	s_lshl_b64 s[58:59], s[58:59], 2
	s_add_u32 s58, s10, s58
	s_waitcnt lgkmcnt(0)
	v_readfirstlane_b32 s63, v70
	s_addc_u32 s59, s11, s59
	v_or_b32_e32 v102, s68, v138
	v_add_u32_e32 v70, s67, v139
	v_readfirstlane_b32 s65, v71
	s_add_u32 s62, s63, 0x2000
	v_ashrrev_i32_e32 v103, 31, v102
	v_lshlrev_b32_e32 v191, 10, v70
	s_addc_u32 s63, s65, 0
	v_lshlrev_b64 v[72:73], 2, v[102:103]
	v_or_b32_e32 v187, 0x400, v191
	v_or_b32_e32 v186, 0x4400, v191
	v_or_b32_e32 v189, 0x4c00, v191
	v_or_b32_e32 v194, 0x6c00, v191
	s_add_u32 s64, s6, 0x5ba1000
	v_lshl_add_u64 v[74:75], s[60:61], 0, v[72:73]
	v_add_u32_e32 v130, v191, v102
	v_add_u32_e32 v132, v187, v102
	v_or_b32_e32 v185, 0x800, v191
	v_or_b32_e32 v184, 0xc00, v191
	v_or_b32_e32 v182, 0x2000, v191
	v_or_b32_e32 v180, 0x2400, v191
	v_or_b32_e32 v71, 0x2800, v191
	v_or_b32_e32 v181, 0x2c00, v191
	v_or_b32_e32 v183, 0x4000, v191
	v_add_u32_e32 v112, v186, v102
	v_or_b32_e32 v188, 0x4800, v191
	v_add_u32_e32 v116, v189, v102
	v_or_b32_e32 v190, 0x6000, v191
	v_or_b32_e32 v192, 0x6400, v191
	v_or_b32_e32 v193, 0x6800, v191
	v_add_u32_e32 v128, v194, v102
	s_addc_u32 s65, s69, 0
	global_load_dword v195, v[74:75], off
	global_load_dword v205, v[74:75], off offset:128
	global_load_dword v224, v[74:75], off offset:256
	v_lshl_add_u64 v[74:75], s[62:63], 0, v[72:73]
	v_ashrrev_i32_e32 v133, 31, v132
	v_add_u32_e32 v134, v185, v102
	v_add_u32_e32 v136, v184, v102
	v_add_u32_e32 v126, v182, v102
	v_add_u32_e32 v118, v180, v102
	v_add_u32_e32 v110, v71, v102
	v_add_u32_e32 v106, v181, v102
	v_add_u32_e32 v108, v183, v102
	v_ashrrev_i32_e32 v113, 31, v112
	v_add_u32_e32 v114, v188, v102
	v_ashrrev_i32_e32 v117, 31, v116
	v_add_u32_e32 v120, v190, v102
	v_add_u32_e32 v122, v192, v102
	v_add_u32_e32 v124, v193, v102
	v_ashrrev_i32_e32 v129, 31, v128
	v_ashrrev_i32_e32 v131, 31, v130
	v_lshl_add_u64 v[72:73], s[64:65], 0, v[72:73]
	global_load_dword v196, v[74:75], off
	global_load_dword v204, v[74:75], off offset:128
	global_load_dword v223, v[74:75], off offset:256
	global_load_dword v197, v[72:73], off
	global_load_dword v203, v[72:73], off offset:128
	global_load_dword v222, v[72:73], off offset:256
	v_lshl_add_u64 v[88:89], v[132:133], 2, s[12:13]
	v_ashrrev_i32_e32 v135, 31, v134
	v_ashrrev_i32_e32 v137, 31, v136
	v_ashrrev_i32_e32 v127, 31, v126
	v_ashrrev_i32_e32 v119, 31, v118
	v_ashrrev_i32_e32 v111, 31, v110
	v_ashrrev_i32_e32 v107, 31, v106
	v_ashrrev_i32_e32 v109, 31, v108
	v_lshl_add_u64 v[86:87], v[112:113], 2, s[12:13]
	v_ashrrev_i32_e32 v115, 31, v114
	v_lshl_add_u64 v[92:93], v[116:117], 2, s[12:13]
	v_ashrrev_i32_e32 v121, 31, v120
	v_ashrrev_i32_e32 v123, 31, v122
	v_ashrrev_i32_e32 v125, 31, v124
	v_lshl_add_u64 v[100:101], v[128:129], 2, s[12:13]
	v_lshl_add_u64 v[104:105], v[130:131], 2, s[12:13]
	v_lshl_add_u64 v[84:85], v[134:135], 2, s[12:13]
	v_lshl_add_u64 v[82:83], v[136:137], 2, s[12:13]
	v_lshl_add_u64 v[78:79], v[126:127], 2, s[12:13]
	v_lshl_add_u64 v[72:73], v[118:119], 2, s[12:13]
	v_lshl_add_u64 v[74:75], v[110:111], 2, s[12:13]
	v_lshl_add_u64 v[76:77], v[106:107], 2, s[12:13]
	v_lshl_add_u64 v[80:81], v[108:109], 2, s[12:13]
	global_load_dword v179, v[88:89], off
	global_load_dword v178, v[84:85], off
	global_load_dword v177, v[82:83], off
	global_load_dword v176, v[78:79], off
	global_load_dword v175, v[72:73], off
	global_load_dword v174, v[74:75], off
	global_load_dword v173, v[76:77], off
	global_load_dword v172, v[80:81], off
	v_lshl_add_u64 v[90:91], v[114:115], 2, s[12:13]
	global_load_dword v171, v[86:87], off
	global_load_dword v169, v[90:91], off
	v_lshl_add_u64 v[94:95], v[120:121], 2, s[12:13]
	v_lshl_add_u64 v[96:97], v[122:123], 2, s[12:13]
	v_lshl_add_u64 v[98:99], v[124:125], 2, s[12:13]
	global_load_dword v170, v[92:93], off
	global_load_dword v168, v[94:95], off
	global_load_dword v167, v[96:97], off
	global_load_dword v166, v[98:99], off
	global_load_dword v103, v[100:101], off
	global_load_dword v198, v[104:105], off
	v_lshl_add_u64 v[110:111], v[110:111], 1, s[8:9]
	v_lshl_add_u64 v[106:107], v[106:107], 1, s[8:9]
	global_load_dword v202, v[104:105], off offset:128
	global_load_dword v206, v[84:85], off offset:128
	global_load_dword v207, v[78:79], off offset:128
	global_load_dword v208, v[72:73], off offset:128
	global_load_dword v209, v[74:75], off offset:128
	global_load_dword v210, v[80:81], off offset:128
	global_load_dword v211, v[76:77], off offset:128
	global_load_dword v212, v[86:87], off offset:128
	global_load_dword v213, v[82:83], off offset:128
	global_load_dword v214, v[90:91], off offset:128
	global_load_dword v215, v[92:93], off offset:128
	global_load_dword v216, v[94:95], off offset:128
	global_load_dword v217, v[96:97], off offset:128
	global_load_dword v218, v[98:99], off offset:128
	global_load_dword v219, v[100:101], off offset:128
	global_load_dword v220, v[88:89], off offset:128
	global_load_dword v221, v[88:89], off offset:256
	global_load_dword v225, v[90:91], off offset:256
	global_load_dword v226, v[92:93], off offset:256
	global_load_dword v227, v[94:95], off offset:256
	global_load_dword v229, v[104:105], off offset:256
	global_load_dword v230, v[84:85], off offset:256
	global_load_dword v231, v[86:87], off offset:256
	global_load_dword v232, v[82:83], off offset:256
	global_load_dword v233, v[78:79], off offset:256
	global_load_dword v234, v[72:73], off offset:256
	global_load_dword v235, v[74:75], off offset:256
	global_load_dword v236, v[80:81], off offset:256
	global_load_dword v237, v[76:77], off offset:256
	global_load_dword v238, v[96:97], off offset:256
	global_load_dword v239, v[98:99], off offset:256
	global_load_dword v240, v[100:101], off offset:256
	s_waitcnt vmcnt(0)
	v_add_f32_e32 v197, 1.0, v197
	v_mul_f32_e32 v196, v196, v197
	v_fmac_f32_e32 v179, v49, v195
	v_fmac_f32_e32 v178, v50, v195
	v_fmac_f32_e32 v177, v51, v195
	v_fmac_f32_e32 v176, v52, v195
	v_fmac_f32_e32 v175, v53, v195
	v_fmac_f32_e32 v174, v54, v195
	v_fmac_f32_e32 v173, v55, v195
	v_fmac_f32_e32 v172, v56, v195
	v_fmac_f32_e32 v171, v57, v195
	v_fmac_f32_e32 v169, v58, v195
	v_fmac_f32_e32 v170, v59, v195
	v_fmac_f32_e32 v168, v60, v195
	v_fmac_f32_e32 v167, v61, v195
	v_fmac_f32_e32 v166, v62, v195
	v_fmac_f32_e32 v103, v63, v195
	v_fmac_f32_e32 v198, v48, v195
	v_mul_f32_e32 v48, v196, v198
	v_cvt_pk_bf16_f32 v58, v48, s0
	v_or_b32_e32 v48, 32, v102
	v_ashrrev_i32_e32 v49, 31, v48
	v_lshlrev_b64 v[52:53], 2, v[48:49]
	global_store_dword v[88:89], v179, off sc1
	global_store_dword v[84:85], v178, off sc1
	global_store_dword v[82:83], v177, off sc1
	global_store_dword v[78:79], v176, off sc1
	global_store_dword v[72:73], v175, off sc1
	global_store_dword v[74:75], v174, off sc1
	global_store_dword v[76:77], v173, off sc1
	global_store_dword v[80:81], v172, off sc1
	global_store_dword v[86:87], v171, off sc1
	global_store_dword v[90:91], v169, off sc1
	global_store_dword v[92:93], v170, off sc1
	global_store_dword v[94:95], v168, off sc1
	global_store_dword v[96:97], v167, off sc1
	global_store_dword v[98:99], v166, off sc1
	global_store_dword v[100:101], v103, off sc1
	global_store_dword v[104:105], v198, off sc1
	v_lshl_add_u64 v[50:51], v[130:131], 1, s[8:9]
	v_lshl_add_u64 v[56:57], s[64:65], 0, v[52:53]
	v_mov_b32_e32 v197, v202
	v_lshl_add_u64 v[54:55], s[62:63], 0, v[52:53]
	v_mov_b32_e32 v130, v203
	v_mov_b32_e32 v131, v204
	v_mul_f32_e32 v49, v196, v179
	global_store_short v[50:51], v58, off sc1
	v_lshl_add_u64 v[50:51], s[60:61], 0, v[52:53]
	v_mov_b32_e32 v195, v205
	v_lshl_add_u64 v[50:51], v[132:133], 1, s[8:9]
	v_cvt_pk_bf16_f32 v49, v49, s0
	global_store_short v[50:51], v49, off sc1
	v_mul_f32_e32 v49, v196, v178
	v_lshl_add_u64 v[50:51], v[134:135], 1, s[8:9]
	v_cvt_pk_bf16_f32 v49, v49, s0
	global_store_short v[50:51], v49, off sc1
	v_mul_f32_e32 v49, v196, v177
	v_lshl_add_u64 v[50:51], v[136:137], 1, s[8:9]
	v_cvt_pk_bf16_f32 v49, v49, s0
	global_store_short v[50:51], v49, off sc1
	v_mul_f32_e32 v49, v196, v176
	v_lshl_add_u64 v[50:51], v[126:127], 1, s[8:9]
	v_cvt_pk_bf16_f32 v49, v49, s0
	global_store_short v[50:51], v49, off sc1
	v_mul_f32_e32 v49, v196, v175
	v_lshl_add_u64 v[50:51], v[118:119], 1, s[8:9]
	v_cvt_pk_bf16_f32 v49, v49, s0
	v_mov_b32_e32 v62, v206
	v_mov_b32_e32 v60, v207
	v_mov_b32_e32 v59, v208
	v_mov_b32_e32 v58, v209
	v_mov_b32_e32 v56, v210
	v_mov_b32_e32 v57, v211
	v_mov_b32_e32 v55, v212
	v_mov_b32_e32 v61, v213
	v_mov_b32_e32 v54, v214
	v_mov_b32_e32 v53, v215
	v_mov_b32_e32 v52, v216
	v_mul_f32_e32 v63, v196, v174
	global_store_short v[50:51], v49, off sc1
	v_mov_b32_e32 v51, v217
	v_cvt_pk_bf16_f32 v63, v63, s0
	v_mov_b32_e32 v50, v218
	v_mov_b32_e32 v49, v219
	v_fmac_f32_e32 v197, v32, v195
	global_store_short v[110:111], v63, off sc1
	v_mov_b32_e32 v63, v220
	v_mul_f32_e32 v110, v196, v173
	v_cvt_pk_bf16_f32 v110, v110, s0
	global_store_short v[106:107], v110, off sc1
	v_lshl_add_u64 v[106:107], v[108:109], 1, s[8:9]
	v_mul_f32_e32 v108, v196, v172
	v_cvt_pk_bf16_f32 v108, v108, s0
	global_store_short v[106:107], v108, off sc1
	v_mul_f32_e32 v108, v196, v171
	v_lshl_add_u64 v[106:107], v[112:113], 1, s[8:9]
	v_cvt_pk_bf16_f32 v108, v108, s0
	global_store_short v[106:107], v108, off sc1
	v_mul_f32_e32 v108, v196, v169
	v_lshl_add_u64 v[106:107], v[114:115], 1, s[8:9]
	v_cvt_pk_bf16_f32 v108, v108, s0
	global_store_short v[106:107], v108, off sc1
	v_mul_f32_e32 v108, v196, v170
	v_lshl_add_u64 v[106:107], v[116:117], 1, s[8:9]
	v_cvt_pk_bf16_f32 v108, v108, s0
	global_store_short v[106:107], v108, off sc1
	v_mul_f32_e32 v108, v196, v168
	v_lshl_add_u64 v[106:107], v[120:121], 1, s[8:9]
	v_cvt_pk_bf16_f32 v108, v108, s0
	global_store_short v[106:107], v108, off sc1
	v_mul_f32_e32 v108, v196, v167
	v_lshl_add_u64 v[106:107], v[122:123], 1, s[8:9]
	v_cvt_pk_bf16_f32 v108, v108, s0
	global_store_short v[106:107], v108, off sc1
	v_mul_f32_e32 v108, v196, v166
	v_lshl_add_u64 v[106:107], v[124:125], 1, s[8:9]
	v_cvt_pk_bf16_f32 v108, v108, s0
	global_store_short v[106:107], v108, off sc1
	v_mul_f32_e32 v108, v196, v103
	v_lshl_add_u64 v[106:107], v[128:129], 1, s[8:9]
	v_cvt_pk_bf16_f32 v108, v108, s0
	global_store_short v[106:107], v108, off sc1
	v_add_f32_e32 v106, 1.0, v130
	v_mul_f32_e32 v107, v131, v106
	v_add_u32_e32 v108, v191, v48
	v_ashrrev_i32_e32 v109, 31, v108
	v_mul_f32_e32 v32, v107, v197
	v_fmac_f32_e32 v62, v34, v195
	v_fmac_f32_e32 v61, v35, v195
	v_fmac_f32_e32 v60, v36, v195
	v_fmac_f32_e32 v59, v37, v195
	v_fmac_f32_e32 v58, v38, v195
	v_fmac_f32_e32 v57, v39, v195
	v_fmac_f32_e32 v56, v40, v195
	v_fmac_f32_e32 v55, v41, v195
	v_fmac_f32_e32 v54, v42, v195
	v_fmac_f32_e32 v53, v43, v195
	v_fmac_f32_e32 v52, v44, v195
	v_fmac_f32_e32 v51, v45, v195
	v_fmac_f32_e32 v50, v46, v195
	v_fmac_f32_e32 v49, v47, v195
	global_store_dword v[104:105], v197, off offset:128 sc1
	v_lshl_add_u64 v[108:109], v[108:109], 1, s[8:9]
	v_cvt_pk_bf16_f32 v32, v32, s0
	global_store_dword v[84:85], v62, off offset:128 sc1
	global_store_dword v[82:83], v61, off offset:128 sc1
	global_store_dword v[78:79], v60, off offset:128 sc1
	global_store_dword v[72:73], v59, off offset:128 sc1
	global_store_dword v[74:75], v58, off offset:128 sc1
	global_store_dword v[76:77], v57, off offset:128 sc1
	global_store_dword v[80:81], v56, off offset:128 sc1
	global_store_dword v[86:87], v55, off offset:128 sc1
	global_store_dword v[90:91], v54, off offset:128 sc1
	global_store_dword v[92:93], v53, off offset:128 sc1
	global_store_dword v[94:95], v52, off offset:128 sc1
	global_store_dword v[96:97], v51, off offset:128 sc1
	global_store_dword v[98:99], v50, off offset:128 sc1
	global_store_dword v[100:101], v49, off offset:128 sc1
	global_store_short v[108:109], v32, off sc1
	v_add_u32_e32 v108, v187, v48
	v_mov_b32_e32 v45, v221
	v_ashrrev_i32_e32 v109, 31, v108
	v_mul_f32_e32 v113, v107, v56
	v_cvt_pk_bf16_f32 v113, v113, s0
	v_mul_f32_e32 v106, v197, v197
	v_fmac_f32_e32 v106, v198, v198
	v_fmac_f32_e32 v63, v33, v195
	v_mul_f32_e32 v34, v107, v63
	v_lshl_add_u64 v[32:33], v[108:109], 1, s[8:9]
	v_cvt_pk_bf16_f32 v34, v34, s0
	global_store_short v[32:33], v34, off sc1
	v_add_u32_e32 v32, v185, v48
	v_ashrrev_i32_e32 v33, 31, v32
	v_mul_f32_e32 v34, v107, v62
	v_lshl_add_u64 v[32:33], v[32:33], 1, s[8:9]
	v_cvt_pk_bf16_f32 v34, v34, s0
	global_store_short v[32:33], v34, off sc1
	v_add_u32_e32 v32, v184, v48
	v_ashrrev_i32_e32 v33, 31, v32
	v_mul_f32_e32 v34, v107, v61
	v_lshl_add_u64 v[32:33], v[32:33], 1, s[8:9]
	v_cvt_pk_bf16_f32 v34, v34, s0
	global_store_short v[32:33], v34, off sc1
	v_add_u32_e32 v32, v182, v48
	v_ashrrev_i32_e32 v33, 31, v32
	v_mul_f32_e32 v34, v107, v60
	v_lshl_add_u64 v[32:33], v[32:33], 1, s[8:9]
	v_cvt_pk_bf16_f32 v34, v34, s0
	global_store_short v[32:33], v34, off sc1
	v_add_u32_e32 v32, v180, v48
	v_ashrrev_i32_e32 v33, 31, v32
	v_lshl_add_u64 v[34:35], v[32:33], 1, s[8:9]
	v_mul_f32_e32 v32, v107, v59
	v_cvt_pk_bf16_f32 v42, v32, s0
	v_or_b32_e32 v32, 64, v102
	v_ashrrev_i32_e32 v33, 31, v32
	v_lshlrev_b64 v[36:37], 2, v[32:33]
	global_store_dword v[88:89], v63, off offset:128 sc1
	v_lshl_add_u64 v[40:41], s[64:65], 0, v[36:37]
	v_lshl_add_u64 v[38:39], s[62:63], 0, v[36:37]
	v_mov_b32_e32 v110, v222
	v_mov_b32_e32 v111, v223
	v_mul_f32_e32 v33, v107, v58
	global_store_short v[34:35], v42, off sc1
	v_lshl_add_u64 v[34:35], s[60:61], 0, v[36:37]
	v_mov_b32_e32 v112, v224
	v_add_u32_e32 v34, v71, v48
	v_ashrrev_i32_e32 v35, 31, v34
	v_lshl_add_u64 v[34:35], v[34:35], 1, s[8:9]
	v_cvt_pk_bf16_f32 v33, v33, s0
	global_store_short v[34:35], v33, off sc1
	v_add_u32_e32 v34, v181, v48
	v_ashrrev_i32_e32 v35, 31, v34
	v_mul_f32_e32 v33, v107, v57
	v_lshl_add_u64 v[34:35], v[34:35], 1, s[8:9]
	v_cvt_pk_bf16_f32 v33, v33, s0
	v_mov_b32_e32 v38, v225
	v_mov_b32_e32 v37, v226
	v_mov_b32_e32 v36, v227
	v_mov_b32_e32 v114, v229
	v_mov_b32_e32 v47, v230
	v_mov_b32_e32 v39, v231
	v_mov_b32_e32 v46, v232
	v_mov_b32_e32 v44, v233
	v_mov_b32_e32 v43, v234
	v_mov_b32_e32 v42, v235
	v_mov_b32_e32 v40, v236
	v_mov_b32_e32 v41, v237
	v_add_u32_e32 v108, v183, v48
	global_store_short v[34:35], v33, off sc1
	v_mov_b32_e32 v35, v238
	v_ashrrev_i32_e32 v109, 31, v108
	v_mov_b32_e32 v34, v239
	v_mov_b32_e32 v33, v240
	v_lshl_add_u64 v[108:109], v[108:109], 1, s[8:9]
	global_store_short v[108:109], v113, off sc1
	v_add_u32_e32 v108, v186, v48
	v_ashrrev_i32_e32 v109, 31, v108
	v_mul_f32_e32 v113, v107, v55
	v_lshl_add_u64 v[108:109], v[108:109], 1, s[8:9]
	v_cvt_pk_bf16_f32 v113, v113, s0
	global_store_short v[108:109], v113, off sc1
	v_add_u32_e32 v108, v188, v48
	v_ashrrev_i32_e32 v109, 31, v108
	v_mul_f32_e32 v113, v107, v54
	v_lshl_add_u64 v[108:109], v[108:109], 1, s[8:9]
	v_cvt_pk_bf16_f32 v113, v113, s0
	global_store_short v[108:109], v113, off sc1
	v_add_u32_e32 v108, v189, v48
	v_ashrrev_i32_e32 v109, 31, v108
	v_mul_f32_e32 v113, v107, v53
	v_lshl_add_u64 v[108:109], v[108:109], 1, s[8:9]
	v_cvt_pk_bf16_f32 v113, v113, s0
	global_store_short v[108:109], v113, off sc1
	v_add_u32_e32 v108, v190, v48
	v_ashrrev_i32_e32 v109, 31, v108
	v_mul_f32_e32 v113, v107, v52
	v_lshl_add_u64 v[108:109], v[108:109], 1, s[8:9]
	v_cvt_pk_bf16_f32 v113, v113, s0
	global_store_short v[108:109], v113, off sc1
	v_add_u32_e32 v108, v192, v48
	v_ashrrev_i32_e32 v109, 31, v108
	v_mul_f32_e32 v113, v107, v51
	v_lshl_add_u64 v[108:109], v[108:109], 1, s[8:9]
	v_cvt_pk_bf16_f32 v113, v113, s0
	global_store_short v[108:109], v113, off sc1
	v_add_u32_e32 v108, v193, v48
	v_ashrrev_i32_e32 v109, 31, v108
	v_mul_f32_e32 v113, v107, v50
	v_lshl_add_u64 v[108:109], v[108:109], 1, s[8:9]
	v_cvt_pk_bf16_f32 v113, v113, s0
	global_store_short v[108:109], v113, off sc1
	v_add_u32_e32 v108, v194, v48
	v_ashrrev_i32_e32 v109, 31, v108
	v_mul_f32_e32 v48, v107, v49
	v_lshl_add_u64 v[108:109], v[108:109], 1, s[8:9]
	v_cvt_pk_bf16_f32 v48, v48, s0
	global_store_short v[108:109], v48, off sc1
	v_add_u32_e32 v108, v191, v32
	v_ashrrev_i32_e32 v109, 31, v108
	v_add_f32_e32 v48, 1.0, v110
	v_mul_f32_e32 v48, v111, v48
	v_fmac_f32_e32 v45, v17, v112
	global_store_dword v[88:89], v45, off offset:256 sc1
	v_fmac_f32_e32 v38, v26, v112
	v_fmac_f32_e32 v37, v27, v112
	v_fmac_f32_e32 v36, v28, v112
	v_fmac_f32_e32 v114, v16, v112
	v_fmac_f32_e32 v47, v18, v112
	v_mul_f32_e32 v18, v48, v114
	v_lshl_add_u64 v[16:17], v[108:109], 1, s[8:9]
	v_cvt_pk_bf16_f32 v18, v18, s0
	global_store_short v[16:17], v18, off sc1
	v_add_u32_e32 v16, v187, v32
	v_ashrrev_i32_e32 v17, 31, v16
	v_mul_f32_e32 v18, v48, v45
	v_lshl_add_u64 v[16:17], v[16:17], 1, s[8:9]
	v_cvt_pk_bf16_f32 v18, v18, s0
	global_store_short v[16:17], v18, off sc1
	v_add_u32_e32 v16, v185, v32
	v_ashrrev_i32_e32 v17, 31, v16
	v_mul_f32_e32 v18, v48, v47
	v_lshl_add_u64 v[16:17], v[16:17], 1, s[8:9]
	v_cvt_pk_bf16_f32 v18, v18, s0
	v_fmac_f32_e32 v46, v19, v112
	global_store_short v[16:17], v18, off sc1
	v_add_u32_e32 v16, v184, v32
	v_ashrrev_i32_e32 v17, 31, v16
	v_mul_f32_e32 v18, v48, v46
	v_lshl_add_u64 v[16:17], v[16:17], 1, s[8:9]
	v_cvt_pk_bf16_f32 v18, v18, s0
	global_store_short v[16:17], v18, off sc1
	v_add_u32_e32 v16, v182, v32
	v_ashrrev_i32_e32 v17, 31, v16
	v_lshl_add_u64 v[18:19], v[16:17], 1, s[8:9]
	v_or_b32_e32 v16, 0x60, v102
	v_ashrrev_i32_e32 v17, 31, v16
	v_fmac_f32_e32 v44, v20, v112
	v_fmac_f32_e32 v43, v21, v112
	v_fmac_f32_e32 v42, v22, v112
	v_fmac_f32_e32 v41, v23, v112
	v_fmac_f32_e32 v40, v24, v112
	v_fmac_f32_e32 v39, v25, v112
	v_fmac_f32_e32 v35, v29, v112
	v_fmac_f32_e32 v34, v30, v112
	v_fmac_f32_e32 v33, v31, v112
	v_lshlrev_b64 v[20:21], 2, v[16:17]
	global_store_dword v[84:85], v47, off offset:256 sc1
	global_store_dword v[82:83], v46, off offset:256 sc1
	global_store_dword v[78:79], v44, off offset:256 sc1
	global_store_dword v[72:73], v43, off offset:256 sc1
	global_store_dword v[74:75], v42, off offset:256 sc1
	global_store_dword v[76:77], v41, off offset:256 sc1
	global_store_dword v[80:81], v40, off offset:256 sc1
	global_store_dword v[86:87], v39, off offset:256 sc1
	global_store_dword v[90:91], v38, off offset:256 sc1
	global_store_dword v[92:93], v37, off offset:256 sc1
	global_store_dword v[94:95], v36, off offset:256 sc1
	global_store_dword v[96:97], v35, off offset:256 sc1
	global_store_dword v[98:99], v34, off offset:256 sc1
	global_store_dword v[100:101], v33, off offset:256 sc1
	global_store_dword v[104:105], v114, off offset:256 sc1
	v_mul_f32_e32 v26, v48, v44
	v_lshl_add_u64 v[22:23], s[62:63], 0, v[20:21]
	v_lshl_add_u64 v[24:25], s[64:65], 0, v[20:21]
	global_load_dword v29, v[104:105], off offset:384
	global_load_dword v17, v[24:25], off
	global_load_dword v30, v[22:23], off
	v_cvt_pk_bf16_f32 v22, v26, s0
	global_store_short v[18:19], v22, off sc1
	v_lshl_add_u64 v[18:19], s[60:61], 0, v[20:21]
	global_load_dword v102, v[18:19], off
	v_add_u32_e32 v18, v180, v32
	v_ashrrev_i32_e32 v19, 31, v18
	v_mul_f32_e32 v20, v48, v43
	v_lshl_add_u64 v[18:19], v[18:19], 1, s[8:9]
	v_cvt_pk_bf16_f32 v20, v20, s0
	global_store_short v[18:19], v20, off sc1
	v_add_u32_e32 v18, v71, v32
	v_ashrrev_i32_e32 v19, 31, v18
	v_mul_f32_e32 v20, v48, v42
	v_lshl_add_u64 v[18:19], v[18:19], 1, s[8:9]
	v_cvt_pk_bf16_f32 v20, v20, s0
	global_store_short v[18:19], v20, off sc1
	v_add_u32_e32 v18, v181, v32
	v_ashrrev_i32_e32 v19, 31, v18
	v_mul_f32_e32 v20, v48, v41
	v_lshl_add_u64 v[18:19], v[18:19], 1, s[8:9]
	v_cvt_pk_bf16_f32 v20, v20, s0
	global_store_short v[18:19], v20, off sc1
	v_add_u32_e32 v18, v183, v32
	v_ashrrev_i32_e32 v19, 31, v18
	v_mul_f32_e32 v20, v48, v40
	v_lshl_add_u64 v[18:19], v[18:19], 1, s[8:9]
	v_cvt_pk_bf16_f32 v20, v20, s0
	global_store_short v[18:19], v20, off sc1
	v_add_u32_e32 v18, v186, v32
	v_ashrrev_i32_e32 v19, 31, v18
	v_mul_f32_e32 v20, v48, v39
	v_lshl_add_u64 v[18:19], v[18:19], 1, s[8:9]
	v_cvt_pk_bf16_f32 v20, v20, s0
	global_store_short v[18:19], v20, off sc1
	v_add_u32_e32 v18, v188, v32
	v_ashrrev_i32_e32 v19, 31, v18
	v_mul_f32_e32 v20, v48, v38
	v_lshl_add_u64 v[18:19], v[18:19], 1, s[8:9]
	v_cvt_pk_bf16_f32 v20, v20, s0
	global_store_short v[18:19], v20, off sc1
	v_add_u32_e32 v18, v189, v32
	v_ashrrev_i32_e32 v19, 31, v18
	v_mul_f32_e32 v20, v48, v37
	v_lshl_add_u64 v[18:19], v[18:19], 1, s[8:9]
	v_cvt_pk_bf16_f32 v20, v20, s0
	global_store_short v[18:19], v20, off sc1
	v_add_u32_e32 v18, v190, v32
	v_ashrrev_i32_e32 v19, 31, v18
	v_mul_f32_e32 v20, v48, v36
	v_lshl_add_u64 v[18:19], v[18:19], 1, s[8:9]
	v_cvt_pk_bf16_f32 v20, v20, s0
	global_store_short v[18:19], v20, off sc1
	v_add_u32_e32 v18, v192, v32
	v_ashrrev_i32_e32 v19, 31, v18
	v_mul_f32_e32 v20, v48, v35
	v_lshl_add_u64 v[18:19], v[18:19], 1, s[8:9]
	v_cvt_pk_bf16_f32 v20, v20, s0
	global_load_dword v28, v[88:89], off offset:384
	global_load_dword v27, v[84:85], off offset:384
	global_load_dword v25, v[78:79], off offset:384
	global_load_dword v24, v[72:73], off offset:384
	global_load_dword v23, v[74:75], off offset:384
	global_load_dword v21, v[80:81], off offset:384
	global_load_dword v22, v[76:77], off offset:384
	v_fmac_f32_e32 v106, v114, v114
	global_store_short v[18:19], v20, off sc1
	v_add_u32_e32 v18, v193, v32
	v_ashrrev_i32_e32 v19, 31, v18
	v_mul_f32_e32 v20, v48, v34
	v_lshl_add_u64 v[18:19], v[18:19], 1, s[8:9]
	v_cvt_pk_bf16_f32 v20, v20, s0
	global_store_short v[18:19], v20, off sc1
	v_add_u32_e32 v18, v194, v32
	v_ashrrev_i32_e32 v19, 31, v18
	v_mul_f32_e32 v20, v48, v33
	v_lshl_add_u64 v[18:19], v[18:19], 1, s[8:9]
	v_cvt_pk_bf16_f32 v20, v20, s0
	global_store_short v[18:19], v20, off sc1
	global_load_dword v20, v[86:87], off offset:384
	s_waitcnt vmcnt(22)
	v_add_f32_e32 v17, 1.0, v17
	global_load_dword v26, v[82:83], off offset:384
	s_waitcnt vmcnt(22)
	v_mul_f32_e32 v32, v30, v17
	v_add_u32_e32 v18, v191, v16
	s_waitcnt vmcnt(20)
	v_fmac_f32_e32 v29, v0, v102
	v_ashrrev_i32_e32 v19, 31, v18
	v_mul_f32_e32 v0, v32, v29
	v_lshl_add_u64 v[18:19], v[18:19], 1, s[8:9]
	v_cvt_pk_bf16_f32 v0, v0, s0
	global_store_short v[18:19], v0, off sc1
	global_load_dword v19, v[90:91], off offset:384
	v_add_u32_e32 v30, v187, v16
	global_load_dword v18, v[92:93], off offset:384
	v_ashrrev_i32_e32 v31, 31, v30
	v_fmac_f32_e32 v106, v29, v29
	global_store_dword v[104:105], v29, off offset:384 sc1
	s_waitcnt vmcnt(15)
	v_fmac_f32_e32 v28, v1, v102
	v_mul_f32_e32 v17, v32, v28
	v_lshl_add_u64 v[0:1], v[30:31], 1, s[8:9]
	v_cvt_pk_bf16_f32 v17, v17, s0
	global_store_short v[0:1], v17, off sc1
	v_add_u32_e32 v0, v185, v16
	s_waitcnt vmcnt(15)
	v_fmac_f32_e32 v27, v2, v102
	global_load_dword v17, v[94:95], off offset:384
	v_ashrrev_i32_e32 v1, 31, v0
	v_mul_f32_e32 v2, v32, v27
	v_lshl_add_u64 v[0:1], v[0:1], 1, s[8:9]
	v_cvt_pk_bf16_f32 v2, v2, s0
	global_store_short v[0:1], v2, off sc1
	v_add_u32_e32 v0, v184, v16
	global_load_dword v2, v[96:97], off offset:384
	v_ashrrev_i32_e32 v1, 31, v0
	v_lshl_add_u64 v[0:1], v[0:1], 1, s[8:9]
	v_add_u32_e32 v30, v182, v16
	s_waitcnt vmcnt(17)
	v_fmac_f32_e32 v25, v4, v102
	v_ashrrev_i32_e32 v31, 31, v30
	v_lshl_add_u64 v[30:31], v[30:31], 1, s[8:9]
	s_waitcnt vmcnt(16)
	v_fmac_f32_e32 v24, v5, v102
	s_waitcnt vmcnt(15)
	v_fmac_f32_e32 v23, v6, v102
	s_waitcnt vmcnt(8)
	v_fmac_f32_e32 v26, v3, v102
	v_mul_f32_e32 v3, v32, v26
	v_cvt_pk_bf16_f32 v3, v3, s0
	global_store_short v[0:1], v3, off sc1
	global_load_dword v1, v[98:99], off offset:384
	v_mul_f32_e32 v0, v32, v25
	v_cvt_pk_bf16_f32 v0, v0, s0
	global_store_short v[30:31], v0, off sc1
	global_load_dword v0, v[100:101], off offset:384
	v_add_u32_e32 v30, v180, v16
	v_ashrrev_i32_e32 v31, 31, v30
	v_mul_f32_e32 v3, v32, v24
	v_lshl_add_u64 v[4:5], v[30:31], 1, s[8:9]
	v_cvt_pk_bf16_f32 v3, v3, s0
	global_store_short v[4:5], v3, off sc1
	v_add_u32_e32 v4, v71, v16
	v_ashrrev_i32_e32 v5, 31, v4
	v_mul_f32_e32 v3, v32, v23
	v_lshl_add_u64 v[4:5], v[4:5], 1, s[8:9]
	v_cvt_pk_bf16_f32 v3, v3, s0
	global_store_short v[4:5], v3, off sc1
	v_add_u32_e32 v4, v181, v16
	v_fmac_f32_e32 v22, v7, v102
	v_ashrrev_i32_e32 v5, 31, v4
	v_mul_f32_e32 v3, v32, v22
	v_lshl_add_u64 v[4:5], v[4:5], 1, s[8:9]
	v_cvt_pk_bf16_f32 v3, v3, s0
	global_store_short v[4:5], v3, off sc1
	v_add_u32_e32 v4, v183, v16
	v_fmac_f32_e32 v21, v8, v102
	v_ashrrev_i32_e32 v5, 31, v4
	v_mul_f32_e32 v3, v32, v21
	v_lshl_add_u64 v[4:5], v[4:5], 1, s[8:9]
	v_cvt_pk_bf16_f32 v3, v3, s0
	global_store_short v[4:5], v3, off sc1
	v_add_u32_e32 v4, v186, v16
	v_fmac_f32_e32 v20, v9, v102
	v_ashrrev_i32_e32 v5, 31, v4
	v_mul_f32_e32 v3, v32, v20
	v_lshl_add_u64 v[4:5], v[4:5], 1, s[8:9]
	v_cvt_pk_bf16_f32 v3, v3, s0
	global_store_short v[4:5], v3, off sc1
	v_add_u32_e32 v4, v188, v16
	s_waitcnt vmcnt(15)
	v_fmac_f32_e32 v19, v10, v102
	v_ashrrev_i32_e32 v5, 31, v4
	v_mul_f32_e32 v3, v32, v19
	v_lshl_add_u64 v[4:5], v[4:5], 1, s[8:9]
	v_cvt_pk_bf16_f32 v3, v3, s0
	global_store_short v[4:5], v3, off sc1
	v_add_u32_e32 v4, v189, v16
	s_waitcnt vmcnt(15)
	v_fmac_f32_e32 v18, v11, v102
	v_ashrrev_i32_e32 v5, 31, v4
	v_mul_f32_e32 v3, v32, v18
	v_lshl_add_u64 v[4:5], v[4:5], 1, s[8:9]
	v_cvt_pk_bf16_f32 v3, v3, s0
	global_store_short v[4:5], v3, off sc1
	v_add_u32_e32 v4, v190, v16
	v_ashrrev_i32_e32 v5, 31, v4
	v_lshl_add_u64 v[4:5], v[4:5], 1, s[8:9]
	v_ashrrev_i32_e32 v71, 31, v70
	global_store_dword v[88:89], v28, off offset:384 sc1
	global_store_dword v[84:85], v27, off offset:384 sc1
	global_store_dword v[82:83], v26, off offset:384 sc1
	global_store_dword v[78:79], v25, off offset:384 sc1
	s_waitcnt vmcnt(17)
	v_fmac_f32_e32 v17, v12, v102
	v_mul_f32_e32 v3, v32, v17
	v_cvt_pk_bf16_f32 v3, v3, s0
	global_store_short v[4:5], v3, off sc1
	v_add_u32_e32 v4, v192, v16
	v_ashrrev_i32_e32 v5, 31, v4
	v_lshl_add_u64 v[4:5], v[4:5], 1, s[8:9]
	s_waitcnt vmcnt(16)
	v_fmac_f32_e32 v2, v13, v102
	v_mul_f32_e32 v3, v32, v2
	v_cvt_pk_bf16_f32 v3, v3, s0
	global_store_short v[4:5], v3, off sc1
	v_add_u32_e32 v4, v193, v16
	v_ashrrev_i32_e32 v5, 31, v4
	v_lshl_add_u64 v[4:5], v[4:5], 1, s[8:9]
	v_xor_b32_e32 v12, 16, v165
	global_store_dword v[72:73], v24, off offset:384 sc1
	global_store_dword v[74:75], v23, off offset:384 sc1
	global_store_dword v[76:77], v22, off offset:384 sc1
	global_store_dword v[80:81], v21, off offset:384 sc1
	global_store_dword v[86:87], v20, off offset:384 sc1
	s_waitcnt vmcnt(20)
	v_fmac_f32_e32 v1, v14, v102
	v_mul_f32_e32 v3, v32, v1
	v_cvt_pk_bf16_f32 v3, v3, s0
	global_store_short v[4:5], v3, off sc1
	v_add_u32_e32 v4, v194, v16
	v_ashrrev_i32_e32 v5, 31, v4
	v_lshl_add_u64 v[10:11], v[4:5], 1, s[8:9]
	v_and_b32_e32 v4, 64, v165
	v_xor_b32_e32 v3, 1, v165
	v_add_u32_e32 v7, 64, v4
	v_cmp_lt_i32_e32 vcc, v3, v7
	v_xor_b32_e32 v4, 2, v165
	s_waitcnt vmcnt(19)
	v_fmac_f32_e32 v0, v15, v102
	v_cndmask_b32_e32 v3, v165, v3, vcc
	v_lshlrev_b32_e32 v3, 2, v3
	v_cmp_lt_i32_e32 vcc, v4, v7
	global_store_dword v[90:91], v19, off offset:384 sc1
	global_store_dword v[92:93], v18, off offset:384 sc1
	v_cndmask_b32_e32 v4, v165, v4, vcc
	v_lshlrev_b32_e32 v4, 2, v4
	v_add_f32_dpp v6, v106, v106 quad_perm:[1,0,3,2] row_mask:0xf bank_mask:0xf
	v_xor_b32_e32 v5, 4, v165
	v_cmp_lt_i32_e32 vcc, v5, v7
	global_store_dword v[94:95], v17, off offset:384 sc1
	global_store_dword v[96:97], v2, off offset:384 sc1
	v_cndmask_b32_e32 v5, v165, v5, vcc
	v_lshlrev_b32_e32 v5, 2, v5
	v_add_f32_dpp v8, v6, v6 quad_perm:[2,3,0,1] row_mask:0xf bank_mask:0xf
	v_xor_b32_e32 v6, 8, v165
	v_cmp_lt_i32_e32 vcc, v6, v7
	global_store_dword v[98:99], v1, off offset:384 sc1
	global_store_dword v[100:101], v0, off offset:384 sc1
	v_cndmask_b32_e32 v6, v165, v6, vcc
	v_lshlrev_b32_e32 v6, 2, v6
	v_add_f32_dpp v8, v8, v8 row_half_mirror row_mask:0xf bank_mask:0xf
	v_cmp_lt_i32_e32 vcc, v12, v7
	v_add_f32_dpp v8, v8, v8 row_mirror row_mask:0xf bank_mask:0xf
	v_cndmask_b32_e32 v7, v165, v12, vcc
	v_lshlrev_b32_e32 v7, 2, v7
	ds_bpermute_b32 v9, v7, v8
	v_mul_f32_e32 v12, v32, v0
	v_cvt_pk_bf16_f32 v12, v12, s0
	global_store_short v[10:11], v12, off sc1
	s_and_saveexec_b64 s[60:61], s[0:1]
	s_cbranch_execz .LBB0_1124
	s_waitcnt lgkmcnt(0)
	v_add_f32_e32 v10, v8, v9
	v_lshl_add_u64 v[8:9], v[70:71], 2, s[58:59]
	global_store_dword v[8:9], v10, off sc1

.LBB0_1326:
	s_add_i32 s58, s66, 0xffffe000
	s_lshr_b32 s58, s58, 12
	s_mulk_i32 s58, 0x1800
	v_mov_b32_e32 v70, s70
	s_add_i32 s58, s58, 0xa800
	ds_read_b64 v[70:71], v70
	s_cmp_gt_i32 s6, 63
	s_cselect_b32 s6, s58, 0x9000
	s_lshl_b64 s[58:59], s[6:7], 2
	s_add_u32 s6, s14, s58
	s_addc_u32 s65, s15, s59
	s_waitcnt lgkmcnt(0)
	v_readfirstlane_b32 s58, v70
	v_readfirstlane_b32 s59, v71
	s_add_u32 s60, s58, 0x2000
	s_addc_u32 s61, s59, 0
	s_lshl_b32 s58, s64, 14
	s_add_i32 s58, s58, 0xa0000
	s_ashr_i32 s59, s58, 31
	s_lshl_b64 s[58:59], s[58:59], 2
	s_add_u32 s58, s10, s58
	s_addc_u32 s59, s11, s59
	s_add_u32 s62, s6, 0x5ba2000
	v_or_b32_e32 v102, s68, v138
	v_add_u32_e32 v70, s66, v139
	s_addc_u32 s63, s65, 0
	v_lshlrev_b32_e32 v188, 10, v70
	v_ashrrev_i32_e32 v103, 31, v102
	s_add_u32 s64, s6, 0x5ba4000
	v_lshlrev_b64 v[72:73], 2, v[102:103]
	v_or_b32_e32 v186, 0x400, v188
	v_or_b32_e32 v185, 0x4400, v188
	v_or_b32_e32 v189, 0x4c00, v188
	v_or_b32_e32 v193, 0x6c00, v188
	s_addc_u32 s65, s65, 0
	v_lshl_add_u64 v[74:75], s[62:63], 0, v[72:73]
	v_add_u32_e32 v132, v188, v102
	v_add_u32_e32 v134, v186, v102
	v_or_b32_e32 v184, 0x800, v188
	v_or_b32_e32 v183, 0xc00, v188
	v_or_b32_e32 v181, 0x2000, v188
	v_or_b32_e32 v179, 0x2400, v188
	v_or_b32_e32 v71, 0x2800, v188
	v_or_b32_e32 v180, 0x2c00, v188
	v_or_b32_e32 v182, 0x4000, v188
	v_add_u32_e32 v112, v185, v102
	v_or_b32_e32 v187, 0x4800, v188
	v_add_u32_e32 v118, v189, v102
	v_or_b32_e32 v190, 0x6000, v188
	v_or_b32_e32 v191, 0x6400, v188
	v_or_b32_e32 v192, 0x6800, v188
	v_add_u32_e32 v128, v193, v102
	global_load_dword v194, v[74:75], off
	global_load_dword v204, v[74:75], off offset:128
	global_load_dword v223, v[74:75], off offset:256
	v_lshl_add_u64 v[74:75], s[60:61], 0, v[72:73]
	v_lshl_add_u64 v[72:73], s[64:65], 0, v[72:73]
	v_ashrrev_i32_e32 v135, 31, v134
	v_add_u32_e32 v136, v184, v102
	v_add_u32_e32 v130, v183, v102
	v_add_u32_e32 v122, v181, v102
	v_add_u32_e32 v114, v179, v102
	v_add_u32_e32 v106, v71, v102
	v_add_u32_e32 v108, v180, v102
	v_add_u32_e32 v110, v182, v102
	v_ashrrev_i32_e32 v113, 31, v112
	v_add_u32_e32 v116, v187, v102
	v_ashrrev_i32_e32 v119, 31, v118
	v_add_u32_e32 v120, v190, v102
	v_add_u32_e32 v124, v191, v102
	v_add_u32_e32 v126, v192, v102
	v_ashrrev_i32_e32 v129, 31, v128
	v_ashrrev_i32_e32 v133, 31, v132
	global_load_dword v196, v[72:73], off
	global_load_dword v202, v[72:73], off offset:128
	global_load_dword v221, v[72:73], off offset:256
	v_lshl_add_u64 v[88:89], v[134:135], 2, s[12:13]
	v_ashrrev_i32_e32 v137, 31, v136
	v_ashrrev_i32_e32 v131, 31, v130
	v_ashrrev_i32_e32 v123, 31, v122
	v_ashrrev_i32_e32 v115, 31, v114
	v_ashrrev_i32_e32 v107, 31, v106
	v_ashrrev_i32_e32 v109, 31, v108
	v_ashrrev_i32_e32 v111, 31, v110
	v_lshl_add_u64 v[86:87], v[112:113], 2, s[12:13]
	v_ashrrev_i32_e32 v117, 31, v116
	v_lshl_add_u64 v[92:93], v[118:119], 2, s[12:13]
	v_ashrrev_i32_e32 v121, 31, v120
	v_ashrrev_i32_e32 v125, 31, v124
	v_ashrrev_i32_e32 v127, 31, v126
	v_lshl_add_u64 v[100:101], v[128:129], 2, s[12:13]
	v_lshl_add_u64 v[104:105], v[132:133], 2, s[12:13]
	global_load_dword v195, v[74:75], off
	global_load_dword v203, v[74:75], off offset:128
	global_load_dword v222, v[74:75], off offset:256
	v_lshl_add_u64 v[84:85], v[136:137], 2, s[12:13]
	v_lshl_add_u64 v[82:83], v[130:131], 2, s[12:13]
	v_lshl_add_u64 v[78:79], v[122:123], 2, s[12:13]
	v_lshl_add_u64 v[72:73], v[114:115], 2, s[12:13]
	v_lshl_add_u64 v[74:75], v[106:107], 2, s[12:13]
	v_lshl_add_u64 v[76:77], v[108:109], 2, s[12:13]
	v_lshl_add_u64 v[80:81], v[110:111], 2, s[12:13]
	global_load_dword v178, v[88:89], off
	global_load_dword v177, v[84:85], off
	global_load_dword v176, v[82:83], off
	global_load_dword v175, v[78:79], off
	global_load_dword v174, v[72:73], off
	global_load_dword v173, v[74:75], off
	global_load_dword v172, v[76:77], off
	global_load_dword v171, v[80:81], off
	v_lshl_add_u64 v[90:91], v[116:117], 2, s[12:13]
	global_load_dword v170, v[86:87], off
	global_load_dword v168, v[90:91], off
	v_lshl_add_u64 v[94:95], v[120:121], 2, s[12:13]
	v_lshl_add_u64 v[96:97], v[124:125], 2, s[12:13]
	v_lshl_add_u64 v[98:99], v[126:127], 2, s[12:13]
	global_load_dword v169, v[92:93], off
	global_load_dword v167, v[94:95], off
	global_load_dword v166, v[96:97], off
	global_load_dword v165, v[98:99], off
	global_load_dword v103, v[100:101], off
	global_load_dword v197, v[104:105], off
	v_lshl_add_u64 v[106:107], v[106:107], 1, s[8:9]
	global_load_dword v198, v[104:105], off offset:128
	global_load_dword v205, v[84:85], off offset:128
	global_load_dword v206, v[78:79], off offset:128
	global_load_dword v207, v[72:73], off offset:128
	global_load_dword v208, v[74:75], off offset:128
	global_load_dword v209, v[80:81], off offset:128
	global_load_dword v210, v[76:77], off offset:128
	global_load_dword v211, v[86:87], off offset:128
	global_load_dword v212, v[82:83], off offset:128
	global_load_dword v213, v[90:91], off offset:128
	global_load_dword v214, v[92:93], off offset:128
	global_load_dword v215, v[94:95], off offset:128
	global_load_dword v216, v[96:97], off offset:128
	global_load_dword v217, v[98:99], off offset:128
	global_load_dword v218, v[100:101], off offset:128
	global_load_dword v219, v[88:89], off offset:128
	global_load_dword v220, v[88:89], off offset:256
	global_load_dword v224, v[90:91], off offset:256
	global_load_dword v225, v[92:93], off offset:256
	global_load_dword v226, v[94:95], off offset:256
	global_load_dword v227, v[104:105], off offset:256
	global_load_dword v229, v[84:85], off offset:256
	global_load_dword v230, v[86:87], off offset:256
	global_load_dword v231, v[82:83], off offset:256
	global_load_dword v232, v[78:79], off offset:256
	global_load_dword v233, v[72:73], off offset:256
	global_load_dword v234, v[74:75], off offset:256
	global_load_dword v235, v[80:81], off offset:256
	global_load_dword v236, v[76:77], off offset:256
	global_load_dword v237, v[96:97], off offset:256
	global_load_dword v238, v[98:99], off offset:256
	global_load_dword v239, v[100:101], off offset:256
	s_waitcnt vmcnt(0)
	v_add_f32_e32 v196, 1.0, v196
	v_mul_f32_e32 v195, v195, v196
	v_fmac_f32_e32 v178, v49, v194
	v_fmac_f32_e32 v177, v50, v194
	v_fmac_f32_e32 v176, v51, v194
	v_fmac_f32_e32 v175, v52, v194
	v_fmac_f32_e32 v174, v53, v194
	v_fmac_f32_e32 v173, v54, v194
	v_fmac_f32_e32 v172, v55, v194
	v_fmac_f32_e32 v171, v56, v194
	v_fmac_f32_e32 v170, v57, v194
	v_fmac_f32_e32 v168, v58, v194
	v_fmac_f32_e32 v169, v59, v194
	v_fmac_f32_e32 v167, v60, v194
	v_fmac_f32_e32 v166, v61, v194
	v_fmac_f32_e32 v165, v62, v194
	v_fmac_f32_e32 v103, v63, v194
	v_fmac_f32_e32 v197, v48, v194
	v_mul_f32_e32 v48, v195, v197
	v_cvt_pk_bf16_f32 v58, v48, s0
	v_or_b32_e32 v48, 32, v102
	v_ashrrev_i32_e32 v49, 31, v48
	v_lshlrev_b64 v[52:53], 2, v[48:49]
	global_store_dword v[88:89], v178, off sc1
	global_store_dword v[84:85], v177, off sc1
	global_store_dword v[82:83], v176, off sc1
	global_store_dword v[78:79], v175, off sc1
	global_store_dword v[72:73], v174, off sc1
	global_store_dword v[74:75], v173, off sc1
	global_store_dword v[76:77], v172, off sc1
	global_store_dword v[80:81], v171, off sc1
	global_store_dword v[86:87], v170, off sc1
	global_store_dword v[90:91], v168, off sc1
	global_store_dword v[92:93], v169, off sc1
	global_store_dword v[94:95], v167, off sc1
	global_store_dword v[96:97], v166, off sc1
	global_store_dword v[98:99], v165, off sc1
	global_store_dword v[100:101], v103, off sc1
	global_store_dword v[104:105], v197, off sc1
	v_lshl_add_u64 v[50:51], v[132:133], 1, s[8:9]
	v_lshl_add_u64 v[56:57], s[64:65], 0, v[52:53]
	v_mov_b32_e32 v196, v198
	v_lshl_add_u64 v[54:55], s[60:61], 0, v[52:53]
	v_mov_b32_e32 v132, v202
	v_mov_b32_e32 v133, v203
	v_mul_f32_e32 v49, v195, v178
	global_store_short v[50:51], v58, off sc1
	v_lshl_add_u64 v[50:51], s[62:63], 0, v[52:53]
	v_mov_b32_e32 v194, v204
	v_cvt_pk_bf16_f32 v49, v49, s0
	v_lshl_add_u64 v[50:51], v[134:135], 1, s[8:9]
	global_store_short v[50:51], v49, off sc1
	v_mul_f32_e32 v49, v195, v177
	v_cvt_pk_bf16_f32 v49, v49, s0
	v_lshl_add_u64 v[50:51], v[136:137], 1, s[8:9]
	global_store_short v[50:51], v49, off sc1
	v_mul_f32_e32 v49, v195, v176
	v_cvt_pk_bf16_f32 v49, v49, s0
	v_lshl_add_u64 v[50:51], v[130:131], 1, s[8:9]
	global_store_short v[50:51], v49, off sc1
	v_mul_f32_e32 v49, v195, v175
	v_cvt_pk_bf16_f32 v49, v49, s0
	v_lshl_add_u64 v[50:51], v[122:123], 1, s[8:9]
	global_store_short v[50:51], v49, off sc1
	v_mul_f32_e32 v49, v195, v174
	v_cvt_pk_bf16_f32 v49, v49, s0
	v_lshl_add_u64 v[50:51], v[114:115], 1, s[8:9]
	global_store_short v[50:51], v49, off sc1
	v_mul_f32_e32 v49, v195, v173
	v_mov_b32_e32 v62, v205
	v_mov_b32_e32 v60, v206
	v_mov_b32_e32 v59, v207
	v_mov_b32_e32 v58, v208
	v_mov_b32_e32 v56, v209
	v_mov_b32_e32 v57, v210
	v_mov_b32_e32 v55, v211
	v_mov_b32_e32 v61, v212
	v_mov_b32_e32 v54, v213
	v_mov_b32_e32 v53, v214
	v_mov_b32_e32 v52, v215
	v_mov_b32_e32 v51, v216
	v_mov_b32_e32 v50, v217
	v_cvt_pk_bf16_f32 v63, v49, s0
	v_mov_b32_e32 v49, v218
	v_fmac_f32_e32 v196, v32, v194
	global_store_short v[106:107], v63, off sc1
	v_mov_b32_e32 v63, v219
	v_mul_f32_e32 v106, v195, v172
	v_cvt_pk_bf16_f32 v114, v106, s0
	v_lshl_add_u64 v[106:107], v[108:109], 1, s[8:9]
	global_store_short v[106:107], v114, off sc1
	v_mul_f32_e32 v106, v195, v171
	v_cvt_pk_bf16_f32 v108, v106, s0
	v_lshl_add_u64 v[106:107], v[110:111], 1, s[8:9]
	global_store_short v[106:107], v108, off sc1
	v_mul_f32_e32 v106, v195, v170
	v_cvt_pk_bf16_f32 v108, v106, s0
	v_lshl_add_u64 v[106:107], v[112:113], 1, s[8:9]
	global_store_short v[106:107], v108, off sc1
	v_mul_f32_e32 v106, v195, v168
	v_cvt_pk_bf16_f32 v108, v106, s0
	v_lshl_add_u64 v[106:107], v[116:117], 1, s[8:9]
	global_store_short v[106:107], v108, off sc1
	v_mul_f32_e32 v106, v195, v169
	v_cvt_pk_bf16_f32 v108, v106, s0
	v_lshl_add_u64 v[106:107], v[118:119], 1, s[8:9]
	global_store_short v[106:107], v108, off sc1
	v_mul_f32_e32 v106, v195, v167
	v_cvt_pk_bf16_f32 v108, v106, s0
	v_lshl_add_u64 v[106:107], v[120:121], 1, s[8:9]
	global_store_short v[106:107], v108, off sc1
	v_mul_f32_e32 v106, v195, v166
	v_cvt_pk_bf16_f32 v108, v106, s0
	v_lshl_add_u64 v[106:107], v[124:125], 1, s[8:9]
	global_store_short v[106:107], v108, off sc1
	v_mul_f32_e32 v106, v195, v165
	v_cvt_pk_bf16_f32 v108, v106, s0
	v_lshl_add_u64 v[106:107], v[126:127], 1, s[8:9]
	global_store_short v[106:107], v108, off sc1
	v_mul_f32_e32 v106, v195, v103
	v_cvt_pk_bf16_f32 v108, v106, s0
	v_lshl_add_u64 v[106:107], v[128:129], 1, s[8:9]
	global_store_short v[106:107], v108, off sc1
	v_add_f32_e32 v106, 1.0, v132
	v_mul_f32_e32 v110, v133, v106
	v_add_u32_e32 v106, v188, v48
	v_fmac_f32_e32 v62, v34, v194
	v_fmac_f32_e32 v61, v35, v194
	v_fmac_f32_e32 v60, v36, v194
	v_fmac_f32_e32 v59, v37, v194
	v_fmac_f32_e32 v58, v38, v194
	v_fmac_f32_e32 v57, v39, v194
	v_fmac_f32_e32 v56, v40, v194
	v_fmac_f32_e32 v55, v41, v194
	v_fmac_f32_e32 v54, v42, v194
	v_fmac_f32_e32 v53, v43, v194
	v_fmac_f32_e32 v52, v44, v194
	v_fmac_f32_e32 v51, v45, v194
	v_fmac_f32_e32 v50, v46, v194
	v_fmac_f32_e32 v49, v47, v194
	v_ashrrev_i32_e32 v107, 31, v106
	global_store_dword v[104:105], v196, off offset:128 sc1
	v_mul_f32_e32 v32, v110, v196
	global_store_dword v[84:85], v62, off offset:128 sc1
	global_store_dword v[82:83], v61, off offset:128 sc1
	global_store_dword v[78:79], v60, off offset:128 sc1
	global_store_dword v[72:73], v59, off offset:128 sc1
	global_store_dword v[74:75], v58, off offset:128 sc1
	global_store_dword v[76:77], v57, off offset:128 sc1
	global_store_dword v[80:81], v56, off offset:128 sc1
	global_store_dword v[86:87], v55, off offset:128 sc1
	global_store_dword v[90:91], v54, off offset:128 sc1
	global_store_dword v[92:93], v53, off offset:128 sc1
	global_store_dword v[94:95], v52, off offset:128 sc1
	global_store_dword v[96:97], v51, off offset:128 sc1
	global_store_dword v[98:99], v50, off offset:128 sc1
	global_store_dword v[100:101], v49, off offset:128 sc1
	v_cvt_pk_bf16_f32 v32, v32, s0
	v_lshl_add_u64 v[106:107], v[106:107], 1, s[8:9]
	v_add_u32_e32 v108, v186, v48
	v_mov_b32_e32 v45, v220
	v_ashrrev_i32_e32 v109, 31, v108
	global_store_short v[106:107], v32, off sc1
	v_mul_f32_e32 v113, v110, v56
	v_cvt_pk_bf16_f32 v113, v113, s0
	v_mul_f32_e32 v106, v196, v196
	v_fmac_f32_e32 v63, v33, v194
	v_mul_f32_e32 v32, v110, v63
	v_cvt_pk_bf16_f32 v34, v32, s0
	v_lshl_add_u64 v[32:33], v[108:109], 1, s[8:9]
	global_store_short v[32:33], v34, off sc1
	v_add_u32_e32 v32, v184, v48
	v_ashrrev_i32_e32 v33, 31, v32
	v_mul_f32_e32 v34, v110, v62
	v_cvt_pk_bf16_f32 v34, v34, s0
	v_lshl_add_u64 v[32:33], v[32:33], 1, s[8:9]
	global_store_short v[32:33], v34, off sc1
	v_add_u32_e32 v32, v183, v48
	v_ashrrev_i32_e32 v33, 31, v32
	v_mul_f32_e32 v34, v110, v61
	v_cvt_pk_bf16_f32 v34, v34, s0
	v_lshl_add_u64 v[32:33], v[32:33], 1, s[8:9]
	global_store_short v[32:33], v34, off sc1
	v_add_u32_e32 v32, v181, v48
	v_ashrrev_i32_e32 v33, 31, v32
	v_mul_f32_e32 v34, v110, v60
	v_cvt_pk_bf16_f32 v34, v34, s0
	v_lshl_add_u64 v[32:33], v[32:33], 1, s[8:9]
	global_store_short v[32:33], v34, off sc1
	v_add_u32_e32 v32, v179, v48
	v_ashrrev_i32_e32 v33, 31, v32
	v_mul_f32_e32 v34, v110, v59
	v_cvt_pk_bf16_f32 v42, v34, s0
	v_lshl_add_u64 v[34:35], v[32:33], 1, s[8:9]
	v_or_b32_e32 v32, 64, v102
	v_ashrrev_i32_e32 v33, 31, v32
	v_lshlrev_b64 v[36:37], 2, v[32:33]
	global_store_dword v[88:89], v63, off offset:128 sc1
	v_lshl_add_u64 v[40:41], s[64:65], 0, v[36:37]
	v_lshl_add_u64 v[38:39], s[60:61], 0, v[36:37]
	v_mov_b32_e32 v107, v221
	v_mov_b32_e32 v111, v222
	v_mul_f32_e32 v33, v110, v58
	global_store_short v[34:35], v42, off sc1
	v_lshl_add_u64 v[34:35], s[62:63], 0, v[36:37]
	v_mov_b32_e32 v112, v223
	v_add_u32_e32 v34, v71, v48
	v_ashrrev_i32_e32 v35, 31, v34
	v_cvt_pk_bf16_f32 v33, v33, s0
	v_lshl_add_u64 v[34:35], v[34:35], 1, s[8:9]
	global_store_short v[34:35], v33, off sc1
	v_add_u32_e32 v34, v180, v48
	v_ashrrev_i32_e32 v35, 31, v34
	v_mul_f32_e32 v33, v110, v57
	v_cvt_pk_bf16_f32 v33, v33, s0
	v_lshl_add_u64 v[34:35], v[34:35], 1, s[8:9]
	v_mov_b32_e32 v38, v224
	v_mov_b32_e32 v37, v225
	v_mov_b32_e32 v36, v226
	v_mov_b32_e32 v114, v227
	v_mov_b32_e32 v47, v229
	v_mov_b32_e32 v39, v230
	v_mov_b32_e32 v46, v231
	v_mov_b32_e32 v44, v232
	v_mov_b32_e32 v43, v233
	v_mov_b32_e32 v42, v234
	v_mov_b32_e32 v40, v235
	v_mov_b32_e32 v41, v236
	v_add_u32_e32 v108, v182, v48
	global_store_short v[34:35], v33, off sc1
	v_mov_b32_e32 v35, v237
	v_ashrrev_i32_e32 v109, 31, v108
	v_mov_b32_e32 v34, v238
	v_mov_b32_e32 v33, v239
	v_lshl_add_u64 v[108:109], v[108:109], 1, s[8:9]
	global_store_short v[108:109], v113, off sc1
	v_add_u32_e32 v108, v185, v48
	v_ashrrev_i32_e32 v109, 31, v108
	v_mul_f32_e32 v113, v110, v55
	v_cvt_pk_bf16_f32 v113, v113, s0
	v_lshl_add_u64 v[108:109], v[108:109], 1, s[8:9]
	global_store_short v[108:109], v113, off sc1
	v_add_u32_e32 v108, v187, v48
	v_ashrrev_i32_e32 v109, 31, v108
	v_mul_f32_e32 v113, v110, v54
	v_cvt_pk_bf16_f32 v113, v113, s0
	v_lshl_add_u64 v[108:109], v[108:109], 1, s[8:9]
	global_store_short v[108:109], v113, off sc1
	v_add_u32_e32 v108, v189, v48
	v_ashrrev_i32_e32 v109, 31, v108
	v_mul_f32_e32 v113, v110, v53
	v_cvt_pk_bf16_f32 v113, v113, s0
	v_lshl_add_u64 v[108:109], v[108:109], 1, s[8:9]
	global_store_short v[108:109], v113, off sc1
	v_add_u32_e32 v108, v190, v48
	v_ashrrev_i32_e32 v109, 31, v108
	v_mul_f32_e32 v113, v110, v52
	v_cvt_pk_bf16_f32 v113, v113, s0
	v_lshl_add_u64 v[108:109], v[108:109], 1, s[8:9]
	global_store_short v[108:109], v113, off sc1
	v_add_u32_e32 v108, v191, v48
	v_ashrrev_i32_e32 v109, 31, v108
	v_mul_f32_e32 v113, v110, v51
	v_cvt_pk_bf16_f32 v113, v113, s0
	v_lshl_add_u64 v[108:109], v[108:109], 1, s[8:9]
	global_store_short v[108:109], v113, off sc1
	v_add_u32_e32 v108, v192, v48
	v_ashrrev_i32_e32 v109, 31, v108
	v_mul_f32_e32 v113, v110, v50
	v_cvt_pk_bf16_f32 v113, v113, s0
	v_lshl_add_u64 v[108:109], v[108:109], 1, s[8:9]
	global_store_short v[108:109], v113, off sc1
	v_add_u32_e32 v108, v193, v48
	v_ashrrev_i32_e32 v109, 31, v108
	v_mul_f32_e32 v48, v110, v49
	v_cvt_pk_bf16_f32 v48, v48, s0
	v_lshl_add_u64 v[108:109], v[108:109], 1, s[8:9]
	global_store_short v[108:109], v48, off sc1
	v_add_u32_e32 v108, v188, v32
	v_ashrrev_i32_e32 v109, 31, v108
	v_add_f32_e32 v48, 1.0, v107
	v_mul_f32_e32 v48, v111, v48
	v_fmac_f32_e32 v106, v197, v197
	v_fmac_f32_e32 v45, v17, v112
	global_store_dword v[88:89], v45, off offset:256 sc1
	v_fmac_f32_e32 v38, v26, v112
	v_fmac_f32_e32 v37, v27, v112
	v_fmac_f32_e32 v36, v28, v112
	v_fmac_f32_e32 v114, v16, v112
	v_mul_f32_e32 v16, v48, v114
	v_fmac_f32_e32 v47, v18, v112
	v_cvt_pk_bf16_f32 v18, v16, s0
	v_lshl_add_u64 v[16:17], v[108:109], 1, s[8:9]
	global_store_short v[16:17], v18, off sc1
	v_add_u32_e32 v16, v186, v32
	v_ashrrev_i32_e32 v17, 31, v16
	v_mul_f32_e32 v18, v48, v45
	v_cvt_pk_bf16_f32 v18, v18, s0
	v_lshl_add_u64 v[16:17], v[16:17], 1, s[8:9]
	global_store_short v[16:17], v18, off sc1
	v_add_u32_e32 v16, v184, v32
	v_ashrrev_i32_e32 v17, 31, v16
	v_mul_f32_e32 v18, v48, v47
	v_cvt_pk_bf16_f32 v18, v18, s0
	v_lshl_add_u64 v[16:17], v[16:17], 1, s[8:9]
	v_fmac_f32_e32 v46, v19, v112
	global_store_short v[16:17], v18, off sc1
	v_add_u32_e32 v16, v183, v32
	v_ashrrev_i32_e32 v17, 31, v16
	v_mul_f32_e32 v18, v48, v46
	v_fmac_f32_e32 v44, v20, v112
	v_cvt_pk_bf16_f32 v18, v18, s0
	v_lshl_add_u64 v[16:17], v[16:17], 1, s[8:9]
	global_store_short v[16:17], v18, off sc1
	v_mul_f32_e32 v16, v48, v44
	v_cvt_pk_bf16_f32 v26, v16, s0
	v_or_b32_e32 v16, 0x60, v102
	v_add_u32_e32 v18, v181, v32
	v_ashrrev_i32_e32 v17, 31, v16
	v_fmac_f32_e32 v43, v21, v112
	v_fmac_f32_e32 v42, v22, v112
	v_fmac_f32_e32 v41, v23, v112
	v_fmac_f32_e32 v40, v24, v112
	v_fmac_f32_e32 v39, v25, v112
	v_fmac_f32_e32 v35, v29, v112
	v_fmac_f32_e32 v34, v30, v112
	v_fmac_f32_e32 v33, v31, v112
	v_ashrrev_i32_e32 v19, 31, v18
	v_lshlrev_b64 v[20:21], 2, v[16:17]
	global_store_dword v[84:85], v47, off offset:256 sc1
	global_store_dword v[82:83], v46, off offset:256 sc1
	global_store_dword v[78:79], v44, off offset:256 sc1
	global_store_dword v[72:73], v43, off offset:256 sc1
	global_store_dword v[74:75], v42, off offset:256 sc1
	global_store_dword v[76:77], v41, off offset:256 sc1
	global_store_dword v[80:81], v40, off offset:256 sc1
	global_store_dword v[86:87], v39, off offset:256 sc1
	global_store_dword v[90:91], v38, off offset:256 sc1
	global_store_dword v[92:93], v37, off offset:256 sc1
	global_store_dword v[94:95], v36, off offset:256 sc1
	global_store_dword v[96:97], v35, off offset:256 sc1
	global_store_dword v[98:99], v34, off offset:256 sc1
	global_store_dword v[100:101], v33, off offset:256 sc1
	global_store_dword v[104:105], v114, off offset:256 sc1
	v_lshl_add_u64 v[24:25], s[64:65], 0, v[20:21]
	v_lshl_add_u64 v[18:19], v[18:19], 1, s[8:9]
	global_load_dword v29, v[104:105], off offset:384
	v_lshl_add_u64 v[22:23], s[60:61], 0, v[20:21]
	global_load_dword v17, v[24:25], off
	global_load_dword v30, v[22:23], off
	global_load_dword v28, v[88:89], off offset:384
	global_load_dword v27, v[84:85], off offset:384
	v_fmac_f32_e32 v106, v114, v114
	global_store_short v[18:19], v26, off sc1
	v_lshl_add_u64 v[18:19], s[62:63], 0, v[20:21]
	global_load_dword v102, v[18:19], off
	v_add_u32_e32 v18, v179, v32
	v_ashrrev_i32_e32 v19, 31, v18
	v_mul_f32_e32 v20, v48, v43
	v_cvt_pk_bf16_f32 v20, v20, s0
	v_lshl_add_u64 v[18:19], v[18:19], 1, s[8:9]
	global_store_short v[18:19], v20, off sc1
	v_add_u32_e32 v18, v71, v32
	v_ashrrev_i32_e32 v19, 31, v18
	v_mul_f32_e32 v20, v48, v42
	v_cvt_pk_bf16_f32 v20, v20, s0
	v_lshl_add_u64 v[18:19], v[18:19], 1, s[8:9]
	global_store_short v[18:19], v20, off sc1
	v_add_u32_e32 v18, v180, v32
	v_ashrrev_i32_e32 v19, 31, v18
	v_mul_f32_e32 v20, v48, v41
	v_cvt_pk_bf16_f32 v20, v20, s0
	v_lshl_add_u64 v[18:19], v[18:19], 1, s[8:9]
	global_store_short v[18:19], v20, off sc1
	v_add_u32_e32 v18, v182, v32
	v_ashrrev_i32_e32 v19, 31, v18
	v_mul_f32_e32 v20, v48, v40
	v_cvt_pk_bf16_f32 v20, v20, s0
	v_lshl_add_u64 v[18:19], v[18:19], 1, s[8:9]
	global_store_short v[18:19], v20, off sc1
	v_add_u32_e32 v18, v185, v32
	v_ashrrev_i32_e32 v19, 31, v18
	v_mul_f32_e32 v20, v48, v39
	v_cvt_pk_bf16_f32 v20, v20, s0
	v_lshl_add_u64 v[18:19], v[18:19], 1, s[8:9]
	global_store_short v[18:19], v20, off sc1
	v_add_u32_e32 v18, v187, v32
	v_ashrrev_i32_e32 v19, 31, v18
	v_mul_f32_e32 v20, v48, v38
	v_cvt_pk_bf16_f32 v20, v20, s0
	v_lshl_add_u64 v[18:19], v[18:19], 1, s[8:9]
	global_store_short v[18:19], v20, off sc1
	v_add_u32_e32 v18, v189, v32
	v_ashrrev_i32_e32 v19, 31, v18
	v_mul_f32_e32 v20, v48, v37
	v_cvt_pk_bf16_f32 v20, v20, s0
	v_lshl_add_u64 v[18:19], v[18:19], 1, s[8:9]
	global_store_short v[18:19], v20, off sc1
	v_add_u32_e32 v18, v190, v32
	v_ashrrev_i32_e32 v19, 31, v18
	v_mul_f32_e32 v20, v48, v36
	v_cvt_pk_bf16_f32 v20, v20, s0
	v_lshl_add_u64 v[18:19], v[18:19], 1, s[8:9]
	global_store_short v[18:19], v20, off sc1
	v_add_u32_e32 v18, v191, v32
	v_ashrrev_i32_e32 v19, 31, v18
	v_mul_f32_e32 v20, v48, v35
	v_cvt_pk_bf16_f32 v20, v20, s0
	v_lshl_add_u64 v[18:19], v[18:19], 1, s[8:9]
	global_store_short v[18:19], v20, off sc1
	v_add_u32_e32 v18, v192, v32
	v_ashrrev_i32_e32 v19, 31, v18
	v_mul_f32_e32 v20, v48, v34
	v_cvt_pk_bf16_f32 v20, v20, s0
	v_lshl_add_u64 v[18:19], v[18:19], 1, s[8:9]
	global_store_short v[18:19], v20, off sc1
	v_add_u32_e32 v18, v193, v32
	v_ashrrev_i32_e32 v19, 31, v18
	v_mul_f32_e32 v20, v48, v33
	v_cvt_pk_bf16_f32 v20, v20, s0
	v_lshl_add_u64 v[18:19], v[18:19], 1, s[8:9]
	global_store_short v[18:19], v20, off sc1
	global_load_dword v20, v[86:87], off offset:384
	v_add_u32_e32 v18, v188, v16
	global_load_dword v26, v[82:83], off offset:384
	global_load_dword v25, v[78:79], off offset:384
	global_load_dword v24, v[72:73], off offset:384
	global_load_dword v23, v[74:75], off offset:384
	global_load_dword v21, v[80:81], off offset:384
	global_load_dword v22, v[76:77], off offset:384
	s_waitcnt vmcnt(23)
	v_add_f32_e32 v17, 1.0, v17
	s_waitcnt vmcnt(22)
	v_mul_f32_e32 v32, v30, v17
	v_ashrrev_i32_e32 v19, 31, v18
	v_lshl_add_u64 v[18:19], v[18:19], 1, s[8:9]
	v_add_u32_e32 v30, v186, v16
	s_waitcnt vmcnt(18)
	v_fmac_f32_e32 v29, v0, v102
	v_mul_f32_e32 v0, v32, v29
	v_cvt_pk_bf16_f32 v0, v0, s0
	global_store_short v[18:19], v0, off sc1
	global_load_dword v19, v[90:91], off offset:384
	v_ashrrev_i32_e32 v31, 31, v30
	global_load_dword v18, v[92:93], off offset:384
	v_fmac_f32_e32 v28, v1, v102
	v_mul_f32_e32 v0, v32, v28
	v_cvt_pk_bf16_f32 v17, v0, s0
	v_lshl_add_u64 v[0:1], v[30:31], 1, s[8:9]
	global_store_short v[0:1], v17, off sc1
	v_add_u32_e32 v0, v184, v16
	v_fmac_f32_e32 v27, v2, v102
	global_load_dword v17, v[94:95], off offset:384
	v_ashrrev_i32_e32 v1, 31, v0
	v_mul_f32_e32 v2, v32, v27
	v_cvt_pk_bf16_f32 v2, v2, s0
	v_lshl_add_u64 v[0:1], v[0:1], 1, s[8:9]
	global_store_short v[0:1], v2, off sc1
	v_add_u32_e32 v0, v183, v16
	global_load_dword v2, v[96:97], off offset:384
	v_ashrrev_i32_e32 v1, 31, v0
	v_lshl_add_u64 v[0:1], v[0:1], 1, s[8:9]
	v_add_u32_e32 v30, v181, v16
	v_ashrrev_i32_e32 v31, 31, v30
	v_lshl_add_u64 v[30:31], v[30:31], 1, s[8:9]
	v_fmac_f32_e32 v106, v29, v29
	global_store_dword v[104:105], v29, off offset:384 sc1
	global_store_dword v[88:89], v28, off offset:384 sc1
	global_store_dword v[84:85], v27, off offset:384 sc1
	s_waitcnt vmcnt(16)
	v_fmac_f32_e32 v20, v9, v102
	global_store_dword v[86:87], v20, off offset:384 sc1
	s_waitcnt vmcnt(16)
	v_fmac_f32_e32 v26, v3, v102
	v_mul_f32_e32 v3, v32, v26
	v_cvt_pk_bf16_f32 v3, v3, s0
	global_store_short v[0:1], v3, off sc1
	global_load_dword v1, v[98:99], off offset:384
	s_waitcnt vmcnt(17)
	v_fmac_f32_e32 v25, v4, v102
	v_mul_f32_e32 v0, v32, v25
	v_cvt_pk_bf16_f32 v0, v0, s0
	global_store_short v[30:31], v0, off sc1
	global_load_dword v0, v[100:101], off offset:384
	v_add_u32_e32 v30, v179, v16
	s_waitcnt vmcnt(18)
	v_fmac_f32_e32 v24, v5, v102
	v_ashrrev_i32_e32 v31, 31, v30
	v_mul_f32_e32 v3, v32, v24
	v_cvt_pk_bf16_f32 v3, v3, s0
	v_lshl_add_u64 v[4:5], v[30:31], 1, s[8:9]
	global_store_short v[4:5], v3, off sc1
	v_add_u32_e32 v4, v71, v16
	s_waitcnt vmcnt(18)
	v_fmac_f32_e32 v23, v6, v102
	v_ashrrev_i32_e32 v5, 31, v4
	v_mul_f32_e32 v3, v32, v23
	v_cvt_pk_bf16_f32 v3, v3, s0
	v_lshl_add_u64 v[4:5], v[4:5], 1, s[8:9]
	global_store_short v[4:5], v3, off sc1
	v_add_u32_e32 v4, v180, v16
	s_waitcnt vmcnt(17)
	v_fmac_f32_e32 v22, v7, v102
	v_ashrrev_i32_e32 v5, 31, v4
	v_mul_f32_e32 v3, v32, v22
	v_cvt_pk_bf16_f32 v3, v3, s0
	v_lshl_add_u64 v[4:5], v[4:5], 1, s[8:9]
	global_store_short v[4:5], v3, off sc1
	v_add_u32_e32 v4, v182, v16
	v_fmac_f32_e32 v21, v8, v102
	v_ashrrev_i32_e32 v5, 31, v4
	v_mul_f32_e32 v3, v32, v21
	v_cvt_pk_bf16_f32 v3, v3, s0
	v_lshl_add_u64 v[4:5], v[4:5], 1, s[8:9]
	global_store_short v[4:5], v3, off sc1
	v_add_u32_e32 v4, v185, v16
	v_ashrrev_i32_e32 v5, 31, v4
	v_mul_f32_e32 v3, v32, v20
	v_cvt_pk_bf16_f32 v3, v3, s0
	v_lshl_add_u64 v[4:5], v[4:5], 1, s[8:9]
	global_store_short v[4:5], v3, off sc1
	v_add_u32_e32 v4, v187, v16
	s_waitcnt vmcnt(18)
	v_fmac_f32_e32 v19, v10, v102
	v_ashrrev_i32_e32 v5, 31, v4
	v_mul_f32_e32 v3, v32, v19
	v_cvt_pk_bf16_f32 v3, v3, s0
	v_lshl_add_u64 v[4:5], v[4:5], 1, s[8:9]
	global_store_short v[4:5], v3, off sc1
	v_add_u32_e32 v4, v189, v16
	s_waitcnt vmcnt(18)
	v_fmac_f32_e32 v18, v11, v102
	v_ashrrev_i32_e32 v5, 31, v4
	v_mul_f32_e32 v3, v32, v18
	v_cvt_pk_bf16_f32 v3, v3, s0
	v_lshl_add_u64 v[4:5], v[4:5], 1, s[8:9]
	global_store_short v[4:5], v3, off sc1
	v_add_u32_e32 v4, v190, v16
	s_waitcnt vmcnt(17)
	v_fmac_f32_e32 v17, v12, v102
	v_ashrrev_i32_e32 v5, 31, v4
	v_mul_f32_e32 v3, v32, v17
	v_cvt_pk_bf16_f32 v3, v3, s0
	v_lshl_add_u64 v[4:5], v[4:5], 1, s[8:9]
	global_store_short v[4:5], v3, off sc1
	v_add_u32_e32 v4, v191, v16
	s_waitcnt vmcnt(16)
	v_fmac_f32_e32 v2, v13, v102
	v_ashrrev_i32_e32 v5, 31, v4
	v_mul_f32_e32 v3, v32, v2
	v_cvt_pk_bf16_f32 v3, v3, s0
	v_lshl_add_u64 v[4:5], v[4:5], 1, s[8:9]
	global_store_short v[4:5], v3, off sc1
	v_add_u32_e32 v4, v192, v16
	v_ashrrev_i32_e32 v5, 31, v4
	v_lshl_add_u64 v[4:5], v[4:5], 1, s[8:9]
	v_xor_b32_e32 v13, 16, v164
	v_add_u32_e32 v10, v193, v16
	v_ashrrev_i32_e32 v11, 31, v10
	v_lshl_add_u64 v[10:11], v[10:11], 1, s[8:9]
	v_ashrrev_i32_e32 v71, 31, v70
	global_store_dword v[82:83], v26, off offset:384 sc1
	global_store_dword v[78:79], v25, off offset:384 sc1
	global_store_dword v[72:73], v24, off offset:384 sc1
	global_store_dword v[74:75], v23, off offset:384 sc1
	s_waitcnt vmcnt(15)
	v_fmac_f32_e32 v1, v14, v102
	v_mul_f32_e32 v3, v32, v1
	v_cvt_pk_bf16_f32 v3, v3, s0
	global_store_short v[4:5], v3, off sc1
	v_and_b32_e32 v4, 64, v164
	v_xor_b32_e32 v3, 1, v164
	v_add_u32_e32 v7, 64, v4
	v_cmp_lt_i32_e32 vcc, v3, v7
	v_xor_b32_e32 v4, 2, v164
	s_waitcnt vmcnt(14)
	v_fmac_f32_e32 v0, v15, v102
	v_cndmask_b32_e32 v3, v164, v3, vcc
	v_lshlrev_b32_e32 v3, 2, v3
	v_cmp_lt_i32_e32 vcc, v4, v7
	v_mul_f32_e32 v12, v32, v0
	v_cvt_pk_bf16_f32 v12, v12, s0
	v_cndmask_b32_e32 v4, v164, v4, vcc
	v_lshlrev_b32_e32 v4, 2, v4
	v_add_f32_dpp v6, v106, v106 quad_perm:[1,0,3,2] row_mask:0xf bank_mask:0xf
	v_xor_b32_e32 v5, 4, v164
	v_cmp_lt_i32_e32 vcc, v5, v7
	global_store_dword v[76:77], v22, off offset:384 sc1
	global_store_dword v[80:81], v21, off offset:384 sc1
	v_cndmask_b32_e32 v5, v164, v5, vcc
	v_lshlrev_b32_e32 v5, 2, v5
	v_add_f32_dpp v8, v6, v6 quad_perm:[2,3,0,1] row_mask:0xf bank_mask:0xf
	v_xor_b32_e32 v6, 8, v164
	v_cmp_lt_i32_e32 vcc, v6, v7
	global_store_dword v[90:91], v19, off offset:384 sc1
	global_store_dword v[92:93], v18, off offset:384 sc1
	v_cndmask_b32_e32 v6, v164, v6, vcc
	v_lshlrev_b32_e32 v6, 2, v6
	v_add_f32_dpp v8, v8, v8 row_half_mirror row_mask:0xf bank_mask:0xf
	v_cmp_lt_i32_e32 vcc, v13, v7
	global_store_dword v[94:95], v17, off offset:384 sc1
	global_store_dword v[96:97], v2, off offset:384 sc1
	v_cndmask_b32_e32 v7, v164, v13, vcc
	v_lshlrev_b32_e32 v7, 2, v7
	v_add_f32_dpp v8, v8, v8 row_mirror row_mask:0xf bank_mask:0xf
	ds_bpermute_b32 v9, v7, v8
	global_store_dword v[98:99], v1, off offset:384 sc1
	global_store_dword v[100:101], v0, off offset:384 sc1
	global_store_short v[10:11], v12, off sc1
	s_and_saveexec_b64 s[60:61], s[0:1]
	s_cbranch_execz .LBB0_1328
	s_waitcnt lgkmcnt(0)
	v_add_f32_e32 v10, v8, v9
	v_lshl_add_u64 v[8:9], v[70:71], 2, s[58:59]
	global_store_dword v[8:9], v10, off sc1

.LBB0_1398:
	s_add_i32 s58, s67, 0xffffe000
	s_lshr_b32 s58, s58, 12
	s_mulk_i32 s58, 0x1800
	s_addk_i32 s58, 0x1800
	s_cmp_gt_i32 s6, 63
	s_cselect_b32 s62, s58, 0
	s_add_i32 s6, s62, 0x9000
	s_lshl_b64 s[58:59], s[6:7], 2
	s_add_u32 s6, s14, s58
	s_addc_u32 s58, s15, s59
	s_add_u32 s60, s6, 0x5ba5000
	s_addc_u32 s61, s58, 0
	s_add_i32 s6, s62, 0xd800
	s_lshl_b64 s[58:59], s[6:7], 2
	v_mov_b32_e32 v70, s66
	s_add_u32 s6, s14, s58
	ds_read_b64 v[70:71], v70
	s_addc_u32 s69, s15, s59
	s_lshl_b32 s58, s64, 14
	s_add_i32 s58, s58, 0xc0000
	s_ashr_i32 s59, s58, 31
	s_lshl_b64 s[58:59], s[58:59], 2
	s_add_u32 s58, s10, s58
	s_waitcnt lgkmcnt(0)
	v_readfirstlane_b32 s63, v70
	s_addc_u32 s59, s11, s59
	v_or_b32_e32 v102, s68, v138
	v_add_u32_e32 v70, s67, v139
	v_readfirstlane_b32 s65, v71
	s_add_u32 s62, s63, 0x3000
	v_ashrrev_i32_e32 v103, 31, v102
	v_lshlrev_b32_e32 v191, 10, v70
	s_addc_u32 s63, s65, 0
	v_lshlrev_b64 v[72:73], 2, v[102:103]
	v_or_b32_e32 v187, 0x400, v191
	v_or_b32_e32 v186, 0x4400, v191
	v_or_b32_e32 v189, 0x4c00, v191
	v_or_b32_e32 v194, 0x6c00, v191
	s_add_u32 s64, s6, 0x5ba1000
	v_lshl_add_u64 v[74:75], s[60:61], 0, v[72:73]
	v_add_u32_e32 v130, v191, v102
	v_add_u32_e32 v132, v187, v102
	v_or_b32_e32 v185, 0x800, v191
	v_or_b32_e32 v184, 0xc00, v191
	v_or_b32_e32 v182, 0x2000, v191
	v_or_b32_e32 v180, 0x2400, v191
	v_or_b32_e32 v71, 0x2800, v191
	v_or_b32_e32 v181, 0x2c00, v191
	v_or_b32_e32 v183, 0x4000, v191
	v_add_u32_e32 v112, v186, v102
	v_or_b32_e32 v188, 0x4800, v191
	v_add_u32_e32 v116, v189, v102
	v_or_b32_e32 v190, 0x6000, v191
	v_or_b32_e32 v192, 0x6400, v191
	v_or_b32_e32 v193, 0x6800, v191
	v_add_u32_e32 v128, v194, v102
	s_addc_u32 s65, s69, 0
	global_load_dword v195, v[74:75], off
	global_load_dword v205, v[74:75], off offset:128
	global_load_dword v224, v[74:75], off offset:256
	v_lshl_add_u64 v[74:75], s[62:63], 0, v[72:73]
	v_ashrrev_i32_e32 v133, 31, v132
	v_add_u32_e32 v134, v185, v102
	v_add_u32_e32 v136, v184, v102
	v_add_u32_e32 v126, v182, v102
	v_add_u32_e32 v118, v180, v102
	v_add_u32_e32 v110, v71, v102
	v_add_u32_e32 v106, v181, v102
	v_add_u32_e32 v108, v183, v102
	v_ashrrev_i32_e32 v113, 31, v112
	v_add_u32_e32 v114, v188, v102
	v_ashrrev_i32_e32 v117, 31, v116
	v_add_u32_e32 v120, v190, v102
	v_add_u32_e32 v122, v192, v102
	v_add_u32_e32 v124, v193, v102
	v_ashrrev_i32_e32 v129, 31, v128
	v_ashrrev_i32_e32 v131, 31, v130
	v_lshl_add_u64 v[72:73], s[64:65], 0, v[72:73]
	global_load_dword v196, v[74:75], off
	global_load_dword v204, v[74:75], off offset:128
	global_load_dword v223, v[74:75], off offset:256
	global_load_dword v197, v[72:73], off
	global_load_dword v203, v[72:73], off offset:128
	global_load_dword v222, v[72:73], off offset:256
	v_lshl_add_u64 v[88:89], v[132:133], 2, s[12:13]
	v_ashrrev_i32_e32 v135, 31, v134
	v_ashrrev_i32_e32 v137, 31, v136
	v_ashrrev_i32_e32 v127, 31, v126
	v_ashrrev_i32_e32 v119, 31, v118
	v_ashrrev_i32_e32 v111, 31, v110
	v_ashrrev_i32_e32 v107, 31, v106
	v_ashrrev_i32_e32 v109, 31, v108
	v_lshl_add_u64 v[86:87], v[112:113], 2, s[12:13]
	v_ashrrev_i32_e32 v115, 31, v114
	v_lshl_add_u64 v[92:93], v[116:117], 2, s[12:13]
	v_ashrrev_i32_e32 v121, 31, v120
	v_ashrrev_i32_e32 v123, 31, v122
	v_ashrrev_i32_e32 v125, 31, v124
	v_lshl_add_u64 v[100:101], v[128:129], 2, s[12:13]
	v_lshl_add_u64 v[104:105], v[130:131], 2, s[12:13]
	v_lshl_add_u64 v[84:85], v[134:135], 2, s[12:13]
	v_lshl_add_u64 v[82:83], v[136:137], 2, s[12:13]
	v_lshl_add_u64 v[78:79], v[126:127], 2, s[12:13]
	v_lshl_add_u64 v[72:73], v[118:119], 2, s[12:13]
	v_lshl_add_u64 v[74:75], v[110:111], 2, s[12:13]
	v_lshl_add_u64 v[76:77], v[106:107], 2, s[12:13]
	v_lshl_add_u64 v[80:81], v[108:109], 2, s[12:13]
	global_load_dword v179, v[88:89], off
	global_load_dword v178, v[84:85], off
	global_load_dword v177, v[82:83], off
	global_load_dword v176, v[78:79], off
	global_load_dword v175, v[72:73], off
	global_load_dword v174, v[74:75], off
	global_load_dword v173, v[76:77], off
	global_load_dword v172, v[80:81], off
	v_lshl_add_u64 v[90:91], v[114:115], 2, s[12:13]
	global_load_dword v171, v[86:87], off
	global_load_dword v169, v[90:91], off
	v_lshl_add_u64 v[94:95], v[120:121], 2, s[12:13]
	v_lshl_add_u64 v[96:97], v[122:123], 2, s[12:13]
	v_lshl_add_u64 v[98:99], v[124:125], 2, s[12:13]
	global_load_dword v170, v[92:93], off
	global_load_dword v168, v[94:95], off
	global_load_dword v167, v[96:97], off
	global_load_dword v166, v[98:99], off
	global_load_dword v103, v[100:101], off
	global_load_dword v198, v[104:105], off
	v_lshl_add_u64 v[110:111], v[110:111], 1, s[8:9]
	v_lshl_add_u64 v[106:107], v[106:107], 1, s[8:9]
	global_load_dword v202, v[104:105], off offset:128
	global_load_dword v206, v[84:85], off offset:128
	global_load_dword v207, v[78:79], off offset:128
	global_load_dword v208, v[72:73], off offset:128
	global_load_dword v209, v[74:75], off offset:128
	global_load_dword v210, v[80:81], off offset:128
	global_load_dword v211, v[76:77], off offset:128
	global_load_dword v212, v[86:87], off offset:128
	global_load_dword v213, v[82:83], off offset:128
	global_load_dword v214, v[90:91], off offset:128
	global_load_dword v215, v[92:93], off offset:128
	global_load_dword v216, v[94:95], off offset:128
	global_load_dword v217, v[96:97], off offset:128
	global_load_dword v218, v[98:99], off offset:128
	global_load_dword v219, v[100:101], off offset:128
	global_load_dword v220, v[88:89], off offset:128
	global_load_dword v221, v[88:89], off offset:256
	global_load_dword v225, v[90:91], off offset:256
	global_load_dword v226, v[92:93], off offset:256
	global_load_dword v227, v[94:95], off offset:256
	global_load_dword v229, v[104:105], off offset:256
	global_load_dword v230, v[84:85], off offset:256
	global_load_dword v231, v[86:87], off offset:256
	global_load_dword v232, v[82:83], off offset:256
	global_load_dword v233, v[78:79], off offset:256
	global_load_dword v234, v[72:73], off offset:256
	global_load_dword v235, v[74:75], off offset:256
	global_load_dword v236, v[80:81], off offset:256
	global_load_dword v237, v[76:77], off offset:256
	global_load_dword v238, v[96:97], off offset:256
	global_load_dword v239, v[98:99], off offset:256
	global_load_dword v240, v[100:101], off offset:256
	s_waitcnt vmcnt(0)
	v_add_f32_e32 v197, 1.0, v197
	v_mul_f32_e32 v196, v196, v197
	v_fmac_f32_e32 v179, v49, v195
	v_fmac_f32_e32 v178, v50, v195
	v_fmac_f32_e32 v177, v51, v195
	v_fmac_f32_e32 v176, v52, v195
	v_fmac_f32_e32 v175, v53, v195
	v_fmac_f32_e32 v174, v54, v195
	v_fmac_f32_e32 v173, v55, v195
	v_fmac_f32_e32 v172, v56, v195
	v_fmac_f32_e32 v171, v57, v195
	v_fmac_f32_e32 v169, v58, v195
	v_fmac_f32_e32 v170, v59, v195
	v_fmac_f32_e32 v168, v60, v195
	v_fmac_f32_e32 v167, v61, v195
	v_fmac_f32_e32 v166, v62, v195
	v_fmac_f32_e32 v103, v63, v195
	v_fmac_f32_e32 v198, v48, v195
	v_mul_f32_e32 v48, v196, v198
	v_cvt_pk_bf16_f32 v58, v48, s0
	v_or_b32_e32 v48, 32, v102
	v_ashrrev_i32_e32 v49, 31, v48
	v_lshlrev_b64 v[52:53], 2, v[48:49]
	global_store_dword v[88:89], v179, off sc1
	global_store_dword v[84:85], v178, off sc1
	global_store_dword v[82:83], v177, off sc1
	global_store_dword v[78:79], v176, off sc1
	global_store_dword v[72:73], v175, off sc1
	global_store_dword v[74:75], v174, off sc1
	global_store_dword v[76:77], v173, off sc1
	global_store_dword v[80:81], v172, off sc1
	global_store_dword v[86:87], v171, off sc1
	global_store_dword v[90:91], v169, off sc1
	global_store_dword v[92:93], v170, off sc1
	global_store_dword v[94:95], v168, off sc1
	global_store_dword v[96:97], v167, off sc1
	global_store_dword v[98:99], v166, off sc1
	global_store_dword v[100:101], v103, off sc1
	global_store_dword v[104:105], v198, off sc1
	v_lshl_add_u64 v[50:51], v[130:131], 1, s[8:9]
	v_lshl_add_u64 v[56:57], s[64:65], 0, v[52:53]
	v_mov_b32_e32 v197, v202
	v_lshl_add_u64 v[54:55], s[62:63], 0, v[52:53]
	v_mov_b32_e32 v130, v203
	v_mov_b32_e32 v131, v204
	v_mul_f32_e32 v49, v196, v179
	global_store_short v[50:51], v58, off sc1
	v_lshl_add_u64 v[50:51], s[60:61], 0, v[52:53]
	v_mov_b32_e32 v195, v205
	v_lshl_add_u64 v[50:51], v[132:133], 1, s[8:9]
	v_cvt_pk_bf16_f32 v49, v49, s0
	global_store_short v[50:51], v49, off sc1
	v_mul_f32_e32 v49, v196, v178
	v_lshl_add_u64 v[50:51], v[134:135], 1, s[8:9]
	v_cvt_pk_bf16_f32 v49, v49, s0
	global_store_short v[50:51], v49, off sc1
	v_mul_f32_e32 v49, v196, v177
	v_lshl_add_u64 v[50:51], v[136:137], 1, s[8:9]
	v_cvt_pk_bf16_f32 v49, v49, s0
	global_store_short v[50:51], v49, off sc1
	v_mul_f32_e32 v49, v196, v176
	v_lshl_add_u64 v[50:51], v[126:127], 1, s[8:9]
	v_cvt_pk_bf16_f32 v49, v49, s0
	global_store_short v[50:51], v49, off sc1
	v_mul_f32_e32 v49, v196, v175
	v_lshl_add_u64 v[50:51], v[118:119], 1, s[8:9]
	v_cvt_pk_bf16_f32 v49, v49, s0
	v_mov_b32_e32 v62, v206
	v_mov_b32_e32 v60, v207
	v_mov_b32_e32 v59, v208
	v_mov_b32_e32 v58, v209
	v_mov_b32_e32 v56, v210
	v_mov_b32_e32 v57, v211
	v_mov_b32_e32 v55, v212
	v_mov_b32_e32 v61, v213
	v_mov_b32_e32 v54, v214
	v_mov_b32_e32 v53, v215
	v_mov_b32_e32 v52, v216
	v_mul_f32_e32 v63, v196, v174
	global_store_short v[50:51], v49, off sc1
	v_mov_b32_e32 v51, v217
	v_cvt_pk_bf16_f32 v63, v63, s0
	v_mov_b32_e32 v50, v218
	v_mov_b32_e32 v49, v219
	v_fmac_f32_e32 v197, v32, v195
	global_store_short v[110:111], v63, off sc1
	v_mov_b32_e32 v63, v220
	v_mul_f32_e32 v110, v196, v173
	v_cvt_pk_bf16_f32 v110, v110, s0
	global_store_short v[106:107], v110, off sc1
	v_lshl_add_u64 v[106:107], v[108:109], 1, s[8:9]
	v_mul_f32_e32 v108, v196, v172
	v_cvt_pk_bf16_f32 v108, v108, s0
	global_store_short v[106:107], v108, off sc1
	v_mul_f32_e32 v108, v196, v171
	v_lshl_add_u64 v[106:107], v[112:113], 1, s[8:9]
	v_cvt_pk_bf16_f32 v108, v108, s0
	global_store_short v[106:107], v108, off sc1
	v_mul_f32_e32 v108, v196, v169
	v_lshl_add_u64 v[106:107], v[114:115], 1, s[8:9]
	v_cvt_pk_bf16_f32 v108, v108, s0
	global_store_short v[106:107], v108, off sc1
	v_mul_f32_e32 v108, v196, v170
	v_lshl_add_u64 v[106:107], v[116:117], 1, s[8:9]
	v_cvt_pk_bf16_f32 v108, v108, s0
	global_store_short v[106:107], v108, off sc1
	v_mul_f32_e32 v108, v196, v168
	v_lshl_add_u64 v[106:107], v[120:121], 1, s[8:9]
	v_cvt_pk_bf16_f32 v108, v108, s0
	global_store_short v[106:107], v108, off sc1
	v_mul_f32_e32 v108, v196, v167
	v_lshl_add_u64 v[106:107], v[122:123], 1, s[8:9]
	v_cvt_pk_bf16_f32 v108, v108, s0
	global_store_short v[106:107], v108, off sc1
	v_mul_f32_e32 v108, v196, v166
	v_lshl_add_u64 v[106:107], v[124:125], 1, s[8:9]
	v_cvt_pk_bf16_f32 v108, v108, s0
	global_store_short v[106:107], v108, off sc1
	v_mul_f32_e32 v108, v196, v103
	v_lshl_add_u64 v[106:107], v[128:129], 1, s[8:9]
	v_cvt_pk_bf16_f32 v108, v108, s0
	global_store_short v[106:107], v108, off sc1
	v_add_f32_e32 v106, 1.0, v130
	v_mul_f32_e32 v107, v131, v106
	v_add_u32_e32 v108, v191, v48
	v_ashrrev_i32_e32 v109, 31, v108
	v_mul_f32_e32 v32, v107, v197
	v_fmac_f32_e32 v62, v34, v195
	v_fmac_f32_e32 v61, v35, v195
	v_fmac_f32_e32 v60, v36, v195
	v_fmac_f32_e32 v59, v37, v195
	v_fmac_f32_e32 v58, v38, v195
	v_fmac_f32_e32 v57, v39, v195
	v_fmac_f32_e32 v56, v40, v195
	v_fmac_f32_e32 v55, v41, v195
	v_fmac_f32_e32 v54, v42, v195
	v_fmac_f32_e32 v53, v43, v195
	v_fmac_f32_e32 v52, v44, v195
	v_fmac_f32_e32 v51, v45, v195
	v_fmac_f32_e32 v50, v46, v195
	v_fmac_f32_e32 v49, v47, v195
	global_store_dword v[104:105], v197, off offset:128 sc1
	v_lshl_add_u64 v[108:109], v[108:109], 1, s[8:9]
	v_cvt_pk_bf16_f32 v32, v32, s0
	global_store_dword v[84:85], v62, off offset:128 sc1
	global_store_dword v[82:83], v61, off offset:128 sc1
	global_store_dword v[78:79], v60, off offset:128 sc1
	global_store_dword v[72:73], v59, off offset:128 sc1
	global_store_dword v[74:75], v58, off offset:128 sc1
	global_store_dword v[76:77], v57, off offset:128 sc1
	global_store_dword v[80:81], v56, off offset:128 sc1
	global_store_dword v[86:87], v55, off offset:128 sc1
	global_store_dword v[90:91], v54, off offset:128 sc1
	global_store_dword v[92:93], v53, off offset:128 sc1
	global_store_dword v[94:95], v52, off offset:128 sc1
	global_store_dword v[96:97], v51, off offset:128 sc1
	global_store_dword v[98:99], v50, off offset:128 sc1
	global_store_dword v[100:101], v49, off offset:128 sc1
	global_store_short v[108:109], v32, off sc1
	v_add_u32_e32 v108, v187, v48
	v_mov_b32_e32 v45, v221
	v_ashrrev_i32_e32 v109, 31, v108
	v_mul_f32_e32 v113, v107, v56
	v_cvt_pk_bf16_f32 v113, v113, s0
	v_mul_f32_e32 v106, v197, v197
	v_fmac_f32_e32 v106, v198, v198
	v_fmac_f32_e32 v63, v33, v195
	v_mul_f32_e32 v34, v107, v63
	v_lshl_add_u64 v[32:33], v[108:109], 1, s[8:9]
	v_cvt_pk_bf16_f32 v34, v34, s0
	global_store_short v[32:33], v34, off sc1
	v_add_u32_e32 v32, v185, v48
	v_ashrrev_i32_e32 v33, 31, v32
	v_mul_f32_e32 v34, v107, v62
	v_lshl_add_u64 v[32:33], v[32:33], 1, s[8:9]
	v_cvt_pk_bf16_f32 v34, v34, s0
	global_store_short v[32:33], v34, off sc1
	v_add_u32_e32 v32, v184, v48
	v_ashrrev_i32_e32 v33, 31, v32
	v_mul_f32_e32 v34, v107, v61
	v_lshl_add_u64 v[32:33], v[32:33], 1, s[8:9]
	v_cvt_pk_bf16_f32 v34, v34, s0
	global_store_short v[32:33], v34, off sc1
	v_add_u32_e32 v32, v182, v48
	v_ashrrev_i32_e32 v33, 31, v32
	v_mul_f32_e32 v34, v107, v60
	v_lshl_add_u64 v[32:33], v[32:33], 1, s[8:9]
	v_cvt_pk_bf16_f32 v34, v34, s0
	global_store_short v[32:33], v34, off sc1
	v_add_u32_e32 v32, v180, v48
	v_ashrrev_i32_e32 v33, 31, v32
	v_lshl_add_u64 v[34:35], v[32:33], 1, s[8:9]
	v_mul_f32_e32 v32, v107, v59
	v_cvt_pk_bf16_f32 v42, v32, s0
	v_or_b32_e32 v32, 64, v102
	v_ashrrev_i32_e32 v33, 31, v32
	v_lshlrev_b64 v[36:37], 2, v[32:33]
	global_store_dword v[88:89], v63, off offset:128 sc1
	v_lshl_add_u64 v[40:41], s[64:65], 0, v[36:37]
	v_lshl_add_u64 v[38:39], s[62:63], 0, v[36:37]
	v_mov_b32_e32 v110, v222
	v_mov_b32_e32 v111, v223
	v_mul_f32_e32 v33, v107, v58
	global_store_short v[34:35], v42, off sc1
	v_lshl_add_u64 v[34:35], s[60:61], 0, v[36:37]
	v_mov_b32_e32 v112, v224
	v_add_u32_e32 v34, v71, v48
	v_ashrrev_i32_e32 v35, 31, v34
	v_lshl_add_u64 v[34:35], v[34:35], 1, s[8:9]
	v_cvt_pk_bf16_f32 v33, v33, s0
	global_store_short v[34:35], v33, off sc1
	v_add_u32_e32 v34, v181, v48
	v_ashrrev_i32_e32 v35, 31, v34
	v_mul_f32_e32 v33, v107, v57
	v_lshl_add_u64 v[34:35], v[34:35], 1, s[8:9]
	v_cvt_pk_bf16_f32 v33, v33, s0
	v_mov_b32_e32 v38, v225
	v_mov_b32_e32 v37, v226
	v_mov_b32_e32 v36, v227
	v_mov_b32_e32 v114, v229
	v_mov_b32_e32 v47, v230
	v_mov_b32_e32 v39, v231
	v_mov_b32_e32 v46, v232
	v_mov_b32_e32 v44, v233
	v_mov_b32_e32 v43, v234
	v_mov_b32_e32 v42, v235
	v_mov_b32_e32 v40, v236
	v_mov_b32_e32 v41, v237
	v_add_u32_e32 v108, v183, v48
	global_store_short v[34:35], v33, off sc1
	v_mov_b32_e32 v35, v238
	v_ashrrev_i32_e32 v109, 31, v108
	v_mov_b32_e32 v34, v239
	v_mov_b32_e32 v33, v240
	v_lshl_add_u64 v[108:109], v[108:109], 1, s[8:9]
	global_store_short v[108:109], v113, off sc1
	v_add_u32_e32 v108, v186, v48
	v_ashrrev_i32_e32 v109, 31, v108
	v_mul_f32_e32 v113, v107, v55
	v_lshl_add_u64 v[108:109], v[108:109], 1, s[8:9]
	v_cvt_pk_bf16_f32 v113, v113, s0
	global_store_short v[108:109], v113, off sc1
	v_add_u32_e32 v108, v188, v48
	v_ashrrev_i32_e32 v109, 31, v108
	v_mul_f32_e32 v113, v107, v54
	v_lshl_add_u64 v[108:109], v[108:109], 1, s[8:9]
	v_cvt_pk_bf16_f32 v113, v113, s0
	global_store_short v[108:109], v113, off sc1
	v_add_u32_e32 v108, v189, v48
	v_ashrrev_i32_e32 v109, 31, v108
	v_mul_f32_e32 v113, v107, v53
	v_lshl_add_u64 v[108:109], v[108:109], 1, s[8:9]
	v_cvt_pk_bf16_f32 v113, v113, s0
	global_store_short v[108:109], v113, off sc1
	v_add_u32_e32 v108, v190, v48
	v_ashrrev_i32_e32 v109, 31, v108
	v_mul_f32_e32 v113, v107, v52
	v_lshl_add_u64 v[108:109], v[108:109], 1, s[8:9]
	v_cvt_pk_bf16_f32 v113, v113, s0
	global_store_short v[108:109], v113, off sc1
	v_add_u32_e32 v108, v192, v48
	v_ashrrev_i32_e32 v109, 31, v108
	v_mul_f32_e32 v113, v107, v51
	v_lshl_add_u64 v[108:109], v[108:109], 1, s[8:9]
	v_cvt_pk_bf16_f32 v113, v113, s0
	global_store_short v[108:109], v113, off sc1
	v_add_u32_e32 v108, v193, v48
	v_ashrrev_i32_e32 v109, 31, v108
	v_mul_f32_e32 v113, v107, v50
	v_lshl_add_u64 v[108:109], v[108:109], 1, s[8:9]
	v_cvt_pk_bf16_f32 v113, v113, s0
	global_store_short v[108:109], v113, off sc1
	v_add_u32_e32 v108, v194, v48
	v_ashrrev_i32_e32 v109, 31, v108
	v_mul_f32_e32 v48, v107, v49
	v_lshl_add_u64 v[108:109], v[108:109], 1, s[8:9]
	v_cvt_pk_bf16_f32 v48, v48, s0
	global_store_short v[108:109], v48, off sc1
	v_add_u32_e32 v108, v191, v32
	v_ashrrev_i32_e32 v109, 31, v108
	v_add_f32_e32 v48, 1.0, v110
	v_mul_f32_e32 v48, v111, v48
	v_fmac_f32_e32 v45, v17, v112
	global_store_dword v[88:89], v45, off offset:256 sc1
	v_fmac_f32_e32 v38, v26, v112
	v_fmac_f32_e32 v37, v27, v112
	v_fmac_f32_e32 v36, v28, v112
	v_fmac_f32_e32 v114, v16, v112
	v_fmac_f32_e32 v47, v18, v112
	v_mul_f32_e32 v18, v48, v114
	v_lshl_add_u64 v[16:17], v[108:109], 1, s[8:9]
	v_cvt_pk_bf16_f32 v18, v18, s0
	global_store_short v[16:17], v18, off sc1
	v_add_u32_e32 v16, v187, v32
	v_ashrrev_i32_e32 v17, 31, v16
	v_mul_f32_e32 v18, v48, v45
	v_lshl_add_u64 v[16:17], v[16:17], 1, s[8:9]
	v_cvt_pk_bf16_f32 v18, v18, s0
	global_store_short v[16:17], v18, off sc1
	v_add_u32_e32 v16, v185, v32
	v_ashrrev_i32_e32 v17, 31, v16
	v_mul_f32_e32 v18, v48, v47
	v_lshl_add_u64 v[16:17], v[16:17], 1, s[8:9]
	v_cvt_pk_bf16_f32 v18, v18, s0
	v_fmac_f32_e32 v46, v19, v112
	global_store_short v[16:17], v18, off sc1
	v_add_u32_e32 v16, v184, v32
	v_ashrrev_i32_e32 v17, 31, v16
	v_mul_f32_e32 v18, v48, v46
	v_lshl_add_u64 v[16:17], v[16:17], 1, s[8:9]
	v_cvt_pk_bf16_f32 v18, v18, s0
	global_store_short v[16:17], v18, off sc1
	v_add_u32_e32 v16, v182, v32
	v_ashrrev_i32_e32 v17, 31, v16
	v_lshl_add_u64 v[18:19], v[16:17], 1, s[8:9]
	v_or_b32_e32 v16, 0x60, v102
	v_ashrrev_i32_e32 v17, 31, v16
	v_fmac_f32_e32 v44, v20, v112
	v_fmac_f32_e32 v43, v21, v112
	v_fmac_f32_e32 v42, v22, v112
	v_fmac_f32_e32 v41, v23, v112
	v_fmac_f32_e32 v40, v24, v112
	v_fmac_f32_e32 v39, v25, v112
	v_fmac_f32_e32 v35, v29, v112
	v_fmac_f32_e32 v34, v30, v112
	v_fmac_f32_e32 v33, v31, v112
	v_lshlrev_b64 v[20:21], 2, v[16:17]
	global_store_dword v[84:85], v47, off offset:256 sc1
	global_store_dword v[82:83], v46, off offset:256 sc1
	global_store_dword v[78:79], v44, off offset:256 sc1
	global_store_dword v[72:73], v43, off offset:256 sc1
	global_store_dword v[74:75], v42, off offset:256 sc1
	global_store_dword v[76:77], v41, off offset:256 sc1
	global_store_dword v[80:81], v40, off offset:256 sc1
	global_store_dword v[86:87], v39, off offset:256 sc1
	global_store_dword v[90:91], v38, off offset:256 sc1
	global_store_dword v[92:93], v37, off offset:256 sc1
	global_store_dword v[94:95], v36, off offset:256 sc1
	global_store_dword v[96:97], v35, off offset:256 sc1
	global_store_dword v[98:99], v34, off offset:256 sc1
	global_store_dword v[100:101], v33, off offset:256 sc1
	global_store_dword v[104:105], v114, off offset:256 sc1
	v_mul_f32_e32 v26, v48, v44
	v_lshl_add_u64 v[22:23], s[62:63], 0, v[20:21]
	v_lshl_add_u64 v[24:25], s[64:65], 0, v[20:21]
	global_load_dword v29, v[104:105], off offset:384
	global_load_dword v17, v[24:25], off
	global_load_dword v30, v[22:23], off
	v_cvt_pk_bf16_f32 v22, v26, s0
	global_store_short v[18:19], v22, off sc1
	v_lshl_add_u64 v[18:19], s[60:61], 0, v[20:21]
	global_load_dword v102, v[18:19], off
	v_add_u32_e32 v18, v180, v32
	v_ashrrev_i32_e32 v19, 31, v18
	v_mul_f32_e32 v20, v48, v43
	v_lshl_add_u64 v[18:19], v[18:19], 1, s[8:9]
	v_cvt_pk_bf16_f32 v20, v20, s0
	global_store_short v[18:19], v20, off sc1
	v_add_u32_e32 v18, v71, v32
	v_ashrrev_i32_e32 v19, 31, v18
	v_mul_f32_e32 v20, v48, v42
	v_lshl_add_u64 v[18:19], v[18:19], 1, s[8:9]
	v_cvt_pk_bf16_f32 v20, v20, s0
	global_store_short v[18:19], v20, off sc1
	v_add_u32_e32 v18, v181, v32
	v_ashrrev_i32_e32 v19, 31, v18
	v_mul_f32_e32 v20, v48, v41
	v_lshl_add_u64 v[18:19], v[18:19], 1, s[8:9]
	v_cvt_pk_bf16_f32 v20, v20, s0
	global_store_short v[18:19], v20, off sc1
	v_add_u32_e32 v18, v183, v32
	v_ashrrev_i32_e32 v19, 31, v18
	v_mul_f32_e32 v20, v48, v40
	v_lshl_add_u64 v[18:19], v[18:19], 1, s[8:9]
	v_cvt_pk_bf16_f32 v20, v20, s0
	global_store_short v[18:19], v20, off sc1
	v_add_u32_e32 v18, v186, v32
	v_ashrrev_i32_e32 v19, 31, v18
	v_mul_f32_e32 v20, v48, v39
	v_lshl_add_u64 v[18:19], v[18:19], 1, s[8:9]
	v_cvt_pk_bf16_f32 v20, v20, s0
	global_store_short v[18:19], v20, off sc1
	v_add_u32_e32 v18, v188, v32
	v_ashrrev_i32_e32 v19, 31, v18
	v_mul_f32_e32 v20, v48, v38
	v_lshl_add_u64 v[18:19], v[18:19], 1, s[8:9]
	v_cvt_pk_bf16_f32 v20, v20, s0
	global_store_short v[18:19], v20, off sc1
	v_add_u32_e32 v18, v189, v32
	v_ashrrev_i32_e32 v19, 31, v18
	v_mul_f32_e32 v20, v48, v37
	v_lshl_add_u64 v[18:19], v[18:19], 1, s[8:9]
	v_cvt_pk_bf16_f32 v20, v20, s0
	global_store_short v[18:19], v20, off sc1
	v_add_u32_e32 v18, v190, v32
	v_ashrrev_i32_e32 v19, 31, v18
	v_mul_f32_e32 v20, v48, v36
	v_lshl_add_u64 v[18:19], v[18:19], 1, s[8:9]
	v_cvt_pk_bf16_f32 v20, v20, s0
	global_store_short v[18:19], v20, off sc1
	v_add_u32_e32 v18, v192, v32
	v_ashrrev_i32_e32 v19, 31, v18
	v_mul_f32_e32 v20, v48, v35
	v_lshl_add_u64 v[18:19], v[18:19], 1, s[8:9]
	v_cvt_pk_bf16_f32 v20, v20, s0
	global_load_dword v28, v[88:89], off offset:384
	global_load_dword v27, v[84:85], off offset:384
	global_load_dword v25, v[78:79], off offset:384
	global_load_dword v24, v[72:73], off offset:384
	global_load_dword v23, v[74:75], off offset:384
	global_load_dword v21, v[80:81], off offset:384
	global_load_dword v22, v[76:77], off offset:384
	v_fmac_f32_e32 v106, v114, v114
	global_store_short v[18:19], v20, off sc1
	v_add_u32_e32 v18, v193, v32
	v_ashrrev_i32_e32 v19, 31, v18
	v_mul_f32_e32 v20, v48, v34
	v_lshl_add_u64 v[18:19], v[18:19], 1, s[8:9]
	v_cvt_pk_bf16_f32 v20, v20, s0
	global_store_short v[18:19], v20, off sc1
	v_add_u32_e32 v18, v194, v32
	v_ashrrev_i32_e32 v19, 31, v18
	v_mul_f32_e32 v20, v48, v33
	v_lshl_add_u64 v[18:19], v[18:19], 1, s[8:9]
	v_cvt_pk_bf16_f32 v20, v20, s0
	global_store_short v[18:19], v20, off sc1
	global_load_dword v20, v[86:87], off offset:384
	s_waitcnt vmcnt(22)
	v_add_f32_e32 v17, 1.0, v17
	global_load_dword v26, v[82:83], off offset:384
	s_waitcnt vmcnt(22)
	v_mul_f32_e32 v32, v30, v17
	v_add_u32_e32 v18, v191, v16
	s_waitcnt vmcnt(20)
	v_fmac_f32_e32 v29, v0, v102
	v_ashrrev_i32_e32 v19, 31, v18
	v_mul_f32_e32 v0, v32, v29
	v_lshl_add_u64 v[18:19], v[18:19], 1, s[8:9]
	v_cvt_pk_bf16_f32 v0, v0, s0
	global_store_short v[18:19], v0, off sc1
	global_load_dword v19, v[90:91], off offset:384
	v_add_u32_e32 v30, v187, v16
	global_load_dword v18, v[92:93], off offset:384
	v_ashrrev_i32_e32 v31, 31, v30
	v_fmac_f32_e32 v106, v29, v29
	global_store_dword v[104:105], v29, off offset:384 sc1
	s_waitcnt vmcnt(15)
	v_fmac_f32_e32 v28, v1, v102
	v_mul_f32_e32 v17, v32, v28
	v_lshl_add_u64 v[0:1], v[30:31], 1, s[8:9]
	v_cvt_pk_bf16_f32 v17, v17, s0
	global_store_short v[0:1], v17, off sc1
	v_add_u32_e32 v0, v185, v16
	s_waitcnt vmcnt(15)
	v_fmac_f32_e32 v27, v2, v102
	global_load_dword v17, v[94:95], off offset:384
	v_ashrrev_i32_e32 v1, 31, v0
	v_mul_f32_e32 v2, v32, v27
	v_lshl_add_u64 v[0:1], v[0:1], 1, s[8:9]
	v_cvt_pk_bf16_f32 v2, v2, s0
	global_store_short v[0:1], v2, off sc1
	v_add_u32_e32 v0, v184, v16
	global_load_dword v2, v[96:97], off offset:384
	v_ashrrev_i32_e32 v1, 31, v0
	v_lshl_add_u64 v[0:1], v[0:1], 1, s[8:9]
	v_add_u32_e32 v30, v182, v16
	s_waitcnt vmcnt(17)
	v_fmac_f32_e32 v25, v4, v102
	v_ashrrev_i32_e32 v31, 31, v30
	v_lshl_add_u64 v[30:31], v[30:31], 1, s[8:9]
	s_waitcnt vmcnt(16)
	v_fmac_f32_e32 v24, v5, v102
	s_waitcnt vmcnt(15)
	v_fmac_f32_e32 v23, v6, v102
	s_waitcnt vmcnt(8)
	v_fmac_f32_e32 v26, v3, v102
	v_mul_f32_e32 v3, v32, v26
	v_cvt_pk_bf16_f32 v3, v3, s0
	global_store_short v[0:1], v3, off sc1
	global_load_dword v1, v[98:99], off offset:384
	v_mul_f32_e32 v0, v32, v25
	v_cvt_pk_bf16_f32 v0, v0, s0
	global_store_short v[30:31], v0, off sc1
	global_load_dword v0, v[100:101], off offset:384
	v_add_u32_e32 v30, v180, v16
	v_ashrrev_i32_e32 v31, 31, v30
	v_mul_f32_e32 v3, v32, v24
	v_lshl_add_u64 v[4:5], v[30:31], 1, s[8:9]
	v_cvt_pk_bf16_f32 v3, v3, s0
	global_store_short v[4:5], v3, off sc1
	v_add_u32_e32 v4, v71, v16
	v_ashrrev_i32_e32 v5, 31, v4
	v_mul_f32_e32 v3, v32, v23
	v_lshl_add_u64 v[4:5], v[4:5], 1, s[8:9]
	v_cvt_pk_bf16_f32 v3, v3, s0
	global_store_short v[4:5], v3, off sc1
	v_add_u32_e32 v4, v181, v16
	v_fmac_f32_e32 v22, v7, v102
	v_ashrrev_i32_e32 v5, 31, v4
	v_mul_f32_e32 v3, v32, v22
	v_lshl_add_u64 v[4:5], v[4:5], 1, s[8:9]
	v_cvt_pk_bf16_f32 v3, v3, s0
	global_store_short v[4:5], v3, off sc1
	v_add_u32_e32 v4, v183, v16
	v_fmac_f32_e32 v21, v8, v102
	v_ashrrev_i32_e32 v5, 31, v4
	v_mul_f32_e32 v3, v32, v21
	v_lshl_add_u64 v[4:5], v[4:5], 1, s[8:9]
	v_cvt_pk_bf16_f32 v3, v3, s0
	global_store_short v[4:5], v3, off sc1
	v_add_u32_e32 v4, v186, v16
	v_fmac_f32_e32 v20, v9, v102
	v_ashrrev_i32_e32 v5, 31, v4
	v_mul_f32_e32 v3, v32, v20
	v_lshl_add_u64 v[4:5], v[4:5], 1, s[8:9]
	v_cvt_pk_bf16_f32 v3, v3, s0
	global_store_short v[4:5], v3, off sc1
	v_add_u32_e32 v4, v188, v16
	s_waitcnt vmcnt(15)
	v_fmac_f32_e32 v19, v10, v102
	v_ashrrev_i32_e32 v5, 31, v4
	v_mul_f32_e32 v3, v32, v19
	v_lshl_add_u64 v[4:5], v[4:5], 1, s[8:9]
	v_cvt_pk_bf16_f32 v3, v3, s0
	global_store_short v[4:5], v3, off sc1
	v_add_u32_e32 v4, v189, v16
	s_waitcnt vmcnt(15)
	v_fmac_f32_e32 v18, v11, v102
	v_ashrrev_i32_e32 v5, 31, v4
	v_mul_f32_e32 v3, v32, v18
	v_lshl_add_u64 v[4:5], v[4:5], 1, s[8:9]
	v_cvt_pk_bf16_f32 v3, v3, s0
	global_store_short v[4:5], v3, off sc1
	v_add_u32_e32 v4, v190, v16
	v_ashrrev_i32_e32 v5, 31, v4
	v_lshl_add_u64 v[4:5], v[4:5], 1, s[8:9]
	v_ashrrev_i32_e32 v71, 31, v70
	global_store_dword v[88:89], v28, off offset:384 sc1
	global_store_dword v[84:85], v27, off offset:384 sc1
	global_store_dword v[82:83], v26, off offset:384 sc1
	global_store_dword v[78:79], v25, off offset:384 sc1
	s_waitcnt vmcnt(17)
	v_fmac_f32_e32 v17, v12, v102
	v_mul_f32_e32 v3, v32, v17
	v_cvt_pk_bf16_f32 v3, v3, s0
	global_store_short v[4:5], v3, off sc1
	v_add_u32_e32 v4, v192, v16
	v_ashrrev_i32_e32 v5, 31, v4
	v_lshl_add_u64 v[4:5], v[4:5], 1, s[8:9]
	s_waitcnt vmcnt(16)
	v_fmac_f32_e32 v2, v13, v102
	v_mul_f32_e32 v3, v32, v2
	v_cvt_pk_bf16_f32 v3, v3, s0
	global_store_short v[4:5], v3, off sc1
	v_add_u32_e32 v4, v193, v16
	v_ashrrev_i32_e32 v5, 31, v4
	v_lshl_add_u64 v[4:5], v[4:5], 1, s[8:9]
	v_xor_b32_e32 v12, 16, v165
	global_store_dword v[72:73], v24, off offset:384 sc1
	global_store_dword v[74:75], v23, off offset:384 sc1
	global_store_dword v[76:77], v22, off offset:384 sc1
	global_store_dword v[80:81], v21, off offset:384 sc1
	global_store_dword v[86:87], v20, off offset:384 sc1
	s_waitcnt vmcnt(20)
	v_fmac_f32_e32 v1, v14, v102
	v_mul_f32_e32 v3, v32, v1
	v_cvt_pk_bf16_f32 v3, v3, s0
	global_store_short v[4:5], v3, off sc1
	v_add_u32_e32 v4, v194, v16
	v_ashrrev_i32_e32 v5, 31, v4
	v_lshl_add_u64 v[10:11], v[4:5], 1, s[8:9]
	v_and_b32_e32 v4, 64, v165
	v_xor_b32_e32 v3, 1, v165
	v_add_u32_e32 v7, 64, v4
	v_cmp_lt_i32_e32 vcc, v3, v7
	v_xor_b32_e32 v4, 2, v165
	s_waitcnt vmcnt(19)
	v_fmac_f32_e32 v0, v15, v102
	v_cndmask_b32_e32 v3, v165, v3, vcc
	v_lshlrev_b32_e32 v3, 2, v3
	v_cmp_lt_i32_e32 vcc, v4, v7
	global_store_dword v[90:91], v19, off offset:384 sc1
	global_store_dword v[92:93], v18, off offset:384 sc1
	v_cndmask_b32_e32 v4, v165, v4, vcc
	v_lshlrev_b32_e32 v4, 2, v4
	v_add_f32_dpp v6, v106, v106 quad_perm:[1,0,3,2] row_mask:0xf bank_mask:0xf
	v_xor_b32_e32 v5, 4, v165
	v_cmp_lt_i32_e32 vcc, v5, v7
	global_store_dword v[94:95], v17, off offset:384 sc1
	global_store_dword v[96:97], v2, off offset:384 sc1
	v_cndmask_b32_e32 v5, v165, v5, vcc
	v_lshlrev_b32_e32 v5, 2, v5
	v_add_f32_dpp v8, v6, v6 quad_perm:[2,3,0,1] row_mask:0xf bank_mask:0xf
	v_xor_b32_e32 v6, 8, v165
	v_cmp_lt_i32_e32 vcc, v6, v7
	global_store_dword v[98:99], v1, off offset:384 sc1
	global_store_dword v[100:101], v0, off offset:384 sc1
	v_cndmask_b32_e32 v6, v165, v6, vcc
	v_lshlrev_b32_e32 v6, 2, v6
	v_add_f32_dpp v8, v8, v8 row_half_mirror row_mask:0xf bank_mask:0xf
	v_cmp_lt_i32_e32 vcc, v12, v7
	v_add_f32_dpp v8, v8, v8 row_mirror row_mask:0xf bank_mask:0xf
	v_cndmask_b32_e32 v7, v165, v12, vcc
	v_lshlrev_b32_e32 v7, 2, v7
	ds_bpermute_b32 v9, v7, v8
	v_mul_f32_e32 v12, v32, v0
	v_cvt_pk_bf16_f32 v12, v12, s0
	global_store_short v[10:11], v12, off sc1
	s_and_saveexec_b64 s[60:61], s[0:1]
	s_cbranch_execz .LBB0_1400
	s_waitcnt lgkmcnt(0)
	v_add_f32_e32 v10, v8, v9
	v_lshl_add_u64 v[8:9], v[70:71], 2, s[58:59]
	global_store_dword v[8:9], v10, off sc1

.LBB0_1569:
	s_add_i32 s58, s66, 0xffffe000
	s_lshr_b32 s58, s58, 12
	s_mulk_i32 s58, 0x1800
	v_mov_b32_e32 v70, s70
	s_add_i32 s58, s58, 0xf000
	ds_read_b64 v[70:71], v70
	s_cmp_gt_i32 s6, 63
	s_cselect_b32 s6, s58, 0xd800
	s_lshl_b64 s[58:59], s[6:7], 2
	s_add_u32 s6, s14, s58
	s_addc_u32 s65, s15, s59
	s_waitcnt lgkmcnt(0)
	v_readfirstlane_b32 s58, v70
	v_readfirstlane_b32 s59, v71
	s_add_u32 s60, s58, 0x3000
	s_addc_u32 s61, s59, 0
	s_lshl_b32 s58, s64, 14
	s_add_i32 s58, s58, 0xe0000
	s_ashr_i32 s59, s58, 31
	s_lshl_b64 s[58:59], s[58:59], 2
	s_add_u32 s58, s10, s58
	s_addc_u32 s59, s11, s59
	s_add_u32 s62, s6, 0x5ba2000
	v_or_b32_e32 v102, s68, v138
	v_add_u32_e32 v70, s66, v139
	s_addc_u32 s63, s65, 0
	v_lshlrev_b32_e32 v188, 10, v70
	v_ashrrev_i32_e32 v103, 31, v102
	s_add_u32 s64, s6, 0x5ba4000
	v_lshlrev_b64 v[72:73], 2, v[102:103]
	v_or_b32_e32 v186, 0x400, v188
	v_or_b32_e32 v185, 0x4400, v188
	v_or_b32_e32 v189, 0x4c00, v188
	v_or_b32_e32 v193, 0x6c00, v188
	s_addc_u32 s65, s65, 0
	v_lshl_add_u64 v[74:75], s[62:63], 0, v[72:73]
	v_add_u32_e32 v132, v188, v102
	v_add_u32_e32 v134, v186, v102
	v_or_b32_e32 v184, 0x800, v188
	v_or_b32_e32 v183, 0xc00, v188
	v_or_b32_e32 v181, 0x2000, v188
	v_or_b32_e32 v179, 0x2400, v188
	v_or_b32_e32 v71, 0x2800, v188
	v_or_b32_e32 v180, 0x2c00, v188
	v_or_b32_e32 v182, 0x4000, v188
	v_add_u32_e32 v112, v185, v102
	v_or_b32_e32 v187, 0x4800, v188
	v_add_u32_e32 v118, v189, v102
	v_or_b32_e32 v190, 0x6000, v188
	v_or_b32_e32 v191, 0x6400, v188
	v_or_b32_e32 v192, 0x6800, v188
	v_add_u32_e32 v128, v193, v102
	global_load_dword v194, v[74:75], off
	global_load_dword v204, v[74:75], off offset:128
	global_load_dword v223, v[74:75], off offset:256
	v_lshl_add_u64 v[74:75], s[60:61], 0, v[72:73]
	v_lshl_add_u64 v[72:73], s[64:65], 0, v[72:73]
	v_ashrrev_i32_e32 v135, 31, v134
	v_add_u32_e32 v136, v184, v102
	v_add_u32_e32 v130, v183, v102
	v_add_u32_e32 v122, v181, v102
	v_add_u32_e32 v114, v179, v102
	v_add_u32_e32 v106, v71, v102
	v_add_u32_e32 v108, v180, v102
	v_add_u32_e32 v110, v182, v102
	v_ashrrev_i32_e32 v113, 31, v112
	v_add_u32_e32 v116, v187, v102
	v_ashrrev_i32_e32 v119, 31, v118
	v_add_u32_e32 v120, v190, v102
	v_add_u32_e32 v124, v191, v102
	v_add_u32_e32 v126, v192, v102
	v_ashrrev_i32_e32 v129, 31, v128
	v_ashrrev_i32_e32 v133, 31, v132
	global_load_dword v196, v[72:73], off
	global_load_dword v202, v[72:73], off offset:128
	global_load_dword v221, v[72:73], off offset:256
	v_lshl_add_u64 v[88:89], v[134:135], 2, s[12:13]
	v_ashrrev_i32_e32 v137, 31, v136
	v_ashrrev_i32_e32 v131, 31, v130
	v_ashrrev_i32_e32 v123, 31, v122
	v_ashrrev_i32_e32 v115, 31, v114
	v_ashrrev_i32_e32 v107, 31, v106
	v_ashrrev_i32_e32 v109, 31, v108
	v_ashrrev_i32_e32 v111, 31, v110
	v_lshl_add_u64 v[86:87], v[112:113], 2, s[12:13]
	v_ashrrev_i32_e32 v117, 31, v116
	v_lshl_add_u64 v[92:93], v[118:119], 2, s[12:13]
	v_ashrrev_i32_e32 v121, 31, v120
	v_ashrrev_i32_e32 v125, 31, v124
	v_ashrrev_i32_e32 v127, 31, v126
	v_lshl_add_u64 v[100:101], v[128:129], 2, s[12:13]
	v_lshl_add_u64 v[104:105], v[132:133], 2, s[12:13]
	global_load_dword v195, v[74:75], off
	global_load_dword v203, v[74:75], off offset:128
	global_load_dword v222, v[74:75], off offset:256
	v_lshl_add_u64 v[84:85], v[136:137], 2, s[12:13]
	v_lshl_add_u64 v[82:83], v[130:131], 2, s[12:13]
	v_lshl_add_u64 v[78:79], v[122:123], 2, s[12:13]
	v_lshl_add_u64 v[72:73], v[114:115], 2, s[12:13]
	v_lshl_add_u64 v[74:75], v[106:107], 2, s[12:13]
	v_lshl_add_u64 v[76:77], v[108:109], 2, s[12:13]
	v_lshl_add_u64 v[80:81], v[110:111], 2, s[12:13]
	global_load_dword v178, v[88:89], off
	global_load_dword v177, v[84:85], off
	global_load_dword v176, v[82:83], off
	global_load_dword v175, v[78:79], off
	global_load_dword v174, v[72:73], off
	global_load_dword v173, v[74:75], off
	global_load_dword v172, v[76:77], off
	global_load_dword v171, v[80:81], off
	v_lshl_add_u64 v[90:91], v[116:117], 2, s[12:13]
	global_load_dword v170, v[86:87], off
	global_load_dword v168, v[90:91], off
	v_lshl_add_u64 v[94:95], v[120:121], 2, s[12:13]
	v_lshl_add_u64 v[96:97], v[124:125], 2, s[12:13]
	v_lshl_add_u64 v[98:99], v[126:127], 2, s[12:13]
	global_load_dword v169, v[92:93], off
	global_load_dword v167, v[94:95], off
	global_load_dword v166, v[96:97], off
	global_load_dword v165, v[98:99], off
	global_load_dword v103, v[100:101], off
	global_load_dword v197, v[104:105], off
	v_lshl_add_u64 v[106:107], v[106:107], 1, s[8:9]
	global_load_dword v198, v[104:105], off offset:128
	global_load_dword v205, v[84:85], off offset:128
	global_load_dword v206, v[78:79], off offset:128
	global_load_dword v207, v[72:73], off offset:128
	global_load_dword v208, v[74:75], off offset:128
	global_load_dword v209, v[80:81], off offset:128
	global_load_dword v210, v[76:77], off offset:128
	global_load_dword v211, v[86:87], off offset:128
	global_load_dword v212, v[82:83], off offset:128
	global_load_dword v213, v[90:91], off offset:128
	global_load_dword v214, v[92:93], off offset:128
	global_load_dword v215, v[94:95], off offset:128
	global_load_dword v216, v[96:97], off offset:128
	global_load_dword v217, v[98:99], off offset:128
	global_load_dword v218, v[100:101], off offset:128
	global_load_dword v219, v[88:89], off offset:128
	global_load_dword v220, v[88:89], off offset:256
	global_load_dword v224, v[90:91], off offset:256
	global_load_dword v225, v[92:93], off offset:256
	global_load_dword v226, v[94:95], off offset:256
	global_load_dword v227, v[104:105], off offset:256
	global_load_dword v229, v[84:85], off offset:256
	global_load_dword v230, v[86:87], off offset:256
	global_load_dword v231, v[82:83], off offset:256
	global_load_dword v232, v[78:79], off offset:256
	global_load_dword v233, v[72:73], off offset:256
	global_load_dword v234, v[74:75], off offset:256
	global_load_dword v235, v[80:81], off offset:256
	global_load_dword v236, v[76:77], off offset:256
	global_load_dword v237, v[96:97], off offset:256
	global_load_dword v238, v[98:99], off offset:256
	global_load_dword v239, v[100:101], off offset:256
	s_waitcnt vmcnt(0)
	v_add_f32_e32 v196, 1.0, v196
	v_mul_f32_e32 v195, v195, v196
	v_fmac_f32_e32 v178, v49, v194
	v_fmac_f32_e32 v177, v50, v194
	v_fmac_f32_e32 v176, v51, v194
	v_fmac_f32_e32 v175, v52, v194
	v_fmac_f32_e32 v174, v53, v194
	v_fmac_f32_e32 v173, v54, v194
	v_fmac_f32_e32 v172, v55, v194
	v_fmac_f32_e32 v171, v56, v194
	v_fmac_f32_e32 v170, v57, v194
	v_fmac_f32_e32 v168, v58, v194
	v_fmac_f32_e32 v169, v59, v194
	v_fmac_f32_e32 v167, v60, v194
	v_fmac_f32_e32 v166, v61, v194
	v_fmac_f32_e32 v165, v62, v194
	v_fmac_f32_e32 v103, v63, v194
	v_fmac_f32_e32 v197, v48, v194
	v_mul_f32_e32 v48, v195, v197
	v_cvt_pk_bf16_f32 v58, v48, s0
	v_or_b32_e32 v48, 32, v102
	v_ashrrev_i32_e32 v49, 31, v48
	v_lshlrev_b64 v[52:53], 2, v[48:49]
	global_store_dword v[88:89], v178, off sc1
	global_store_dword v[84:85], v177, off sc1
	global_store_dword v[82:83], v176, off sc1
	global_store_dword v[78:79], v175, off sc1
	global_store_dword v[72:73], v174, off sc1
	global_store_dword v[74:75], v173, off sc1
	global_store_dword v[76:77], v172, off sc1
	global_store_dword v[80:81], v171, off sc1
	global_store_dword v[86:87], v170, off sc1
	global_store_dword v[90:91], v168, off sc1
	global_store_dword v[92:93], v169, off sc1
	global_store_dword v[94:95], v167, off sc1
	global_store_dword v[96:97], v166, off sc1
	global_store_dword v[98:99], v165, off sc1
	global_store_dword v[100:101], v103, off sc1
	global_store_dword v[104:105], v197, off sc1
	v_lshl_add_u64 v[50:51], v[132:133], 1, s[8:9]
	v_lshl_add_u64 v[56:57], s[64:65], 0, v[52:53]
	v_mov_b32_e32 v196, v198
	v_lshl_add_u64 v[54:55], s[60:61], 0, v[52:53]
	v_mov_b32_e32 v132, v202
	v_mov_b32_e32 v133, v203
	v_mul_f32_e32 v49, v195, v178
	global_store_short v[50:51], v58, off sc1
	v_lshl_add_u64 v[50:51], s[62:63], 0, v[52:53]
	v_mov_b32_e32 v194, v204
	v_cvt_pk_bf16_f32 v49, v49, s0
	v_lshl_add_u64 v[50:51], v[134:135], 1, s[8:9]
	global_store_short v[50:51], v49, off sc1
	v_mul_f32_e32 v49, v195, v177
	v_cvt_pk_bf16_f32 v49, v49, s0
	v_lshl_add_u64 v[50:51], v[136:137], 1, s[8:9]
	global_store_short v[50:51], v49, off sc1
	v_mul_f32_e32 v49, v195, v176
	v_cvt_pk_bf16_f32 v49, v49, s0
	v_lshl_add_u64 v[50:51], v[130:131], 1, s[8:9]
	global_store_short v[50:51], v49, off sc1
	v_mul_f32_e32 v49, v195, v175
	v_cvt_pk_bf16_f32 v49, v49, s0
	v_lshl_add_u64 v[50:51], v[122:123], 1, s[8:9]
	global_store_short v[50:51], v49, off sc1
	v_mul_f32_e32 v49, v195, v174
	v_cvt_pk_bf16_f32 v49, v49, s0
	v_lshl_add_u64 v[50:51], v[114:115], 1, s[8:9]
	global_store_short v[50:51], v49, off sc1
	v_mul_f32_e32 v49, v195, v173
	v_mov_b32_e32 v62, v205
	v_mov_b32_e32 v60, v206
	v_mov_b32_e32 v59, v207
	v_mov_b32_e32 v58, v208
	v_mov_b32_e32 v56, v209
	v_mov_b32_e32 v57, v210
	v_mov_b32_e32 v55, v211
	v_mov_b32_e32 v61, v212
	v_mov_b32_e32 v54, v213
	v_mov_b32_e32 v53, v214
	v_mov_b32_e32 v52, v215
	v_mov_b32_e32 v51, v216
	v_mov_b32_e32 v50, v217
	v_cvt_pk_bf16_f32 v63, v49, s0
	v_mov_b32_e32 v49, v218
	v_fmac_f32_e32 v196, v32, v194
	global_store_short v[106:107], v63, off sc1
	v_mov_b32_e32 v63, v219
	v_mul_f32_e32 v106, v195, v172
	v_cvt_pk_bf16_f32 v114, v106, s0
	v_lshl_add_u64 v[106:107], v[108:109], 1, s[8:9]
	global_store_short v[106:107], v114, off sc1
	v_mul_f32_e32 v106, v195, v171
	v_cvt_pk_bf16_f32 v108, v106, s0
	v_lshl_add_u64 v[106:107], v[110:111], 1, s[8:9]
	global_store_short v[106:107], v108, off sc1
	v_mul_f32_e32 v106, v195, v170
	v_cvt_pk_bf16_f32 v108, v106, s0
	v_lshl_add_u64 v[106:107], v[112:113], 1, s[8:9]
	global_store_short v[106:107], v108, off sc1
	v_mul_f32_e32 v106, v195, v168
	v_cvt_pk_bf16_f32 v108, v106, s0
	v_lshl_add_u64 v[106:107], v[116:117], 1, s[8:9]
	global_store_short v[106:107], v108, off sc1
	v_mul_f32_e32 v106, v195, v169
	v_cvt_pk_bf16_f32 v108, v106, s0
	v_lshl_add_u64 v[106:107], v[118:119], 1, s[8:9]
	global_store_short v[106:107], v108, off sc1
	v_mul_f32_e32 v106, v195, v167
	v_cvt_pk_bf16_f32 v108, v106, s0
	v_lshl_add_u64 v[106:107], v[120:121], 1, s[8:9]
	global_store_short v[106:107], v108, off sc1
	v_mul_f32_e32 v106, v195, v166
	v_cvt_pk_bf16_f32 v108, v106, s0
	v_lshl_add_u64 v[106:107], v[124:125], 1, s[8:9]
	global_store_short v[106:107], v108, off sc1
	v_mul_f32_e32 v106, v195, v165
	v_cvt_pk_bf16_f32 v108, v106, s0
	v_lshl_add_u64 v[106:107], v[126:127], 1, s[8:9]
	global_store_short v[106:107], v108, off sc1
	v_mul_f32_e32 v106, v195, v103
	v_cvt_pk_bf16_f32 v108, v106, s0
	v_lshl_add_u64 v[106:107], v[128:129], 1, s[8:9]
	global_store_short v[106:107], v108, off sc1
	v_add_f32_e32 v106, 1.0, v132
	v_mul_f32_e32 v110, v133, v106
	v_add_u32_e32 v106, v188, v48
	v_fmac_f32_e32 v62, v34, v194
	v_fmac_f32_e32 v61, v35, v194
	v_fmac_f32_e32 v60, v36, v194
	v_fmac_f32_e32 v59, v37, v194
	v_fmac_f32_e32 v58, v38, v194
	v_fmac_f32_e32 v57, v39, v194
	v_fmac_f32_e32 v56, v40, v194
	v_fmac_f32_e32 v55, v41, v194
	v_fmac_f32_e32 v54, v42, v194
	v_fmac_f32_e32 v53, v43, v194
	v_fmac_f32_e32 v52, v44, v194
	v_fmac_f32_e32 v51, v45, v194
	v_fmac_f32_e32 v50, v46, v194
	v_fmac_f32_e32 v49, v47, v194
	v_ashrrev_i32_e32 v107, 31, v106
	global_store_dword v[104:105], v196, off offset:128 sc1
	v_mul_f32_e32 v32, v110, v196
	global_store_dword v[84:85], v62, off offset:128 sc1
	global_store_dword v[82:83], v61, off offset:128 sc1
	global_store_dword v[78:79], v60, off offset:128 sc1
	global_store_dword v[72:73], v59, off offset:128 sc1
	global_store_dword v[74:75], v58, off offset:128 sc1
	global_store_dword v[76:77], v57, off offset:128 sc1
	global_store_dword v[80:81], v56, off offset:128 sc1
	global_store_dword v[86:87], v55, off offset:128 sc1
	global_store_dword v[90:91], v54, off offset:128 sc1
	global_store_dword v[92:93], v53, off offset:128 sc1
	global_store_dword v[94:95], v52, off offset:128 sc1
	global_store_dword v[96:97], v51, off offset:128 sc1
	global_store_dword v[98:99], v50, off offset:128 sc1
	global_store_dword v[100:101], v49, off offset:128 sc1
	v_cvt_pk_bf16_f32 v32, v32, s0
	v_lshl_add_u64 v[106:107], v[106:107], 1, s[8:9]
	v_add_u32_e32 v108, v186, v48
	v_mov_b32_e32 v45, v220
	v_ashrrev_i32_e32 v109, 31, v108
	global_store_short v[106:107], v32, off sc1
	v_mul_f32_e32 v113, v110, v56
	v_cvt_pk_bf16_f32 v113, v113, s0
	v_mul_f32_e32 v106, v196, v196
	v_fmac_f32_e32 v63, v33, v194
	v_mul_f32_e32 v32, v110, v63
	v_cvt_pk_bf16_f32 v34, v32, s0
	v_lshl_add_u64 v[32:33], v[108:109], 1, s[8:9]
	global_store_short v[32:33], v34, off sc1
	v_add_u32_e32 v32, v184, v48
	v_ashrrev_i32_e32 v33, 31, v32
	v_mul_f32_e32 v34, v110, v62
	v_cvt_pk_bf16_f32 v34, v34, s0
	v_lshl_add_u64 v[32:33], v[32:33], 1, s[8:9]
	global_store_short v[32:33], v34, off sc1
	v_add_u32_e32 v32, v183, v48
	v_ashrrev_i32_e32 v33, 31, v32
	v_mul_f32_e32 v34, v110, v61
	v_cvt_pk_bf16_f32 v34, v34, s0
	v_lshl_add_u64 v[32:33], v[32:33], 1, s[8:9]
	global_store_short v[32:33], v34, off sc1
	v_add_u32_e32 v32, v181, v48
	v_ashrrev_i32_e32 v33, 31, v32
	v_mul_f32_e32 v34, v110, v60
	v_cvt_pk_bf16_f32 v34, v34, s0
	v_lshl_add_u64 v[32:33], v[32:33], 1, s[8:9]
	global_store_short v[32:33], v34, off sc1
	v_add_u32_e32 v32, v179, v48
	v_ashrrev_i32_e32 v33, 31, v32
	v_mul_f32_e32 v34, v110, v59
	v_cvt_pk_bf16_f32 v42, v34, s0
	v_lshl_add_u64 v[34:35], v[32:33], 1, s[8:9]
	v_or_b32_e32 v32, 64, v102
	v_ashrrev_i32_e32 v33, 31, v32
	v_lshlrev_b64 v[36:37], 2, v[32:33]
	global_store_dword v[88:89], v63, off offset:128 sc1
	v_lshl_add_u64 v[40:41], s[64:65], 0, v[36:37]
	v_lshl_add_u64 v[38:39], s[60:61], 0, v[36:37]
	v_mov_b32_e32 v107, v221
	v_mov_b32_e32 v111, v222
	v_mul_f32_e32 v33, v110, v58
	global_store_short v[34:35], v42, off sc1
	v_lshl_add_u64 v[34:35], s[62:63], 0, v[36:37]
	v_mov_b32_e32 v112, v223
	v_add_u32_e32 v34, v71, v48
	v_ashrrev_i32_e32 v35, 31, v34
	v_cvt_pk_bf16_f32 v33, v33, s0
	v_lshl_add_u64 v[34:35], v[34:35], 1, s[8:9]
	global_store_short v[34:35], v33, off sc1
	v_add_u32_e32 v34, v180, v48
	v_ashrrev_i32_e32 v35, 31, v34
	v_mul_f32_e32 v33, v110, v57
	v_cvt_pk_bf16_f32 v33, v33, s0
	v_lshl_add_u64 v[34:35], v[34:35], 1, s[8:9]
	v_mov_b32_e32 v38, v224
	v_mov_b32_e32 v37, v225
	v_mov_b32_e32 v36, v226
	v_mov_b32_e32 v114, v227
	v_mov_b32_e32 v47, v229
	v_mov_b32_e32 v39, v230
	v_mov_b32_e32 v46, v231
	v_mov_b32_e32 v44, v232
	v_mov_b32_e32 v43, v233
	v_mov_b32_e32 v42, v234
	v_mov_b32_e32 v40, v235
	v_mov_b32_e32 v41, v236
	v_add_u32_e32 v108, v182, v48
	global_store_short v[34:35], v33, off sc1
	v_mov_b32_e32 v35, v237
	v_ashrrev_i32_e32 v109, 31, v108
	v_mov_b32_e32 v34, v238
	v_mov_b32_e32 v33, v239
	v_lshl_add_u64 v[108:109], v[108:109], 1, s[8:9]
	global_store_short v[108:109], v113, off sc1
	v_add_u32_e32 v108, v185, v48
	v_ashrrev_i32_e32 v109, 31, v108
	v_mul_f32_e32 v113, v110, v55
	v_cvt_pk_bf16_f32 v113, v113, s0
	v_lshl_add_u64 v[108:109], v[108:109], 1, s[8:9]
	global_store_short v[108:109], v113, off sc1
	v_add_u32_e32 v108, v187, v48
	v_ashrrev_i32_e32 v109, 31, v108
	v_mul_f32_e32 v113, v110, v54
	v_cvt_pk_bf16_f32 v113, v113, s0
	v_lshl_add_u64 v[108:109], v[108:109], 1, s[8:9]
	global_store_short v[108:109], v113, off sc1
	v_add_u32_e32 v108, v189, v48
	v_ashrrev_i32_e32 v109, 31, v108
	v_mul_f32_e32 v113, v110, v53
	v_cvt_pk_bf16_f32 v113, v113, s0
	v_lshl_add_u64 v[108:109], v[108:109], 1, s[8:9]
	global_store_short v[108:109], v113, off sc1
	v_add_u32_e32 v108, v190, v48
	v_ashrrev_i32_e32 v109, 31, v108
	v_mul_f32_e32 v113, v110, v52
	v_cvt_pk_bf16_f32 v113, v113, s0
	v_lshl_add_u64 v[108:109], v[108:109], 1, s[8:9]
	global_store_short v[108:109], v113, off sc1
	v_add_u32_e32 v108, v191, v48
	v_ashrrev_i32_e32 v109, 31, v108
	v_mul_f32_e32 v113, v110, v51
	v_cvt_pk_bf16_f32 v113, v113, s0
	v_lshl_add_u64 v[108:109], v[108:109], 1, s[8:9]
	global_store_short v[108:109], v113, off sc1
	v_add_u32_e32 v108, v192, v48
	v_ashrrev_i32_e32 v109, 31, v108
	v_mul_f32_e32 v113, v110, v50
	v_cvt_pk_bf16_f32 v113, v113, s0
	v_lshl_add_u64 v[108:109], v[108:109], 1, s[8:9]
	global_store_short v[108:109], v113, off sc1
	v_add_u32_e32 v108, v193, v48
	v_ashrrev_i32_e32 v109, 31, v108
	v_mul_f32_e32 v48, v110, v49
	v_cvt_pk_bf16_f32 v48, v48, s0
	v_lshl_add_u64 v[108:109], v[108:109], 1, s[8:9]
	global_store_short v[108:109], v48, off sc1
	v_add_u32_e32 v108, v188, v32
	v_ashrrev_i32_e32 v109, 31, v108
	v_add_f32_e32 v48, 1.0, v107
	v_mul_f32_e32 v48, v111, v48
	v_fmac_f32_e32 v106, v197, v197
	v_fmac_f32_e32 v45, v17, v112
	global_store_dword v[88:89], v45, off offset:256 sc1
	v_fmac_f32_e32 v38, v26, v112
	v_fmac_f32_e32 v37, v27, v112
	v_fmac_f32_e32 v36, v28, v112
	v_fmac_f32_e32 v114, v16, v112
	v_mul_f32_e32 v16, v48, v114
	v_fmac_f32_e32 v47, v18, v112
	v_cvt_pk_bf16_f32 v18, v16, s0
	v_lshl_add_u64 v[16:17], v[108:109], 1, s[8:9]
	global_store_short v[16:17], v18, off sc1
	v_add_u32_e32 v16, v186, v32
	v_ashrrev_i32_e32 v17, 31, v16
	v_mul_f32_e32 v18, v48, v45
	v_cvt_pk_bf16_f32 v18, v18, s0
	v_lshl_add_u64 v[16:17], v[16:17], 1, s[8:9]
	global_store_short v[16:17], v18, off sc1
	v_add_u32_e32 v16, v184, v32
	v_ashrrev_i32_e32 v17, 31, v16
	v_mul_f32_e32 v18, v48, v47
	v_cvt_pk_bf16_f32 v18, v18, s0
	v_lshl_add_u64 v[16:17], v[16:17], 1, s[8:9]
	v_fmac_f32_e32 v46, v19, v112
	global_store_short v[16:17], v18, off sc1
	v_add_u32_e32 v16, v183, v32
	v_ashrrev_i32_e32 v17, 31, v16
	v_mul_f32_e32 v18, v48, v46
	v_fmac_f32_e32 v44, v20, v112
	v_cvt_pk_bf16_f32 v18, v18, s0
	v_lshl_add_u64 v[16:17], v[16:17], 1, s[8:9]
	global_store_short v[16:17], v18, off sc1
	v_mul_f32_e32 v16, v48, v44
	v_cvt_pk_bf16_f32 v26, v16, s0
	v_or_b32_e32 v16, 0x60, v102
	v_add_u32_e32 v18, v181, v32
	v_ashrrev_i32_e32 v17, 31, v16
	v_fmac_f32_e32 v43, v21, v112
	v_fmac_f32_e32 v42, v22, v112
	v_fmac_f32_e32 v41, v23, v112
	v_fmac_f32_e32 v40, v24, v112
	v_fmac_f32_e32 v39, v25, v112
	v_fmac_f32_e32 v35, v29, v112
	v_fmac_f32_e32 v34, v30, v112
	v_fmac_f32_e32 v33, v31, v112
	v_ashrrev_i32_e32 v19, 31, v18
	v_lshlrev_b64 v[20:21], 2, v[16:17]
	global_store_dword v[84:85], v47, off offset:256 sc1
	global_store_dword v[82:83], v46, off offset:256 sc1
	global_store_dword v[78:79], v44, off offset:256 sc1
	global_store_dword v[72:73], v43, off offset:256 sc1
	global_store_dword v[74:75], v42, off offset:256 sc1
	global_store_dword v[76:77], v41, off offset:256 sc1
	global_store_dword v[80:81], v40, off offset:256 sc1
	global_store_dword v[86:87], v39, off offset:256 sc1
	global_store_dword v[90:91], v38, off offset:256 sc1
	global_store_dword v[92:93], v37, off offset:256 sc1
	global_store_dword v[94:95], v36, off offset:256 sc1
	global_store_dword v[96:97], v35, off offset:256 sc1
	global_store_dword v[98:99], v34, off offset:256 sc1
	global_store_dword v[100:101], v33, off offset:256 sc1
	global_store_dword v[104:105], v114, off offset:256 sc1
	v_lshl_add_u64 v[24:25], s[64:65], 0, v[20:21]
	v_lshl_add_u64 v[18:19], v[18:19], 1, s[8:9]
	global_load_dword v29, v[104:105], off offset:384
	v_lshl_add_u64 v[22:23], s[60:61], 0, v[20:21]
	global_load_dword v17, v[24:25], off
	global_load_dword v30, v[22:23], off
	global_load_dword v28, v[88:89], off offset:384
	global_load_dword v27, v[84:85], off offset:384
	v_fmac_f32_e32 v106, v114, v114
	global_store_short v[18:19], v26, off sc1
	v_lshl_add_u64 v[18:19], s[62:63], 0, v[20:21]
	global_load_dword v102, v[18:19], off
	v_add_u32_e32 v18, v179, v32
	v_ashrrev_i32_e32 v19, 31, v18
	v_mul_f32_e32 v20, v48, v43
	v_cvt_pk_bf16_f32 v20, v20, s0
	v_lshl_add_u64 v[18:19], v[18:19], 1, s[8:9]
	global_store_short v[18:19], v20, off sc1
	v_add_u32_e32 v18, v71, v32
	v_ashrrev_i32_e32 v19, 31, v18
	v_mul_f32_e32 v20, v48, v42
	v_cvt_pk_bf16_f32 v20, v20, s0
	v_lshl_add_u64 v[18:19], v[18:19], 1, s[8:9]
	global_store_short v[18:19], v20, off sc1
	v_add_u32_e32 v18, v180, v32
	v_ashrrev_i32_e32 v19, 31, v18
	v_mul_f32_e32 v20, v48, v41
	v_cvt_pk_bf16_f32 v20, v20, s0
	v_lshl_add_u64 v[18:19], v[18:19], 1, s[8:9]
	global_store_short v[18:19], v20, off sc1
	v_add_u32_e32 v18, v182, v32
	v_ashrrev_i32_e32 v19, 31, v18
	v_mul_f32_e32 v20, v48, v40
	v_cvt_pk_bf16_f32 v20, v20, s0
	v_lshl_add_u64 v[18:19], v[18:19], 1, s[8:9]
	global_store_short v[18:19], v20, off sc1
	v_add_u32_e32 v18, v185, v32
	v_ashrrev_i32_e32 v19, 31, v18
	v_mul_f32_e32 v20, v48, v39
	v_cvt_pk_bf16_f32 v20, v20, s0
	v_lshl_add_u64 v[18:19], v[18:19], 1, s[8:9]
	global_store_short v[18:19], v20, off sc1
	v_add_u32_e32 v18, v187, v32
	v_ashrrev_i32_e32 v19, 31, v18
	v_mul_f32_e32 v20, v48, v38
	v_cvt_pk_bf16_f32 v20, v20, s0
	v_lshl_add_u64 v[18:19], v[18:19], 1, s[8:9]
	global_store_short v[18:19], v20, off sc1
	v_add_u32_e32 v18, v189, v32
	v_ashrrev_i32_e32 v19, 31, v18
	v_mul_f32_e32 v20, v48, v37
	v_cvt_pk_bf16_f32 v20, v20, s0
	v_lshl_add_u64 v[18:19], v[18:19], 1, s[8:9]
	global_store_short v[18:19], v20, off sc1
	v_add_u32_e32 v18, v190, v32
	v_ashrrev_i32_e32 v19, 31, v18
	v_mul_f32_e32 v20, v48, v36
	v_cvt_pk_bf16_f32 v20, v20, s0
	v_lshl_add_u64 v[18:19], v[18:19], 1, s[8:9]
	global_store_short v[18:19], v20, off sc1
	v_add_u32_e32 v18, v191, v32
	v_ashrrev_i32_e32 v19, 31, v18
	v_mul_f32_e32 v20, v48, v35
	v_cvt_pk_bf16_f32 v20, v20, s0
	v_lshl_add_u64 v[18:19], v[18:19], 1, s[8:9]
	global_store_short v[18:19], v20, off sc1
	v_add_u32_e32 v18, v192, v32
	v_ashrrev_i32_e32 v19, 31, v18
	v_mul_f32_e32 v20, v48, v34
	v_cvt_pk_bf16_f32 v20, v20, s0
	v_lshl_add_u64 v[18:19], v[18:19], 1, s[8:9]
	global_store_short v[18:19], v20, off sc1
	v_add_u32_e32 v18, v193, v32
	v_ashrrev_i32_e32 v19, 31, v18
	v_mul_f32_e32 v20, v48, v33
	v_cvt_pk_bf16_f32 v20, v20, s0
	v_lshl_add_u64 v[18:19], v[18:19], 1, s[8:9]
	global_store_short v[18:19], v20, off sc1
	global_load_dword v20, v[86:87], off offset:384
	v_add_u32_e32 v18, v188, v16
	global_load_dword v26, v[82:83], off offset:384
	global_load_dword v25, v[78:79], off offset:384
	global_load_dword v24, v[72:73], off offset:384
	global_load_dword v23, v[74:75], off offset:384
	global_load_dword v21, v[80:81], off offset:384
	global_load_dword v22, v[76:77], off offset:384
	s_waitcnt vmcnt(23)
	v_add_f32_e32 v17, 1.0, v17
	s_waitcnt vmcnt(22)
	v_mul_f32_e32 v32, v30, v17
	v_ashrrev_i32_e32 v19, 31, v18
	v_lshl_add_u64 v[18:19], v[18:19], 1, s[8:9]
	v_add_u32_e32 v30, v186, v16
	s_waitcnt vmcnt(18)
	v_fmac_f32_e32 v29, v0, v102
	v_mul_f32_e32 v0, v32, v29
	v_cvt_pk_bf16_f32 v0, v0, s0
	global_store_short v[18:19], v0, off sc1
	global_load_dword v19, v[90:91], off offset:384
	v_ashrrev_i32_e32 v31, 31, v30
	global_load_dword v18, v[92:93], off offset:384
	v_fmac_f32_e32 v28, v1, v102
	v_mul_f32_e32 v0, v32, v28
	v_cvt_pk_bf16_f32 v17, v0, s0
	v_lshl_add_u64 v[0:1], v[30:31], 1, s[8:9]
	global_store_short v[0:1], v17, off sc1
	v_add_u32_e32 v0, v184, v16
	v_fmac_f32_e32 v27, v2, v102
	global_load_dword v17, v[94:95], off offset:384
	v_ashrrev_i32_e32 v1, 31, v0
	v_mul_f32_e32 v2, v32, v27
	v_cvt_pk_bf16_f32 v2, v2, s0
	v_lshl_add_u64 v[0:1], v[0:1], 1, s[8:9]
	global_store_short v[0:1], v2, off sc1
	v_add_u32_e32 v0, v183, v16
	global_load_dword v2, v[96:97], off offset:384
	v_ashrrev_i32_e32 v1, 31, v0
	v_lshl_add_u64 v[0:1], v[0:1], 1, s[8:9]
	v_add_u32_e32 v30, v181, v16
	v_ashrrev_i32_e32 v31, 31, v30
	v_lshl_add_u64 v[30:31], v[30:31], 1, s[8:9]
	v_fmac_f32_e32 v106, v29, v29
	global_store_dword v[104:105], v29, off offset:384 sc1
	global_store_dword v[88:89], v28, off offset:384 sc1
	global_store_dword v[84:85], v27, off offset:384 sc1
	s_waitcnt vmcnt(16)
	v_fmac_f32_e32 v20, v9, v102
	global_store_dword v[86:87], v20, off offset:384 sc1
	s_waitcnt vmcnt(16)
	v_fmac_f32_e32 v26, v3, v102
	v_mul_f32_e32 v3, v32, v26
	v_cvt_pk_bf16_f32 v3, v3, s0
	global_store_short v[0:1], v3, off sc1
	global_load_dword v1, v[98:99], off offset:384
	s_waitcnt vmcnt(17)
	v_fmac_f32_e32 v25, v4, v102
	v_mul_f32_e32 v0, v32, v25
	v_cvt_pk_bf16_f32 v0, v0, s0
	global_store_short v[30:31], v0, off sc1
	global_load_dword v0, v[100:101], off offset:384
	v_add_u32_e32 v30, v179, v16
	s_waitcnt vmcnt(18)
	v_fmac_f32_e32 v24, v5, v102
	v_ashrrev_i32_e32 v31, 31, v30
	v_mul_f32_e32 v3, v32, v24
	v_cvt_pk_bf16_f32 v3, v3, s0
	v_lshl_add_u64 v[4:5], v[30:31], 1, s[8:9]
	global_store_short v[4:5], v3, off sc1
	v_add_u32_e32 v4, v71, v16
	s_waitcnt vmcnt(18)
	v_fmac_f32_e32 v23, v6, v102
	v_ashrrev_i32_e32 v5, 31, v4
	v_mul_f32_e32 v3, v32, v23
	v_cvt_pk_bf16_f32 v3, v3, s0
	v_lshl_add_u64 v[4:5], v[4:5], 1, s[8:9]
	global_store_short v[4:5], v3, off sc1
	v_add_u32_e32 v4, v180, v16
	s_waitcnt vmcnt(17)
	v_fmac_f32_e32 v22, v7, v102
	v_ashrrev_i32_e32 v5, 31, v4
	v_mul_f32_e32 v3, v32, v22
	v_cvt_pk_bf16_f32 v3, v3, s0
	v_lshl_add_u64 v[4:5], v[4:5], 1, s[8:9]
	global_store_short v[4:5], v3, off sc1
	v_add_u32_e32 v4, v182, v16
	v_fmac_f32_e32 v21, v8, v102
	v_ashrrev_i32_e32 v5, 31, v4
	v_mul_f32_e32 v3, v32, v21
	v_cvt_pk_bf16_f32 v3, v3, s0
	v_lshl_add_u64 v[4:5], v[4:5], 1, s[8:9]
	global_store_short v[4:5], v3, off sc1
	v_add_u32_e32 v4, v185, v16
	v_ashrrev_i32_e32 v5, 31, v4
	v_mul_f32_e32 v3, v32, v20
	v_cvt_pk_bf16_f32 v3, v3, s0
	v_lshl_add_u64 v[4:5], v[4:5], 1, s[8:9]
	global_store_short v[4:5], v3, off sc1
	v_add_u32_e32 v4, v187, v16
	s_waitcnt vmcnt(18)
	v_fmac_f32_e32 v19, v10, v102
	v_ashrrev_i32_e32 v5, 31, v4
	v_mul_f32_e32 v3, v32, v19
	v_cvt_pk_bf16_f32 v3, v3, s0
	v_lshl_add_u64 v[4:5], v[4:5], 1, s[8:9]
	global_store_short v[4:5], v3, off sc1
	v_add_u32_e32 v4, v189, v16
	s_waitcnt vmcnt(18)
	v_fmac_f32_e32 v18, v11, v102
	v_ashrrev_i32_e32 v5, 31, v4
	v_mul_f32_e32 v3, v32, v18
	v_cvt_pk_bf16_f32 v3, v3, s0
	v_lshl_add_u64 v[4:5], v[4:5], 1, s[8:9]
	global_store_short v[4:5], v3, off sc1
	v_add_u32_e32 v4, v190, v16
	s_waitcnt vmcnt(17)
	v_fmac_f32_e32 v17, v12, v102
	v_ashrrev_i32_e32 v5, 31, v4
	v_mul_f32_e32 v3, v32, v17
	v_cvt_pk_bf16_f32 v3, v3, s0
	v_lshl_add_u64 v[4:5], v[4:5], 1, s[8:9]
	global_store_short v[4:5], v3, off sc1
	v_add_u32_e32 v4, v191, v16
	s_waitcnt vmcnt(16)
	v_fmac_f32_e32 v2, v13, v102
	v_ashrrev_i32_e32 v5, 31, v4
	v_mul_f32_e32 v3, v32, v2
	v_cvt_pk_bf16_f32 v3, v3, s0
	v_lshl_add_u64 v[4:5], v[4:5], 1, s[8:9]
	global_store_short v[4:5], v3, off sc1
	v_add_u32_e32 v4, v192, v16
	v_ashrrev_i32_e32 v5, 31, v4
	v_lshl_add_u64 v[4:5], v[4:5], 1, s[8:9]
	v_xor_b32_e32 v13, 16, v164
	v_add_u32_e32 v10, v193, v16
	v_ashrrev_i32_e32 v11, 31, v10
	v_lshl_add_u64 v[10:11], v[10:11], 1, s[8:9]
	v_ashrrev_i32_e32 v71, 31, v70
	global_store_dword v[82:83], v26, off offset:384 sc1
	global_store_dword v[78:79], v25, off offset:384 sc1
	global_store_dword v[72:73], v24, off offset:384 sc1
	global_store_dword v[74:75], v23, off offset:384 sc1
	s_waitcnt vmcnt(15)
	v_fmac_f32_e32 v1, v14, v102
	v_mul_f32_e32 v3, v32, v1
	v_cvt_pk_bf16_f32 v3, v3, s0
	global_store_short v[4:5], v3, off sc1
	v_and_b32_e32 v4, 64, v164
	v_xor_b32_e32 v3, 1, v164
	v_add_u32_e32 v7, 64, v4
	v_cmp_lt_i32_e32 vcc, v3, v7
	v_xor_b32_e32 v4, 2, v164
	s_waitcnt vmcnt(14)
	v_fmac_f32_e32 v0, v15, v102
	v_cndmask_b32_e32 v3, v164, v3, vcc
	v_lshlrev_b32_e32 v3, 2, v3
	v_cmp_lt_i32_e32 vcc, v4, v7
	v_mul_f32_e32 v12, v32, v0
	v_cvt_pk_bf16_f32 v12, v12, s0
	v_cndmask_b32_e32 v4, v164, v4, vcc
	v_lshlrev_b32_e32 v4, 2, v4
	v_add_f32_dpp v6, v106, v106 quad_perm:[1,0,3,2] row_mask:0xf bank_mask:0xf
	v_xor_b32_e32 v5, 4, v164
	v_cmp_lt_i32_e32 vcc, v5, v7
	global_store_dword v[76:77], v22, off offset:384 sc1
	global_store_dword v[80:81], v21, off offset:384 sc1
	v_cndmask_b32_e32 v5, v164, v5, vcc
	v_lshlrev_b32_e32 v5, 2, v5
	v_add_f32_dpp v8, v6, v6 quad_perm:[2,3,0,1] row_mask:0xf bank_mask:0xf
	v_xor_b32_e32 v6, 8, v164
	v_cmp_lt_i32_e32 vcc, v6, v7
	global_store_dword v[90:91], v19, off offset:384 sc1
	global_store_dword v[92:93], v18, off offset:384 sc1
	v_cndmask_b32_e32 v6, v164, v6, vcc
	v_lshlrev_b32_e32 v6, 2, v6
	v_add_f32_dpp v8, v8, v8 row_half_mirror row_mask:0xf bank_mask:0xf
	v_cmp_lt_i32_e32 vcc, v13, v7
	global_store_dword v[94:95], v17, off offset:384 sc1
	global_store_dword v[96:97], v2, off offset:384 sc1
	v_cndmask_b32_e32 v7, v164, v13, vcc
	v_lshlrev_b32_e32 v7, 2, v7
	v_add_f32_dpp v8, v8, v8 row_mirror row_mask:0xf bank_mask:0xf
	ds_bpermute_b32 v9, v7, v8
	global_store_dword v[98:99], v1, off offset:384 sc1
	global_store_dword v[100:101], v0, off offset:384 sc1
	global_store_short v[10:11], v12, off sc1
	s_and_saveexec_b64 s[60:61], s[0:1]
	s_cbranch_execz .LBB0_1571
	s_waitcnt lgkmcnt(0)
	v_add_f32_e32 v10, v8, v9
	v_lshl_add_u64 v[8:9], v[70:71], 2, s[58:59]
	global_store_dword v[8:9], v10, off sc1
